# epilogue de-serialisation: the two wave halves are realigned at every unit boundary (leading half waits one barrier at K-loop exit, lagging half one barrier at epilogue end) so both halves run their e
# speedup vs baseline: 1.0053x; 1.0053x over previous
; __device__ __forceinline__ unsigned cvt_pk_bf16(float lo, float hi) { const f32x2 v = {lo, hi}; const bf16v2_ r = __builtin_convertvector(v, bf16v2_); return __builtin_bit_cast(unsigned, r); }
; template <class Epi, class Sched>
; __device__ __forceinline__ void gemm_phase(LAS unsigned char* lds, const Gemm g, const Sched& S, const Epi& E) {
;     ...
;         if (!has_next) break;
; #pragma unroll
;         for (int a = 0; a < 2; ++a)
; #pragma unroll
;             for (int b = 0; b < 2; ++b)
; #pragma unroll
;                 for (int m = 0; m < 4; ++m)
; #pragma unroll
;                     for (int n = 0; n < 2; ++n) acc[a][b][m][n] = (f32x4){0.f, 0.f, 0.f, 0.f};
;         cur = nxt; cA = nA; cB = nB; ++ui;
;     __device__ __forceinline__ void operator()(const f32x4 (&acc)[2][2][4][2], const Unit& u, int wr, int wc, int ui, int) const {
;     ...
;             for (int m = 0; m < 4; ++m) { const int row = row0 + ai * HALF + m * 16; const float r = r_[ai][m];
; #pragma unroll
;                 for (int bj = 0; bj < 2; ++bj) { const f32x4 v0 = acc[ai][bj][m][0] * r, v1 = acc[ai][bj][m][1] * r;
;                     u32x4 w; w.x = cvt_pk_bf16(v0[0], v0[1]); w.y = cvt_pk_bf16(v0[2], v0[3]); w.z = cvt_pk_bf16(v1[0], v1[1]); w.w = cvt_pk_bf16(v1[2], v1[3]);
;                     bf16_t* p = cmp ? cb + ((size_t)((row / T) * 2 + bj) * T + (row % T)) * 128 + wc * 32 + 8 * fq
;                                     : O + (size_t)row * ldc + col0 + bj * HALF;
;                     *(u32x4*)p = w; } }
.LBB0_346:
	v_mov_b32_e32 v145, v144
	v_mov_b32_e32 v14, v144
	v_mov_b32_e32 v15, v144
	v_pk_mul_f32 v[10:11], v[10:11], v[14:15]
	v_pk_mul_f32 v[8:9], v[8:9], v[144:145]
	v_pk_mul_f32 v[6:7], v[6:7], v[14:15]
	v_pk_mul_f32 v[4:5], v[4:5], v[144:145]
	v_cvt_pk_bf16_f32 v8, v8, v9
	v_cvt_pk_bf16_f32 v9, v10, v11
	v_cvt_pk_bf16_f32 v10, v4, v5
	v_cvt_pk_bf16_f32 v11, v6, v7
	s_and_b64 vcc, exec, s[42:43]
	s_mov_b32 s44, s0
	s_mov_b32 s50, s14
	s_mov_b64 s[20:21], s[4:5]
	s_mov_b64 s[6:7], s[18:19]
	s_mov_b32 s45, s49
	global_store_dwordx4 v[12:13], v[8:11], off
	s_cmpk_lt_u32 s2, 0x100
	s_cbranch_scc1 .Lalign_b_352
	s_barrier
.Lalign_b_352:
	s_cbranch_vccnz .LBB0_417

; #define PG8_STAGE(bufoff, gbase, voff) do { _Pragma("unroll") for (int _i = 0; _i < 2; ++_i) \
;         __builtin_amdgcn_global_load_lds((const unsigned*)((const char*)(gbase) + (voff)[_i]), (LAS unsigned*)(lds + (bufoff) + ldsw + _i * 8192), 16, 0, 0); } while (0)
; #define PG8_LDA(dst, b, h) do { _Pragma("unroll") for (int m = 0; m < 4; ++m) _Pragma("unroll") for (int k = 0; k < 2; ++k) dst[m][k] = *(const LAS bf16x8*)(lds + PG8_SA(b, h) + aoff + m * 2048 + k * 1024); } while (0)
; #define PG8_LDB(dst, b, h) do { _Pragma("unroll") for (int n = 0; n < 2; ++n) _Pragma("unroll") for (int k = 0; k < 2; ++k) dst[n][k] = *(const LAS bf16x8*)(lds + PG8_SB(b, h) + boff + n * 2048 + k * 1024); } while (0)
; #define PG8_MMA(ai, bj, At, Bt) do { __builtin_amdgcn_s_setprio(1); _Pragma("unroll") for (int m = 0; m < 4; ++m) _Pragma("unroll") for (int n = 0; n < 2; ++n) _Pragma("unroll") for (int k = 0; k < 2; ++k) \
;         acc[ai][bj][m][n] = __builtin_amdgcn_mfma_f32_16x16x32_bf16(Bt[n][k], At[m][k], acc[ai][bj][m][n], 0, 0, 0); __builtin_amdgcn_s_setprio(0); } while (0)
; #define PG8_WAIT_V(n) asm volatile("s_waitcnt vmcnt(" #n ")" ::: "memory")
; #define PG8_WAIT_L(n) asm volatile("s_waitcnt lgkmcnt(" #n ")" ::: "memory")
; #define PG8_BAR __builtin_amdgcn_s_barrier()
; #define PG8_SCHED __builtin_amdgcn_sched_barrier(0)
; template <class Epi, class Sched>
; __device__ __forceinline__ void gemm_phase(LAS unsigned char* lds, const Gemm g, const Sched& S, const Epi& E) {
;     ...
;             PG8_LDB(B0, 0, 0); PG8_SCHED; PG8_LDA(At, 0, 0); PG8_STAGE(PG8_SA(1, 1), a1 + hstepA, voffA);
;             PG8_WAIT_L(8); PG8_BAR; PG8_WAIT_L(0); PG8_MMA(0, 0, At, B0); PG8_BAR; PG8_SCHED;
;             PG8_LDB(B1, 0, 1); PG8_STAGE(PG8_SB(0, 0), b2, voffB);
;             PG8_BAR; PG8_WAIT_L(0); PG8_MMA(0, 1, At, B1); PG8_BAR;
;             PG8_LDA(At, 0, 1); PG8_STAGE(PG8_SA(0, 0), a2, voffA);
;             PG8_BAR; PG8_WAIT_L(0); PG8_MMA(1, 0, At, B0); PG8_BAR; PG8_SCHED;
;             PG8_STAGE(PG8_SB(0, 1), b2 + hstepB, voffB);
;             PG8_WAIT_V(6); PG8_BAR; PG8_MMA(1, 1, At, B1); PG8_BAR;
.LBB0_352:
	s_setprio 0
	s_add_u32 s20, s6, 0xfff80080
	s_addc_u32 s21, s7, -1
	s_add_i32 s56, 0, 0x10000
	v_add_u32_e32 v2, s56, v1
	ds_read_b128 v[144:147], v2
	ds_read_b128 v[150:153], v2 offset:1024
	ds_read_b128 v[154:157], v2 offset:2048
	ds_read_b128 v[158:161], v2 offset:3072
	s_cmp_eq_u32 s55, 28
	s_cselect_b32 s25, s15, s21
	s_cselect_b32 s24, s51, s20
	s_cselect_b32 s21, s1, s54
	s_cselect_b32 s20, s52, s53
	ds_read_b128 v[162:165], v149
	ds_read_b128 v[166:169], v149 offset:1024
	ds_read_b128 v[170:173], v149 offset:2048
	ds_read_b128 v[174:177], v149 offset:3072
	ds_read_b128 v[178:181], v149 offset:4096
	ds_read_b128 v[182:185], v149 offset:5120
	ds_read_b128 v[186:189], v149 offset:6144
	ds_read_b128 v[190:193], v149 offset:7168
	s_add_i32 s58, 0, 0x14000
	v_add_u32_e32 v2, s58, v1
	ds_read_b128 v[194:197], v2
	ds_read_b128 v[198:201], v2 offset:1024
	ds_read_b128 v[202:205], v2 offset:2048
	ds_read_b128 v[206:209], v2 offset:3072
	s_add_i32 m0, s31, 0xc000
	s_nop 0
	global_load_lds_dwordx4 v140, s[6:7]
	s_add_i32 m0, s31, 0xe000
	s_nop 0
	global_load_lds_dwordx4 v142, s[6:7]
	s_waitcnt lgkmcnt(0)
	s_setprio 1
	s_barrier
	v_mfma_f32_16x16x32_bf16 v[128:131], v[144:147], v[162:165], v[128:131]
	v_mfma_f32_16x16x32_bf16 v[124:127], v[154:157], v[162:165], v[124:127]
	v_mfma_f32_16x16x32_bf16 v[112:115], v[144:147], v[170:173], v[112:115]
	v_mfma_f32_16x16x32_bf16 v[108:111], v[154:157], v[170:173], v[108:111]
	v_mfma_f32_16x16x32_bf16 v[96:99], v[144:147], v[178:181], v[96:99]
	v_mfma_f32_16x16x32_bf16 v[92:95], v[154:157], v[178:181], v[92:95]
	v_mfma_f32_16x16x32_bf16 v[80:83], v[144:147], v[186:189], v[80:83]
	v_mfma_f32_16x16x32_bf16 v[76:79], v[154:157], v[186:189], v[76:79]
	v_mfma_f32_16x16x32_bf16 v[128:131], v[150:153], v[166:169], v[128:131]
	v_mfma_f32_16x16x32_bf16 v[124:127], v[158:161], v[166:169], v[124:127]
	v_mfma_f32_16x16x32_bf16 v[112:115], v[150:153], v[174:177], v[112:115]
	v_mfma_f32_16x16x32_bf16 v[108:111], v[158:161], v[174:177], v[108:111]
	v_mfma_f32_16x16x32_bf16 v[96:99], v[150:153], v[182:185], v[96:99]
	v_mfma_f32_16x16x32_bf16 v[92:95], v[158:161], v[182:185], v[92:95]
	v_mfma_f32_16x16x32_bf16 v[80:83], v[150:153], v[190:193], v[80:83]
	v_mfma_f32_16x16x32_bf16 v[76:79], v[158:161], v[190:193], v[76:79]
	v_mfma_f32_16x16x32_bf16 v[120:123], v[194:197], v[162:165], v[120:123]
	v_mfma_f32_16x16x32_bf16 v[116:119], v[202:205], v[162:165], v[116:119]
	v_mfma_f32_16x16x32_bf16 v[104:107], v[194:197], v[170:173], v[104:107]
	v_mfma_f32_16x16x32_bf16 v[100:103], v[202:205], v[170:173], v[100:103]
	v_mfma_f32_16x16x32_bf16 v[88:91], v[194:197], v[178:181], v[88:91]
	v_mfma_f32_16x16x32_bf16 v[84:87], v[202:205], v[178:181], v[84:87]
	v_mfma_f32_16x16x32_bf16 v[72:75], v[194:197], v[186:189], v[72:75]
	v_mfma_f32_16x16x32_bf16 v[68:71], v[202:205], v[186:189], v[68:71]
	v_mfma_f32_16x16x32_bf16 v[120:123], v[198:201], v[166:169], v[120:123]
	v_mfma_f32_16x16x32_bf16 v[116:119], v[206:209], v[166:169], v[116:119]
	v_mfma_f32_16x16x32_bf16 v[104:107], v[198:201], v[174:177], v[104:107]
	v_mfma_f32_16x16x32_bf16 v[100:103], v[206:209], v[174:177], v[100:103]
	v_mfma_f32_16x16x32_bf16 v[88:91], v[198:201], v[182:185], v[88:91]
	v_mfma_f32_16x16x32_bf16 v[84:87], v[206:209], v[182:185], v[84:87]
	v_mfma_f32_16x16x32_bf16 v[72:75], v[198:201], v[190:193], v[72:75]
	v_mfma_f32_16x16x32_bf16 v[68:71], v[206:209], v[190:193], v[68:71]
	s_barrier
	s_setprio 0
	ds_read_b128 v[162:165], v149 offset:16384
	ds_read_b128 v[166:169], v149 offset:17408
	ds_read_b128 v[170:173], v149 offset:18432
	ds_read_b128 v[174:177], v149 offset:19456
	ds_read_b128 v[178:181], v149 offset:20480
	ds_read_b128 v[182:185], v149 offset:21504
	ds_read_b128 v[186:189], v149 offset:22528
	ds_read_b128 v[190:193], v149 offset:23552
	s_add_i32 s56, s56, s30
	v_lshl_add_u64 v[210:211], s[20:21], 0, v[136:137]
	s_mov_b32 m0, s56
	s_nop 0
	global_load_lds_dwordx4 v[210:211], off
	v_lshl_add_u64 v[212:213], s[20:21], 0, v[132:133]
	s_add_i32 m0, s56, 0x2000
	s_nop 0
	global_load_lds_dwordx4 v[212:213], off
	s_mov_b32 m0, s31
	v_lshl_add_u64 v[216:217], s[24:25], 0, v[138:139]
	global_load_lds_dwordx4 v[216:217], off
	v_lshl_add_u64 v[218:219], s[24:25], 0, v[134:135]
	s_mov_b32 m0, s35
	s_nop 0
	global_load_lds_dwordx4 v[218:219], off
	s_add_u32 s56, s20, 0x80000
	s_addc_u32 s57, s21, 0
	s_add_i32 s58, s58, s30
	s_mov_b32 m0, s58
	s_nop 0
	global_load_lds_dwordx4 v136, s[56:57]
	s_add_i32 m0, s58, 0x2000
	s_nop 0
	global_load_lds_dwordx4 v132, s[56:57]
	s_waitcnt lgkmcnt(0)
	s_waitcnt vmcnt(6)
	s_setprio 1
	s_barrier
; #define PG8_STAGE(bufoff, gbase, voff) do { _Pragma("unroll") for (int _i = 0; _i < 2; ++_i) \
;         __builtin_amdgcn_global_load_lds((const unsigned*)((const char*)(gbase) + (voff)[_i]), (LAS unsigned*)(lds + (bufoff) + ldsw + _i * 8192), 16, 0, 0); } while (0)
; #define PG8_LDA(dst, b, h) do { _Pragma("unroll") for (int m = 0; m < 4; ++m) _Pragma("unroll") for (int k = 0; k < 2; ++k) dst[m][k] = *(const LAS bf16x8*)(lds + PG8_SA(b, h) + aoff + m * 2048 + k * 1024); } while (0)
; #define PG8_LDB(dst, b, h) do { _Pragma("unroll") for (int n = 0; n < 2; ++n) _Pragma("unroll") for (int k = 0; k < 2; ++k) dst[n][k] = *(const LAS bf16x8*)(lds + PG8_SB(b, h) + boff + n * 2048 + k * 1024); } while (0)
; #define PG8_MMA(ai, bj, At, Bt) do { __builtin_amdgcn_s_setprio(1); _Pragma("unroll") for (int m = 0; m < 4; ++m) _Pragma("unroll") for (int n = 0; n < 2; ++n) _Pragma("unroll") for (int k = 0; k < 2; ++k) \
;         acc[ai][bj][m][n] = __builtin_amdgcn_mfma_f32_16x16x32_bf16(Bt[n][k], At[m][k], acc[ai][bj][m][n], 0, 0, 0); __builtin_amdgcn_s_setprio(0); } while (0)
; #define PG8_WAIT_V(n) asm volatile("s_waitcnt vmcnt(" #n ")" ::: "memory")
; #define PG8_WAIT_L(n) asm volatile("s_waitcnt lgkmcnt(" #n ")" ::: "memory")
; #define PG8_BAR __builtin_amdgcn_s_barrier()
; #define PG8_SCHED __builtin_amdgcn_sched_barrier(0)
; template <class Epi, class Sched>
; __device__ __forceinline__ void gemm_phase(LAS unsigned char* lds, const Gemm g, const Sched& S, const Epi& E) {
;     ...
;             PG8_BAR; PG8_WAIT_L(0); PG8_MMA(1, 0, At, B0); PG8_BAR; PG8_SCHED;
;             PG8_STAGE(PG8_SB(0, 1), b2 + hstepB, voffB);
;             PG8_WAIT_V(6); PG8_BAR; PG8_MMA(1, 1, At, B1); PG8_BAR;
;             PG8_LDB(B0, 1, 0); PG8_SCHED; PG8_LDA(At, 1, 0); PG8_STAGE(PG8_SA(0, 1), a2 + hstepA, voffA);
;             PG8_WAIT_L(8); PG8_BAR; PG8_WAIT_L(0); PG8_MMA(0, 0, At, B0); PG8_BAR; PG8_SCHED;
;             PG8_LDB(B1, 1, 1); PG8_STAGE(PG8_SB(1, 0), b3, voffB);
;             PG8_BAR; PG8_WAIT_L(0); PG8_MMA(0, 1, At, B1); PG8_BAR;
;             PG8_LDA(At, 1, 1); PG8_STAGE(PG8_SA(1, 0), a3, voffA);
;             PG8_BAR; PG8_WAIT_L(0); PG8_MMA(1, 0, At, B0); PG8_BAR; PG8_SCHED;
	v_mfma_f32_16x16x32_bf16 v[64:67], v[144:147], v[162:165], v[64:67]
	v_mfma_f32_16x16x32_bf16 v[60:63], v[154:157], v[162:165], v[60:63]
	v_mfma_f32_16x16x32_bf16 v[48:51], v[144:147], v[170:173], v[48:51]
	v_mfma_f32_16x16x32_bf16 v[44:47], v[154:157], v[170:173], v[44:47]
	v_mfma_f32_16x16x32_bf16 v[32:35], v[144:147], v[178:181], v[32:35]
	v_mfma_f32_16x16x32_bf16 v[28:31], v[154:157], v[178:181], v[28:31]
	v_mfma_f32_16x16x32_bf16 v[16:19], v[144:147], v[186:189], v[16:19]
	v_mfma_f32_16x16x32_bf16 v[12:15], v[154:157], v[186:189], v[12:15]
	v_mfma_f32_16x16x32_bf16 v[64:67], v[150:153], v[166:169], v[64:67]
	v_mfma_f32_16x16x32_bf16 v[60:63], v[158:161], v[166:169], v[60:63]
	v_mfma_f32_16x16x32_bf16 v[48:51], v[150:153], v[174:177], v[48:51]
	v_mfma_f32_16x16x32_bf16 v[44:47], v[158:161], v[174:177], v[44:47]
	v_mfma_f32_16x16x32_bf16 v[32:35], v[150:153], v[182:185], v[32:35]
	v_mfma_f32_16x16x32_bf16 v[28:31], v[158:161], v[182:185], v[28:31]
	v_mfma_f32_16x16x32_bf16 v[16:19], v[150:153], v[190:193], v[16:19]
	v_mfma_f32_16x16x32_bf16 v[12:15], v[158:161], v[190:193], v[12:15]
	v_mfma_f32_16x16x32_bf16 v[56:59], v[194:197], v[162:165], v[56:59]
	v_mfma_f32_16x16x32_bf16 v[52:55], v[202:205], v[162:165], v[52:55]
	v_mfma_f32_16x16x32_bf16 v[40:43], v[194:197], v[170:173], v[40:43]
	v_mfma_f32_16x16x32_bf16 v[36:39], v[202:205], v[170:173], v[36:39]
	v_mfma_f32_16x16x32_bf16 v[24:27], v[194:197], v[178:181], v[24:27]
	v_mfma_f32_16x16x32_bf16 v[20:23], v[202:205], v[178:181], v[20:23]
	v_mfma_f32_16x16x32_bf16 v[8:11], v[194:197], v[186:189], v[8:11]
	v_mfma_f32_16x16x32_bf16 v[4:7], v[202:205], v[186:189], v[4:7]
	v_mfma_f32_16x16x32_bf16 v[56:59], v[198:201], v[166:169], v[56:59]
	v_mfma_f32_16x16x32_bf16 v[52:55], v[206:209], v[166:169], v[52:55]
	v_mfma_f32_16x16x32_bf16 v[40:43], v[198:201], v[174:177], v[40:43]
	v_mfma_f32_16x16x32_bf16 v[36:39], v[206:209], v[174:177], v[36:39]
	v_mfma_f32_16x16x32_bf16 v[24:27], v[198:201], v[182:185], v[24:27]
	v_mfma_f32_16x16x32_bf16 v[20:23], v[206:209], v[182:185], v[20:23]
	v_mfma_f32_16x16x32_bf16 v[8:11], v[198:201], v[190:193], v[8:11]
	v_mfma_f32_16x16x32_bf16 v[4:7], v[206:209], v[190:193], v[4:7]
	s_barrier
	s_setprio 0
	s_add_i32 s56, 0, 0x18000
	v_add_u32_e32 v2, s56, v1
	ds_read_b128 v[144:147], v2
	ds_read_b128 v[150:153], v2 offset:1024
	ds_read_b128 v[154:157], v2 offset:2048
	ds_read_b128 v[158:161], v2 offset:3072
	s_add_u32 s24, s24, 0x80000
	s_addc_u32 s25, s25, 0
	ds_read_b128 v[162:165], v149 offset:32768
	ds_read_b128 v[166:169], v149 offset:33792
	ds_read_b128 v[170:173], v149 offset:34816
	ds_read_b128 v[174:177], v149 offset:35840
	ds_read_b128 v[178:181], v149 offset:36864
	ds_read_b128 v[182:185], v149 offset:37888
	ds_read_b128 v[186:189], v149 offset:38912
	ds_read_b128 v[190:193], v149 offset:39936
	s_mov_b32 m0, s36
	s_nop 0
	global_load_lds_dwordx4 v138, s[24:25]
	s_mov_b32 m0, s37
	s_nop 0
	global_load_lds_dwordx4 v134, s[24:25]
	s_add_i32 s24, 0, 0x1c000
	v_add_u32_e32 v2, s24, v1
	ds_read_b128 v[194:197], v2
	ds_read_b128 v[198:201], v2 offset:1024
	ds_read_b128 v[202:205], v2 offset:2048
	ds_read_b128 v[206:209], v2 offset:3072
	s_waitcnt lgkmcnt(0)
	s_setprio 1
	s_barrier
	v_mfma_f32_16x16x32_bf16 v[128:131], v[144:147], v[162:165], v[128:131]
	v_mfma_f32_16x16x32_bf16 v[124:127], v[154:157], v[162:165], v[124:127]
	v_mfma_f32_16x16x32_bf16 v[112:115], v[144:147], v[170:173], v[112:115]
	v_mfma_f32_16x16x32_bf16 v[108:111], v[154:157], v[170:173], v[108:111]
	v_mfma_f32_16x16x32_bf16 v[96:99], v[144:147], v[178:181], v[96:99]
	v_mfma_f32_16x16x32_bf16 v[92:95], v[154:157], v[178:181], v[92:95]
	v_mfma_f32_16x16x32_bf16 v[80:83], v[144:147], v[186:189], v[80:83]
	v_mfma_f32_16x16x32_bf16 v[76:79], v[154:157], v[186:189], v[76:79]
	v_mfma_f32_16x16x32_bf16 v[128:131], v[150:153], v[166:169], v[128:131]
	v_mfma_f32_16x16x32_bf16 v[124:127], v[158:161], v[166:169], v[124:127]
	v_mfma_f32_16x16x32_bf16 v[112:115], v[150:153], v[174:177], v[112:115]
	v_mfma_f32_16x16x32_bf16 v[108:111], v[158:161], v[174:177], v[108:111]
	v_mfma_f32_16x16x32_bf16 v[96:99], v[150:153], v[182:185], v[96:99]
	v_mfma_f32_16x16x32_bf16 v[92:95], v[158:161], v[182:185], v[92:95]
	v_mfma_f32_16x16x32_bf16 v[80:83], v[150:153], v[190:193], v[80:83]
	v_mfma_f32_16x16x32_bf16 v[76:79], v[158:161], v[190:193], v[76:79]
	v_mfma_f32_16x16x32_bf16 v[120:123], v[194:197], v[162:165], v[120:123]
	v_mfma_f32_16x16x32_bf16 v[116:119], v[202:205], v[162:165], v[116:119]
	v_mfma_f32_16x16x32_bf16 v[104:107], v[194:197], v[170:173], v[104:107]
	v_mfma_f32_16x16x32_bf16 v[100:103], v[202:205], v[170:173], v[100:103]
	v_mfma_f32_16x16x32_bf16 v[88:91], v[194:197], v[178:181], v[88:91]
	v_mfma_f32_16x16x32_bf16 v[84:87], v[202:205], v[178:181], v[84:87]
	v_mfma_f32_16x16x32_bf16 v[72:75], v[194:197], v[186:189], v[72:75]
	v_mfma_f32_16x16x32_bf16 v[68:71], v[202:205], v[186:189], v[68:71]
	v_mfma_f32_16x16x32_bf16 v[120:123], v[198:201], v[166:169], v[120:123]
	v_mfma_f32_16x16x32_bf16 v[116:119], v[206:209], v[166:169], v[116:119]
	v_mfma_f32_16x16x32_bf16 v[104:107], v[198:201], v[174:177], v[104:107]
	v_mfma_f32_16x16x32_bf16 v[100:103], v[206:209], v[174:177], v[100:103]
	v_mfma_f32_16x16x32_bf16 v[88:91], v[198:201], v[182:185], v[88:91]
	v_mfma_f32_16x16x32_bf16 v[84:87], v[206:209], v[182:185], v[84:87]
	v_mfma_f32_16x16x32_bf16 v[72:75], v[198:201], v[190:193], v[72:75]
	v_mfma_f32_16x16x32_bf16 v[68:71], v[206:209], v[190:193], v[68:71]
	s_barrier
; __device__ __forceinline__ int opaque_tid() { int t = threadIdx.x; asm volatile("" : "+v"(t)); return t; }
; #define PG8_STAGE(bufoff, gbase, voff) do { _Pragma("unroll") for (int _i = 0; _i < 2; ++_i) \
;         __builtin_amdgcn_global_load_lds((const unsigned*)((const char*)(gbase) + (voff)[_i]), (LAS unsigned*)(lds + (bufoff) + ldsw + _i * 8192), 16, 0, 0); } while (0)
; #define PG8_MMA(ai, bj, At, Bt) do { __builtin_amdgcn_s_setprio(1); _Pragma("unroll") for (int m = 0; m < 4; ++m) _Pragma("unroll") for (int n = 0; n < 2; ++n) _Pragma("unroll") for (int k = 0; k < 2; ++k) \
;         acc[ai][bj][m][n] = __builtin_amdgcn_mfma_f32_16x16x32_bf16(Bt[n][k], At[m][k], acc[ai][bj][m][n], 0, 0, 0); __builtin_amdgcn_s_setprio(0); } while (0)
; #define PG8_WAIT_V(n) asm volatile("s_waitcnt vmcnt(" #n ")" ::: "memory")
; #define PG8_WAIT_L(n) asm volatile("s_waitcnt lgkmcnt(" #n ")" ::: "memory")
; #define PG8_BAR __builtin_amdgcn_s_barrier()
; #define PG8_SCHED __builtin_amdgcn_sched_barrier(0)
; template <class Epi, class Sched>
; __device__ __forceinline__ void gemm_phase(LAS unsigned char* lds, const Gemm g, const Sched& S, const Epi& E) {
;     ...
;             PG8_BAR; PG8_WAIT_L(0); PG8_MMA(1, 0, At, B0); PG8_BAR; PG8_SCHED;
;             PG8_STAGE(PG8_SB(1, 1), b3 + hstepB, voffB);
;             PG8_WAIT_V(6); PG8_BAR; PG8_MMA(1, 1, At, B1); PG8_BAR;
;     __device__ __forceinline__ void operator()(const f32x4 (&acc)[2][2][4][2], const Unit& u, int wr, int wc, int ui, int) const {
;         const int ol_ = opaque_tid() & 63, fr = ol_ & 15, fq = ol_ >> 4;
;         const int row0 = u.pm * BM + wr * 64 + fr, col0 = u.pn * BM + wc * 32 + 8 * fq;
;         const bool cmp = (u.pn == 8 || u.pn == 9);
;         bf16_t* cb = (u.pn == 8) ? kcmp : vcmp;
;         float r_[2][4];
;         rs_read(r_, ui, wr, fr);
	s_setprio 0
	ds_read_b128 v[162:165], v149 offset:49152
	ds_read_b128 v[166:169], v149 offset:50176
	ds_read_b128 v[170:173], v149 offset:51200
	ds_read_b128 v[174:177], v149 offset:52224
	ds_read_b128 v[178:181], v149 offset:53248
	ds_read_b128 v[182:185], v149 offset:54272
	ds_read_b128 v[186:189], v149 offset:55296
	ds_read_b128 v[190:193], v149 offset:56320
	s_add_i32 s25, s56, s30
	v_lshl_add_u64 v[210:211], v[210:211], 0, s[8:9]
	s_mov_b32 m0, s25
	s_nop 0
	global_load_lds_dwordx4 v[210:211], off
	v_lshl_add_u64 v[210:211], v[212:213], 0, s[8:9]
	s_add_i32 m0, s25, 0x2000
	s_nop 0
	global_load_lds_dwordx4 v[210:211], off
	s_mov_b32 m0, s40
	v_lshl_add_u64 v[210:211], v[216:217], 0, s[8:9]
	global_load_lds_dwordx4 v[210:211], off
	v_lshl_add_u64 v[210:211], v[218:219], 0, s[8:9]
	s_mov_b32 m0, s41
	s_nop 0
	global_load_lds_dwordx4 v[210:211], off
	s_add_u32 s20, s20, 0x80080
	s_addc_u32 s21, s21, 0
	s_add_i32 s24, s24, s30
	s_mov_b32 m0, s24
	s_nop 0
	global_load_lds_dwordx4 v136, s[20:21]
	s_add_i32 m0, s24, 0x2000
	s_nop 0
	global_load_lds_dwordx4 v132, s[20:21]
	s_add_i32 s55, s55, 2
	s_add_u32 s6, s6, 0x100
	s_addc_u32 s7, s7, 0
	s_add_u32 s53, s53, 0x100
	s_addc_u32 s54, s54, 0
	s_cmp_gt_u32 s55, 29
	s_waitcnt lgkmcnt(0)
	s_waitcnt vmcnt(6)
	s_setprio 1
	s_barrier
	v_mfma_f32_16x16x32_bf16 v[64:67], v[144:147], v[162:165], v[64:67]
	v_mfma_f32_16x16x32_bf16 v[60:63], v[154:157], v[162:165], v[60:63]
	v_mfma_f32_16x16x32_bf16 v[48:51], v[144:147], v[170:173], v[48:51]
	v_mfma_f32_16x16x32_bf16 v[44:47], v[154:157], v[170:173], v[44:47]
	v_mfma_f32_16x16x32_bf16 v[32:35], v[144:147], v[178:181], v[32:35]
	v_mfma_f32_16x16x32_bf16 v[28:31], v[154:157], v[178:181], v[28:31]
	v_mfma_f32_16x16x32_bf16 v[16:19], v[144:147], v[186:189], v[16:19]
	v_mfma_f32_16x16x32_bf16 v[12:15], v[154:157], v[186:189], v[12:15]
	v_mfma_f32_16x16x32_bf16 v[64:67], v[150:153], v[166:169], v[64:67]
	v_mfma_f32_16x16x32_bf16 v[60:63], v[158:161], v[166:169], v[60:63]
	v_mfma_f32_16x16x32_bf16 v[48:51], v[150:153], v[174:177], v[48:51]
	v_mfma_f32_16x16x32_bf16 v[44:47], v[158:161], v[174:177], v[44:47]
	v_mfma_f32_16x16x32_bf16 v[32:35], v[150:153], v[182:185], v[32:35]
	v_mfma_f32_16x16x32_bf16 v[28:31], v[158:161], v[182:185], v[28:31]
	v_mfma_f32_16x16x32_bf16 v[16:19], v[150:153], v[190:193], v[16:19]
	v_mfma_f32_16x16x32_bf16 v[12:15], v[158:161], v[190:193], v[12:15]
	v_mfma_f32_16x16x32_bf16 v[56:59], v[194:197], v[162:165], v[56:59]
	v_mfma_f32_16x16x32_bf16 v[52:55], v[202:205], v[162:165], v[52:55]
	v_mfma_f32_16x16x32_bf16 v[40:43], v[194:197], v[170:173], v[40:43]
	v_mfma_f32_16x16x32_bf16 v[36:39], v[202:205], v[170:173], v[36:39]
	v_mfma_f32_16x16x32_bf16 v[24:27], v[194:197], v[178:181], v[24:27]
	v_mfma_f32_16x16x32_bf16 v[20:23], v[202:205], v[178:181], v[20:23]
	v_mfma_f32_16x16x32_bf16 v[8:11], v[194:197], v[186:189], v[8:11]
	v_mfma_f32_16x16x32_bf16 v[4:7], v[202:205], v[186:189], v[4:7]
	v_mfma_f32_16x16x32_bf16 v[56:59], v[198:201], v[166:169], v[56:59]
	v_mfma_f32_16x16x32_bf16 v[52:55], v[206:209], v[166:169], v[52:55]
	v_mfma_f32_16x16x32_bf16 v[40:43], v[198:201], v[174:177], v[40:43]
	v_mfma_f32_16x16x32_bf16 v[36:39], v[206:209], v[174:177], v[36:39]
	v_mfma_f32_16x16x32_bf16 v[24:27], v[198:201], v[182:185], v[24:27]
	v_mfma_f32_16x16x32_bf16 v[20:23], v[206:209], v[182:185], v[20:23]
	v_mfma_f32_16x16x32_bf16 v[8:11], v[198:201], v[190:193], v[8:11]
	v_mfma_f32_16x16x32_bf16 v[4:7], v[206:209], v[190:193], v[4:7]
	s_barrier
	s_cbranch_scc0 .LBB0_352
	s_setprio 0
	s_cmpk_gt_u32 s2, 0xff
	s_cbranch_scc1 .Lalign_a_352
	s_barrier
.Lalign_a_352:
	s_lshl_b32 s1, s50, 8
	s_lshl_b32 s6, s44, 8
	s_add_i32 s1, s1, s38
	s_or_b32 s6, s6, s39
	s_cmp_eq_u32 s44, 8
	s_mov_b32 s7, 0x3bcb0000
	s_cselect_b32 s15, s7, 0x3ccb4000
	s_lshl_b32 s7, s45, 10
	v_mov_b32_e32 v2, v0
	s_and_b32 s7, s7, 0x400
	s_add_i32 s7, s46, s7
	v_and_b32_e32 v144, 15, v2
	v_or_b32_e32 v148, s1, v144
	v_lshl_add_u32 v144, v144, 2, s7
	v_lshrrev_b32_e32 v2, 1, v2
	ds_read2_b32 v[164:165], v144 offset1:16
	ds_read2_b32 v[160:161], v144 offset0:32 offset1:48
	ds_read2_b32 v[156:157], v144 offset0:128 offset1:144
	ds_read2_b32 v[152:153], v144 offset0:160 offset1:176
	v_and_b32_e32 v2, 24, v2
	v_or_b32_e32 v146, s6, v2
	s_and_b32 s6, s44, -2
	s_cmp_lg_u32 s6, 8
	s_cselect_b64 s[6:7], -1, 0
	s_add_u32 s24, s47, s15
	s_waitcnt lgkmcnt(0)
	v_mov_b32_e32 v162, v165
	v_mov_b32_e32 v158, v161
	v_mov_b32_e32 v154, v157
	v_mov_b32_e32 v144, v153
	v_ashrrev_i32_e32 v147, 31, v146
	s_addc_u32 s25, s48, 0
	s_mov_b64 s[20:21], -1
	s_and_b64 vcc, exec, s[6:7]
	s_cbranch_vccz .LBB0_355
	v_mov_b64_e32 v[150:151], s[92:93]
	s_movk_i32 s15, 0x3600
	v_mad_i64_i32 v[150:151], s[20:21], v148, s15, v[150:151]
	v_lshl_add_u64 v[170:171], v[146:147], 1, v[150:151]
	s_mov_b64 s[20:21], 0

; #define PG8_STAGE(bufoff, gbase, voff) do { _Pragma("unroll") for (int _i = 0; _i < 2; ++_i) \
;         __builtin_amdgcn_global_load_lds((const unsigned*)((const char*)(gbase) + (voff)[_i]), (LAS unsigned*)(lds + (bufoff) + ldsw + _i * 8192), 16, 0, 0); } while (0)
; #define PG8_LDA(dst, b, h) do { _Pragma("unroll") for (int m = 0; m < 4; ++m) _Pragma("unroll") for (int k = 0; k < 2; ++k) dst[m][k] = *(const LAS bf16x8*)(lds + PG8_SA(b, h) + aoff + m * 2048 + k * 1024); } while (0)
; #define PG8_LDB(dst, b, h) do { _Pragma("unroll") for (int n = 0; n < 2; ++n) _Pragma("unroll") for (int k = 0; k < 2; ++k) dst[n][k] = *(const LAS bf16x8*)(lds + PG8_SB(b, h) + boff + n * 2048 + k * 1024); } while (0)
; #define PG8_MMA(ai, bj, At, Bt) do { __builtin_amdgcn_s_setprio(1); _Pragma("unroll") for (int m = 0; m < 4; ++m) _Pragma("unroll") for (int n = 0; n < 2; ++n) _Pragma("unroll") for (int k = 0; k < 2; ++k) \
;         acc[ai][bj][m][n] = __builtin_amdgcn_mfma_f32_16x16x32_bf16(Bt[n][k], At[m][k], acc[ai][bj][m][n], 0, 0, 0); __builtin_amdgcn_s_setprio(0); } while (0)
; #define PG8_WAIT_V(n) asm volatile("s_waitcnt vmcnt(" #n ")" ::: "memory")
; #define PG8_WAIT_L(n) asm volatile("s_waitcnt lgkmcnt(" #n ")" ::: "memory")
; #define PG8_BAR __builtin_amdgcn_s_barrier()
; #define PG8_SCHED __builtin_amdgcn_sched_barrier(0)
; template <class Epi, class Sched>
; __device__ __forceinline__ void gemm_phase(LAS unsigned char* lds, const Gemm g, const Sched& S, const Epi& E) {
;     ...
;             PG8_LDB(B0, 0, 0); PG8_SCHED; PG8_LDA(At, 0, 0); PG8_STAGE(PG8_SA(1, 1), a1 + hstepA, voffA);
;             PG8_WAIT_L(8); PG8_BAR; PG8_WAIT_L(0); PG8_MMA(0, 0, At, B0); PG8_BAR; PG8_SCHED;
;             PG8_LDB(B1, 0, 1); PG8_STAGE(PG8_SB(0, 0), b2, voffB);
;             PG8_BAR; PG8_WAIT_L(0); PG8_MMA(0, 1, At, B1); PG8_BAR;
;             PG8_LDA(At, 0, 1); PG8_STAGE(PG8_SA(0, 0), a2, voffA);
;             PG8_BAR; PG8_WAIT_L(0); PG8_MMA(1, 0, At, B0); PG8_BAR; PG8_SCHED;
;             PG8_STAGE(PG8_SB(0, 1), b2 + hstepB, voffB);
;             PG8_WAIT_V(6); PG8_BAR; PG8_MMA(1, 1, At, B1); PG8_BAR;
.LBB0_966:
	s_setprio 0
	s_add_u32 s20, s6, 0xfff80080
	s_addc_u32 s21, s7, -1
	s_add_i32 s52, 0, 0x10000
	v_add_u32_e32 v144, s52, v1
	ds_read_b128 v[132:135], v144
	ds_read_b128 v[136:139], v144 offset:1024
	ds_read_b128 v[140:143], v144 offset:2048
	ds_read_b128 v[144:147], v144 offset:3072
	s_cmp_eq_u32 s51, 28
	s_cselect_b32 s25, s15, s21
	s_cselect_b32 s24, s47, s20
	s_cselect_b32 s21, s1, s50
	s_cselect_b32 s20, s48, s49
	ds_read_b128 v[148:151], v224
	ds_read_b128 v[152:155], v224 offset:1024
	ds_read_b128 v[156:159], v224 offset:2048
	ds_read_b128 v[160:163], v224 offset:3072
	ds_read_b128 v[164:167], v224 offset:4096
	ds_read_b128 v[168:171], v224 offset:5120
	ds_read_b128 v[172:175], v224 offset:6144
	ds_read_b128 v[176:179], v224 offset:7168
	s_add_i32 s54, 0, 0x14000
	v_add_u32_e32 v202, s54, v1
	ds_read_b128 v[180:183], v202
	ds_read_b128 v[184:187], v202 offset:1024
	ds_read_b128 v[188:191], v202 offset:2048
	ds_read_b128 v[202:205], v202 offset:3072
	s_add_i32 m0, s31, 0xc000
	s_nop 0
	global_load_lds_dwordx4 v198, s[6:7]
	s_add_i32 m0, s31, 0xe000
	s_nop 0
	global_load_lds_dwordx4 v200, s[6:7]
	s_waitcnt lgkmcnt(0)
	s_setprio 1
	s_barrier
	v_mfma_f32_16x16x32_bf16 v[128:131], v[132:135], v[148:151], v[128:131]
	v_mfma_f32_16x16x32_bf16 v[124:127], v[140:143], v[148:151], v[124:127]
	v_mfma_f32_16x16x32_bf16 v[112:115], v[132:135], v[156:159], v[112:115]
	v_mfma_f32_16x16x32_bf16 v[108:111], v[140:143], v[156:159], v[108:111]
	v_mfma_f32_16x16x32_bf16 v[100:103], v[132:135], v[164:167], v[100:103]
	v_mfma_f32_16x16x32_bf16 v[92:95], v[140:143], v[164:167], v[92:95]
	v_mfma_f32_16x16x32_bf16 v[84:87], v[132:135], v[172:175], v[84:87]
	v_mfma_f32_16x16x32_bf16 v[76:79], v[140:143], v[172:175], v[76:79]
	v_mfma_f32_16x16x32_bf16 v[128:131], v[136:139], v[152:155], v[128:131]
	v_mfma_f32_16x16x32_bf16 v[124:127], v[144:147], v[152:155], v[124:127]
	v_mfma_f32_16x16x32_bf16 v[112:115], v[136:139], v[160:163], v[112:115]
	v_mfma_f32_16x16x32_bf16 v[108:111], v[144:147], v[160:163], v[108:111]
	v_mfma_f32_16x16x32_bf16 v[100:103], v[136:139], v[168:171], v[100:103]
	v_mfma_f32_16x16x32_bf16 v[92:95], v[144:147], v[168:171], v[92:95]
	v_mfma_f32_16x16x32_bf16 v[84:87], v[136:139], v[176:179], v[84:87]
	v_mfma_f32_16x16x32_bf16 v[76:79], v[144:147], v[176:179], v[76:79]
	v_mfma_f32_16x16x32_bf16 v[120:123], v[180:183], v[148:151], v[120:123]
	v_mfma_f32_16x16x32_bf16 v[116:119], v[188:191], v[148:151], v[116:119]
	v_mfma_f32_16x16x32_bf16 v[104:107], v[180:183], v[156:159], v[104:107]
	v_mfma_f32_16x16x32_bf16 v[96:99], v[188:191], v[156:159], v[96:99]
	v_mfma_f32_16x16x32_bf16 v[88:91], v[180:183], v[164:167], v[88:91]
	v_mfma_f32_16x16x32_bf16 v[80:83], v[188:191], v[164:167], v[80:83]
	v_mfma_f32_16x16x32_bf16 v[72:75], v[180:183], v[172:175], v[72:75]
	v_mfma_f32_16x16x32_bf16 v[68:71], v[188:191], v[172:175], v[68:71]
	v_mfma_f32_16x16x32_bf16 v[120:123], v[184:187], v[152:155], v[120:123]
	v_mfma_f32_16x16x32_bf16 v[116:119], v[202:205], v[152:155], v[116:119]
	v_mfma_f32_16x16x32_bf16 v[104:107], v[184:187], v[160:163], v[104:107]
	v_mfma_f32_16x16x32_bf16 v[96:99], v[202:205], v[160:163], v[96:99]
	v_mfma_f32_16x16x32_bf16 v[88:91], v[184:187], v[168:171], v[88:91]
	v_mfma_f32_16x16x32_bf16 v[80:83], v[202:205], v[168:171], v[80:83]
	v_mfma_f32_16x16x32_bf16 v[72:75], v[184:187], v[176:179], v[72:75]
	v_mfma_f32_16x16x32_bf16 v[68:71], v[202:205], v[176:179], v[68:71]
	s_barrier
	s_setprio 0
	ds_read_b128 v[148:151], v224 offset:16384
	ds_read_b128 v[152:155], v224 offset:17408
	ds_read_b128 v[156:159], v224 offset:18432
	ds_read_b128 v[160:163], v224 offset:19456
	ds_read_b128 v[164:167], v224 offset:20480
	ds_read_b128 v[168:171], v224 offset:21504
	ds_read_b128 v[172:175], v224 offset:22528
	ds_read_b128 v[176:179], v224 offset:23552
	s_add_i32 s52, s52, s30
	v_lshl_add_u64 v[206:207], s[20:21], 0, v[2:3]
	s_mov_b32 m0, s52
	s_nop 0
	global_load_lds_dwordx4 v[206:207], off
	v_lshl_add_u64 v[208:209], s[20:21], 0, v[192:193]
	s_add_i32 m0, s52, 0x2000
	s_nop 0
	global_load_lds_dwordx4 v[208:209], off
	s_mov_b32 m0, s31
	v_lshl_add_u64 v[210:211], s[24:25], 0, v[196:197]
	global_load_lds_dwordx4 v[210:211], off
	v_lshl_add_u64 v[212:213], s[24:25], 0, v[194:195]
	s_mov_b32 m0, s35
	s_nop 0
	global_load_lds_dwordx4 v[212:213], off
	s_add_u32 s52, s20, 0x80000
	s_addc_u32 s53, s21, 0
	s_add_i32 s54, s54, s30
	s_mov_b32 m0, s54
	s_nop 0
	global_load_lds_dwordx4 v2, s[52:53]
	s_add_i32 m0, s54, 0x2000
	s_nop 0
	global_load_lds_dwordx4 v192, s[52:53]
	s_waitcnt lgkmcnt(0)
	s_waitcnt vmcnt(6)
	s_setprio 1
	s_barrier
; #define PG8_STAGE(bufoff, gbase, voff) do { _Pragma("unroll") for (int _i = 0; _i < 2; ++_i) \
;         __builtin_amdgcn_global_load_lds((const unsigned*)((const char*)(gbase) + (voff)[_i]), (LAS unsigned*)(lds + (bufoff) + ldsw + _i * 8192), 16, 0, 0); } while (0)
; #define PG8_LDA(dst, b, h) do { _Pragma("unroll") for (int m = 0; m < 4; ++m) _Pragma("unroll") for (int k = 0; k < 2; ++k) dst[m][k] = *(const LAS bf16x8*)(lds + PG8_SA(b, h) + aoff + m * 2048 + k * 1024); } while (0)
; #define PG8_LDB(dst, b, h) do { _Pragma("unroll") for (int n = 0; n < 2; ++n) _Pragma("unroll") for (int k = 0; k < 2; ++k) dst[n][k] = *(const LAS bf16x8*)(lds + PG8_SB(b, h) + boff + n * 2048 + k * 1024); } while (0)
; #define PG8_MMA(ai, bj, At, Bt) do { __builtin_amdgcn_s_setprio(1); _Pragma("unroll") for (int m = 0; m < 4; ++m) _Pragma("unroll") for (int n = 0; n < 2; ++n) _Pragma("unroll") for (int k = 0; k < 2; ++k) \
;         acc[ai][bj][m][n] = __builtin_amdgcn_mfma_f32_16x16x32_bf16(Bt[n][k], At[m][k], acc[ai][bj][m][n], 0, 0, 0); __builtin_amdgcn_s_setprio(0); } while (0)
; #define PG8_WAIT_V(n) asm volatile("s_waitcnt vmcnt(" #n ")" ::: "memory")
; #define PG8_WAIT_L(n) asm volatile("s_waitcnt lgkmcnt(" #n ")" ::: "memory")
; #define PG8_BAR __builtin_amdgcn_s_barrier()
; #define PG8_SCHED __builtin_amdgcn_sched_barrier(0)
; template <class Epi, class Sched>
; __device__ __forceinline__ void gemm_phase(LAS unsigned char* lds, const Gemm g, const Sched& S, const Epi& E) {
;     ...
;             PG8_BAR; PG8_WAIT_L(0); PG8_MMA(1, 0, At, B0); PG8_BAR; PG8_SCHED;
;             PG8_STAGE(PG8_SB(0, 1), b2 + hstepB, voffB);
;             PG8_WAIT_V(6); PG8_BAR; PG8_MMA(1, 1, At, B1); PG8_BAR;
;             PG8_LDB(B0, 1, 0); PG8_SCHED; PG8_LDA(At, 1, 0); PG8_STAGE(PG8_SA(0, 1), a2 + hstepA, voffA);
;             PG8_WAIT_L(8); PG8_BAR; PG8_WAIT_L(0); PG8_MMA(0, 0, At, B0); PG8_BAR; PG8_SCHED;
;             PG8_LDB(B1, 1, 1); PG8_STAGE(PG8_SB(1, 0), b3, voffB);
;             PG8_BAR; PG8_WAIT_L(0); PG8_MMA(0, 1, At, B1); PG8_BAR;
;             PG8_LDA(At, 1, 1); PG8_STAGE(PG8_SA(1, 0), a3, voffA);
;             PG8_BAR; PG8_WAIT_L(0); PG8_MMA(1, 0, At, B0); PG8_BAR; PG8_SCHED;
	v_mfma_f32_16x16x32_bf16 v[64:67], v[132:135], v[148:151], v[64:67]
	v_mfma_f32_16x16x32_bf16 v[60:63], v[140:143], v[148:151], v[60:63]
	v_mfma_f32_16x16x32_bf16 v[52:55], v[132:135], v[156:159], v[52:55]
	v_mfma_f32_16x16x32_bf16 v[44:47], v[140:143], v[156:159], v[44:47]
	v_mfma_f32_16x16x32_bf16 v[36:39], v[132:135], v[164:167], v[36:39]
	v_mfma_f32_16x16x32_bf16 v[28:31], v[140:143], v[164:167], v[28:31]
	v_mfma_f32_16x16x32_bf16 v[20:23], v[132:135], v[172:175], v[20:23]
	v_mfma_f32_16x16x32_bf16 v[12:15], v[140:143], v[172:175], v[12:15]
	v_mfma_f32_16x16x32_bf16 v[64:67], v[136:139], v[152:155], v[64:67]
	v_mfma_f32_16x16x32_bf16 v[60:63], v[144:147], v[152:155], v[60:63]
	v_mfma_f32_16x16x32_bf16 v[52:55], v[136:139], v[160:163], v[52:55]
	v_mfma_f32_16x16x32_bf16 v[44:47], v[144:147], v[160:163], v[44:47]
	v_mfma_f32_16x16x32_bf16 v[36:39], v[136:139], v[168:171], v[36:39]
	v_mfma_f32_16x16x32_bf16 v[28:31], v[144:147], v[168:171], v[28:31]
	v_mfma_f32_16x16x32_bf16 v[20:23], v[136:139], v[176:179], v[20:23]
	v_mfma_f32_16x16x32_bf16 v[12:15], v[144:147], v[176:179], v[12:15]
	v_mfma_f32_16x16x32_bf16 v[56:59], v[180:183], v[148:151], v[56:59]
	v_mfma_f32_16x16x32_bf16 v[48:51], v[188:191], v[148:151], v[48:51]
	v_mfma_f32_16x16x32_bf16 v[40:43], v[180:183], v[156:159], v[40:43]
	v_mfma_f32_16x16x32_bf16 v[32:35], v[188:191], v[156:159], v[32:35]
	v_mfma_f32_16x16x32_bf16 v[24:27], v[180:183], v[164:167], v[24:27]
	v_mfma_f32_16x16x32_bf16 v[16:19], v[188:191], v[164:167], v[16:19]
	v_mfma_f32_16x16x32_bf16 v[8:11], v[180:183], v[172:175], v[8:11]
	v_mfma_f32_16x16x32_bf16 v[4:7], v[188:191], v[172:175], v[4:7]
	v_mfma_f32_16x16x32_bf16 v[56:59], v[184:187], v[152:155], v[56:59]
	v_mfma_f32_16x16x32_bf16 v[48:51], v[202:205], v[152:155], v[48:51]
	v_mfma_f32_16x16x32_bf16 v[40:43], v[184:187], v[160:163], v[40:43]
	v_mfma_f32_16x16x32_bf16 v[32:35], v[202:205], v[160:163], v[32:35]
	v_mfma_f32_16x16x32_bf16 v[24:27], v[184:187], v[168:171], v[24:27]
	v_mfma_f32_16x16x32_bf16 v[16:19], v[202:205], v[168:171], v[16:19]
	v_mfma_f32_16x16x32_bf16 v[8:11], v[184:187], v[176:179], v[8:11]
	v_mfma_f32_16x16x32_bf16 v[4:7], v[202:205], v[176:179], v[4:7]
	s_barrier
	s_setprio 0
	s_add_i32 s52, 0, 0x18000
	v_add_u32_e32 v144, s52, v1
	ds_read_b128 v[132:135], v144
	ds_read_b128 v[136:139], v144 offset:1024
	ds_read_b128 v[140:143], v144 offset:2048
	ds_read_b128 v[144:147], v144 offset:3072
	s_add_u32 s24, s24, 0x80000
	s_addc_u32 s25, s25, 0
	ds_read_b128 v[148:151], v224 offset:32768
	ds_read_b128 v[152:155], v224 offset:33792
	ds_read_b128 v[156:159], v224 offset:34816
	ds_read_b128 v[160:163], v224 offset:35840
	ds_read_b128 v[164:167], v224 offset:36864
	ds_read_b128 v[168:171], v224 offset:37888
	ds_read_b128 v[172:175], v224 offset:38912
	ds_read_b128 v[176:179], v224 offset:39936
	s_mov_b32 m0, s36
	s_nop 0
	global_load_lds_dwordx4 v196, s[24:25]
	s_mov_b32 m0, s37
	s_nop 0
	global_load_lds_dwordx4 v194, s[24:25]
	s_add_i32 s24, 0, 0x1c000
	v_add_u32_e32 v202, s24, v1
	ds_read_b128 v[180:183], v202
	ds_read_b128 v[184:187], v202 offset:1024
	ds_read_b128 v[188:191], v202 offset:2048
	ds_read_b128 v[202:205], v202 offset:3072
	s_waitcnt lgkmcnt(0)
	s_setprio 1
	s_barrier
	v_mfma_f32_16x16x32_bf16 v[128:131], v[132:135], v[148:151], v[128:131]
	v_mfma_f32_16x16x32_bf16 v[124:127], v[140:143], v[148:151], v[124:127]
	v_mfma_f32_16x16x32_bf16 v[112:115], v[132:135], v[156:159], v[112:115]
	v_mfma_f32_16x16x32_bf16 v[108:111], v[140:143], v[156:159], v[108:111]
	v_mfma_f32_16x16x32_bf16 v[100:103], v[132:135], v[164:167], v[100:103]
	v_mfma_f32_16x16x32_bf16 v[92:95], v[140:143], v[164:167], v[92:95]
	v_mfma_f32_16x16x32_bf16 v[84:87], v[132:135], v[172:175], v[84:87]
	v_mfma_f32_16x16x32_bf16 v[76:79], v[140:143], v[172:175], v[76:79]
	v_mfma_f32_16x16x32_bf16 v[128:131], v[136:139], v[152:155], v[128:131]
	v_mfma_f32_16x16x32_bf16 v[124:127], v[144:147], v[152:155], v[124:127]
	v_mfma_f32_16x16x32_bf16 v[112:115], v[136:139], v[160:163], v[112:115]
	v_mfma_f32_16x16x32_bf16 v[108:111], v[144:147], v[160:163], v[108:111]
	v_mfma_f32_16x16x32_bf16 v[100:103], v[136:139], v[168:171], v[100:103]
	v_mfma_f32_16x16x32_bf16 v[92:95], v[144:147], v[168:171], v[92:95]
	v_mfma_f32_16x16x32_bf16 v[84:87], v[136:139], v[176:179], v[84:87]
	v_mfma_f32_16x16x32_bf16 v[76:79], v[144:147], v[176:179], v[76:79]
	v_mfma_f32_16x16x32_bf16 v[120:123], v[180:183], v[148:151], v[120:123]
	v_mfma_f32_16x16x32_bf16 v[116:119], v[188:191], v[148:151], v[116:119]
	v_mfma_f32_16x16x32_bf16 v[104:107], v[180:183], v[156:159], v[104:107]
	v_mfma_f32_16x16x32_bf16 v[96:99], v[188:191], v[156:159], v[96:99]
	v_mfma_f32_16x16x32_bf16 v[88:91], v[180:183], v[164:167], v[88:91]
	v_mfma_f32_16x16x32_bf16 v[80:83], v[188:191], v[164:167], v[80:83]
	v_mfma_f32_16x16x32_bf16 v[72:75], v[180:183], v[172:175], v[72:75]
	v_mfma_f32_16x16x32_bf16 v[68:71], v[188:191], v[172:175], v[68:71]
	v_mfma_f32_16x16x32_bf16 v[120:123], v[184:187], v[152:155], v[120:123]
	v_mfma_f32_16x16x32_bf16 v[116:119], v[202:205], v[152:155], v[116:119]
	v_mfma_f32_16x16x32_bf16 v[104:107], v[184:187], v[160:163], v[104:107]
	v_mfma_f32_16x16x32_bf16 v[96:99], v[202:205], v[160:163], v[96:99]
	v_mfma_f32_16x16x32_bf16 v[88:91], v[184:187], v[168:171], v[88:91]
	v_mfma_f32_16x16x32_bf16 v[80:83], v[202:205], v[168:171], v[80:83]
	v_mfma_f32_16x16x32_bf16 v[72:75], v[184:187], v[176:179], v[72:75]
	v_mfma_f32_16x16x32_bf16 v[68:71], v[202:205], v[176:179], v[68:71]
	s_barrier
; __device__ __forceinline__ int opaque_tid() { int t = threadIdx.x; asm volatile("" : "+v"(t)); return t; }
; #define PG8_STAGE(bufoff, gbase, voff) do { _Pragma("unroll") for (int _i = 0; _i < 2; ++_i) \
;         __builtin_amdgcn_global_load_lds((const unsigned*)((const char*)(gbase) + (voff)[_i]), (LAS unsigned*)(lds + (bufoff) + ldsw + _i * 8192), 16, 0, 0); } while (0)
; #define PG8_MMA(ai, bj, At, Bt) do { __builtin_amdgcn_s_setprio(1); _Pragma("unroll") for (int m = 0; m < 4; ++m) _Pragma("unroll") for (int n = 0; n < 2; ++n) _Pragma("unroll") for (int k = 0; k < 2; ++k) \
;         acc[ai][bj][m][n] = __builtin_amdgcn_mfma_f32_16x16x32_bf16(Bt[n][k], At[m][k], acc[ai][bj][m][n], 0, 0, 0); __builtin_amdgcn_s_setprio(0); } while (0)
; #define PG8_WAIT_V(n) asm volatile("s_waitcnt vmcnt(" #n ")" ::: "memory")
; #define PG8_WAIT_L(n) asm volatile("s_waitcnt lgkmcnt(" #n ")" ::: "memory")
; #define PG8_BAR __builtin_amdgcn_s_barrier()
; #define PG8_SCHED __builtin_amdgcn_sched_barrier(0)
;     __device__ __forceinline__ void operator()(const f32x4 (&acc)[2][2][4][2], const Unit& u, int wr, int wc, int, int) const {
;         const int ol_ = opaque_tid() & 63, fr = ol_ & 15, fq = ol_ >> 4;
;         const int row0 = u.pm * BM + wr * 64 + fr, col0 = u.pn * BM + wc * 32 + 8 * fq;
;         u32x4 cin[2][4][2];
; #pragma unroll
;         for (int ai = 0; ai < 2; ++ai)
; #pragma unroll
;             for (int m = 0; m < 4; ++m)
; #pragma unroll
;                 for (int bj = 0; bj < 2; ++bj) cin[ai][m][bj] = *(const u32x4*)(C + (size_t)(row0 + ai * HALF + m * 16) * ldc + col0 + bj * HALF);
; template <class Epi, class Sched>
; __device__ __forceinline__ void gemm_phase(LAS unsigned char* lds, const Gemm g, const Sched& S, const Epi& E) {
;     ...
;             PG8_BAR; PG8_WAIT_L(0); PG8_MMA(1, 0, At, B0); PG8_BAR; PG8_SCHED;
;             PG8_STAGE(PG8_SB(1, 1), b3 + hstepB, voffB);
;             PG8_WAIT_V(6); PG8_BAR; PG8_MMA(1, 1, At, B1); PG8_BAR;
	s_setprio 0
	ds_read_b128 v[148:151], v224 offset:49152
	ds_read_b128 v[152:155], v224 offset:50176
	ds_read_b128 v[156:159], v224 offset:51200
	ds_read_b128 v[160:163], v224 offset:52224
	ds_read_b128 v[164:167], v224 offset:53248
	ds_read_b128 v[168:171], v224 offset:54272
	ds_read_b128 v[172:175], v224 offset:55296
	ds_read_b128 v[176:179], v224 offset:56320
	s_add_i32 s25, s52, s30
	v_lshl_add_u64 v[206:207], v[206:207], 0, s[8:9]
	s_mov_b32 m0, s25
	s_nop 0
	global_load_lds_dwordx4 v[206:207], off
	v_lshl_add_u64 v[206:207], v[208:209], 0, s[8:9]
	s_add_i32 m0, s25, 0x2000
	s_nop 0
	global_load_lds_dwordx4 v[206:207], off
	s_mov_b32 m0, s40
	v_lshl_add_u64 v[206:207], v[210:211], 0, s[8:9]
	global_load_lds_dwordx4 v[206:207], off
	v_lshl_add_u64 v[206:207], v[212:213], 0, s[8:9]
	s_mov_b32 m0, s41
	s_nop 0
	global_load_lds_dwordx4 v[206:207], off
	s_add_u32 s20, s20, 0x80080
	s_addc_u32 s21, s21, 0
	s_add_i32 s24, s24, s30
	s_mov_b32 m0, s24
	s_nop 0
	global_load_lds_dwordx4 v2, s[20:21]
	s_add_i32 m0, s24, 0x2000
	s_nop 0
	global_load_lds_dwordx4 v192, s[20:21]
	s_add_i32 s51, s51, 2
	s_add_u32 s6, s6, 0x100
	s_addc_u32 s7, s7, 0
	s_add_u32 s49, s49, 0x100
	s_addc_u32 s50, s50, 0
	s_cmp_gt_u32 s51, 29
	s_waitcnt lgkmcnt(0)
	s_waitcnt vmcnt(6)
	s_setprio 1
	s_barrier
	v_mfma_f32_16x16x32_bf16 v[64:67], v[132:135], v[148:151], v[64:67]
	v_mfma_f32_16x16x32_bf16 v[60:63], v[140:143], v[148:151], v[60:63]
	v_mfma_f32_16x16x32_bf16 v[52:55], v[132:135], v[156:159], v[52:55]
	v_mfma_f32_16x16x32_bf16 v[44:47], v[140:143], v[156:159], v[44:47]
	v_mfma_f32_16x16x32_bf16 v[36:39], v[132:135], v[164:167], v[36:39]
	v_mfma_f32_16x16x32_bf16 v[28:31], v[140:143], v[164:167], v[28:31]
	v_mfma_f32_16x16x32_bf16 v[20:23], v[132:135], v[172:175], v[20:23]
	v_mfma_f32_16x16x32_bf16 v[12:15], v[140:143], v[172:175], v[12:15]
	v_mfma_f32_16x16x32_bf16 v[64:67], v[136:139], v[152:155], v[64:67]
	v_mfma_f32_16x16x32_bf16 v[60:63], v[144:147], v[152:155], v[60:63]
	v_mfma_f32_16x16x32_bf16 v[52:55], v[136:139], v[160:163], v[52:55]
	v_mfma_f32_16x16x32_bf16 v[44:47], v[144:147], v[160:163], v[44:47]
	v_mfma_f32_16x16x32_bf16 v[36:39], v[136:139], v[168:171], v[36:39]
	v_mfma_f32_16x16x32_bf16 v[28:31], v[144:147], v[168:171], v[28:31]
	v_mfma_f32_16x16x32_bf16 v[20:23], v[136:139], v[176:179], v[20:23]
	v_mfma_f32_16x16x32_bf16 v[12:15], v[144:147], v[176:179], v[12:15]
	v_mfma_f32_16x16x32_bf16 v[56:59], v[180:183], v[148:151], v[56:59]
	v_mfma_f32_16x16x32_bf16 v[48:51], v[188:191], v[148:151], v[48:51]
	v_mfma_f32_16x16x32_bf16 v[40:43], v[180:183], v[156:159], v[40:43]
	v_mfma_f32_16x16x32_bf16 v[32:35], v[188:191], v[156:159], v[32:35]
	v_mfma_f32_16x16x32_bf16 v[24:27], v[180:183], v[164:167], v[24:27]
	v_mfma_f32_16x16x32_bf16 v[16:19], v[188:191], v[164:167], v[16:19]
	v_mfma_f32_16x16x32_bf16 v[8:11], v[180:183], v[172:175], v[8:11]
	v_mfma_f32_16x16x32_bf16 v[4:7], v[188:191], v[172:175], v[4:7]
	v_mfma_f32_16x16x32_bf16 v[56:59], v[184:187], v[152:155], v[56:59]
	v_mfma_f32_16x16x32_bf16 v[48:51], v[202:205], v[152:155], v[48:51]
	v_mfma_f32_16x16x32_bf16 v[40:43], v[184:187], v[160:163], v[40:43]
	v_mfma_f32_16x16x32_bf16 v[32:35], v[202:205], v[160:163], v[32:35]
	v_mfma_f32_16x16x32_bf16 v[24:27], v[184:187], v[168:171], v[24:27]
	v_mfma_f32_16x16x32_bf16 v[16:19], v[202:205], v[168:171], v[16:19]
	v_mfma_f32_16x16x32_bf16 v[8:11], v[184:187], v[176:179], v[8:11]
	v_mfma_f32_16x16x32_bf16 v[4:7], v[202:205], v[176:179], v[4:7]
	s_barrier
	s_cbranch_scc0 .LBB0_966
	s_setprio 0
	s_cmpk_gt_u32 s2, 0xff
	s_cbranch_scc1 .Lalign_a_966
	s_barrier
.Lalign_a_966:
	v_mov_b32_e32 v133, v0
	s_lshl_b32 s1, s46, 8
	s_add_i32 s1, s1, s38
	v_and_or_b32 v132, v133, 15, s1
	s_lshl_b32 s1, s45, 8
	v_lshrrev_b32_e32 v133, 1, v133
	v_and_or_b32 v133, v133, 24, s1
	v_or_b32_e32 v134, s39, v133
	v_ashrrev_i32_e32 v135, 31, v134
	v_lshlrev_b64 v[202:203], 1, v[134:135]
	v_ashrrev_i32_e32 v133, 31, v132
	v_lshl_add_u64 v[134:135], s[88:89], 0, v[202:203]
	v_lshlrev_b64 v[226:227], 12, v[132:133]
	v_lshl_add_u64 v[136:137], v[134:135], 0, v[226:227]
	global_load_dwordx4 v[216:219], v[136:137], off
	global_load_dwordx4 v[188:191], v[136:137], off offset:256
	v_or_b32_e32 v136, 16, v132
	v_ashrrev_i32_e32 v137, 31, v136
	v_lshlrev_b64 v[222:223], 12, v[136:137]
	v_lshl_add_u64 v[136:137], v[134:135], 0, v[222:223]
	global_load_dwordx4 v[184:187], v[136:137], off
	global_load_dwordx4 v[180:183], v[136:137], off offset:256
	v_or_b32_e32 v136, 32, v132
	v_ashrrev_i32_e32 v137, 31, v136
	v_lshlrev_b64 v[220:221], 12, v[136:137]
	v_lshl_add_u64 v[136:137], v[134:135], 0, v[220:221]
	global_load_dwordx4 v[176:179], v[136:137], off
	global_load_dwordx4 v[168:171], v[136:137], off offset:256
	v_or_b32_e32 v132, 48, v132
	v_ashrrev_i32_e32 v133, 31, v132
	v_lshlrev_b64 v[212:213], 12, v[132:133]
	v_lshl_add_u64 v[132:133], v[134:135], 0, v[212:213]
	global_load_dwordx4 v[172:175], v[132:133], off
	global_load_dwordx4 v[164:167], v[132:133], off offset:256
	s_mov_b64 s[6:7], 0x80000
	v_lshl_add_u64 v[210:211], v[226:227], 0, s[6:7]
	v_lshl_add_u64 v[132:133], v[134:135], 0, v[210:211]
	global_load_dwordx4 v[160:163], v[132:133], off
	global_load_dwordx4 v[156:159], v[132:133], off offset:256
	s_mov_b64 s[6:7], 0x90000
	v_lshl_add_u64 v[208:209], v[226:227], 0, s[6:7]
	v_lshl_add_u64 v[132:133], v[134:135], 0, v[208:209]
	global_load_dwordx4 v[152:155], v[132:133], off
	global_load_dwordx4 v[148:151], v[132:133], off offset:256
	s_mov_b64 s[6:7], 0xa0000
	v_lshl_add_u64 v[206:207], v[226:227], 0, s[6:7]
	v_lshl_add_u64 v[132:133], v[134:135], 0, v[206:207]
	global_load_dwordx4 v[144:147], v[132:133], off
	global_load_dwordx4 v[140:143], v[132:133], off offset:256
	s_mov_b64 s[6:7], 0xb0000
	v_lshl_add_u64 v[204:205], v[226:227], 0, s[6:7]
	v_lshl_add_u64 v[132:133], v[134:135], 0, v[204:205]
	global_load_dwordx4 v[136:139], v[132:133], off
	s_nop 0
	global_load_dwordx4 v[132:135], v[132:133], off offset:256
	s_and_b64 vcc, exec, s[42:43]
	s_mov_b32 s45, s0
	s_mov_b32 s46, s14
	s_mov_b64 s[20:21], s[18:19]
	s_mov_b64 s[6:7], s[4:5]
	s_waitcnt vmcnt(15)
; __device__ __forceinline__ unsigned cvt_pk_bf16(float lo, float hi) { const f32x2 v = {lo, hi}; const bf16v2_ r = __builtin_convertvector(v, bf16v2_); return __builtin_bit_cast(unsigned, r); }
; __device__ __forceinline__ float bflo(unsigned w) { return __uint_as_float(w << 16); }
; __device__ __forceinline__ float bfhi(unsigned w) { return __uint_as_float(w & 0xffff0000u); }
;     __device__ __forceinline__ void operator()(const f32x4 (&acc)[2][2][4][2], const Unit& u, int wr, int wc, int, int) const {
;     ...
; #pragma unroll
;         for (int ai = 0; ai < 2; ++ai)
; #pragma unroll
;             for (int m = 0; m < 4; ++m)
; #pragma unroll
;                 for (int bj = 0; bj < 2; ++bj) { const u32x4 c = cin[ai][m][bj]; const f32x4 v0 = acc[ai][bj][m][0], v1 = acc[ai][bj][m][1];
;                     u32x4 w; w.x = cvt_pk_bf16(bflo(c.x) + v0[0], bfhi(c.x) + v0[1]); w.y = cvt_pk_bf16(bflo(c.y) + v0[2], bfhi(c.y) + v0[3]);
;                     w.z = cvt_pk_bf16(bflo(c.z) + v1[0], bfhi(c.z) + v1[1]); w.w = cvt_pk_bf16(bflo(c.w) + v1[2], bfhi(c.w) + v1[3]);
;                     *(u32x4*)(C + (size_t)(row0 + ai * HALF + m * 16) * ldc + col0 + bj * HALF) = w; }
	v_lshlrev_b32_e32 v228, 16, v216
	v_and_b32_e32 v229, 0xffff0000, v216
	v_lshlrev_b32_e32 v216, 16, v217
	v_and_b32_e32 v217, 0xffff0000, v217
	v_pk_add_f32 v[128:129], v[128:129], v[228:229]
	v_pk_add_f32 v[130:131], v[130:131], v[216:217]
	v_cvt_pk_bf16_f32 v128, v128, v129
	v_cvt_pk_bf16_f32 v129, v130, v131
	v_lshlrev_b32_e32 v130, 16, v218
	v_and_b32_e32 v131, 0xffff0000, v218
	v_pk_add_f32 v[124:125], v[124:125], v[130:131]
	s_nop 0
	v_cvt_pk_bf16_f32 v130, v124, v125
	v_lshlrev_b32_e32 v124, 16, v219
	v_and_b32_e32 v125, 0xffff0000, v219
	v_pk_add_f32 v[124:125], v[126:127], v[124:125]
	s_waitcnt vmcnt(14)
	v_lshlrev_b32_e32 v126, 16, v188
	v_and_b32_e32 v127, 0xffff0000, v188
	v_pk_add_f32 v[120:121], v[120:121], v[126:127]
	v_lshlrev_b32_e32 v126, 16, v189
	v_and_b32_e32 v127, 0xffff0000, v189
	v_pk_add_f32 v[122:123], v[122:123], v[126:127]
	v_cvt_pk_bf16_f32 v120, v120, v121
	v_cvt_pk_bf16_f32 v121, v122, v123
	v_lshlrev_b32_e32 v122, 16, v190
	v_and_b32_e32 v123, 0xffff0000, v190
	v_pk_add_f32 v[116:117], v[116:117], v[122:123]
	v_cvt_pk_bf16_f32 v131, v124, v125
	v_cvt_pk_bf16_f32 v122, v116, v117
	v_lshlrev_b32_e32 v116, 16, v191
	v_and_b32_e32 v117, 0xffff0000, v191
	v_pk_add_f32 v[116:117], v[118:119], v[116:117]
	v_lshl_add_u64 v[124:125], s[88:89], 0, v[226:227]
	v_cvt_pk_bf16_f32 v123, v116, v117
	s_waitcnt vmcnt(13)
	v_lshlrev_b32_e32 v116, 16, v184
	v_and_b32_e32 v117, 0xffff0000, v184
	v_pk_add_f32 v[112:113], v[112:113], v[116:117]
	v_lshlrev_b32_e32 v116, 16, v185
	v_and_b32_e32 v117, 0xffff0000, v185
	v_pk_add_f32 v[114:115], v[114:115], v[116:117]
	v_cvt_pk_bf16_f32 v112, v112, v113
	v_cvt_pk_bf16_f32 v113, v114, v115
	v_lshlrev_b32_e32 v114, 16, v186
	v_and_b32_e32 v115, 0xffff0000, v186
	v_pk_add_f32 v[108:109], v[108:109], v[114:115]
	v_lshl_add_u64 v[124:125], v[124:125], 0, v[202:203]
	v_cvt_pk_bf16_f32 v114, v108, v109
	v_lshlrev_b32_e32 v108, 16, v187
	v_and_b32_e32 v109, 0xffff0000, v187
	v_pk_add_f32 v[108:109], v[110:111], v[108:109]
	s_waitcnt vmcnt(12)
	v_lshlrev_b32_e32 v110, 16, v180
	v_and_b32_e32 v111, 0xffff0000, v180
	v_pk_add_f32 v[104:105], v[104:105], v[110:111]
	v_lshlrev_b32_e32 v110, 16, v181
	v_and_b32_e32 v111, 0xffff0000, v181
	v_pk_add_f32 v[106:107], v[106:107], v[110:111]
	v_cvt_pk_bf16_f32 v104, v104, v105
	v_cvt_pk_bf16_f32 v105, v106, v107
	v_lshlrev_b32_e32 v106, 16, v182
	v_and_b32_e32 v107, 0xffff0000, v182
	v_pk_add_f32 v[96:97], v[96:97], v[106:107]
	v_cvt_pk_bf16_f32 v115, v108, v109
	v_cvt_pk_bf16_f32 v106, v96, v97
	v_lshlrev_b32_e32 v96, 16, v183
	v_and_b32_e32 v97, 0xffff0000, v183
	v_pk_add_f32 v[96:97], v[98:99], v[96:97]
	s_waitcnt vmcnt(11)
	v_lshlrev_b32_e32 v98, 16, v177
	v_cvt_pk_bf16_f32 v107, v96, v97
	v_lshlrev_b32_e32 v96, 16, v176
	v_and_b32_e32 v97, 0xffff0000, v176
	v_and_b32_e32 v99, 0xffff0000, v177
	v_pk_add_f32 v[96:97], v[100:101], v[96:97]
	v_pk_add_f32 v[98:99], v[102:103], v[98:99]
	v_cvt_pk_bf16_f32 v96, v96, v97
	v_cvt_pk_bf16_f32 v97, v98, v99
	v_lshlrev_b32_e32 v98, 16, v178
	v_and_b32_e32 v99, 0xffff0000, v178
	v_pk_add_f32 v[92:93], v[92:93], v[98:99]
	v_lshl_add_u64 v[108:109], s[88:89], 0, v[222:223]
	v_cvt_pk_bf16_f32 v98, v92, v93
	v_lshlrev_b32_e32 v92, 16, v179
	v_and_b32_e32 v93, 0xffff0000, v179
	v_pk_add_f32 v[92:93], v[94:95], v[92:93]
	s_waitcnt vmcnt(10)
	v_lshlrev_b32_e32 v94, 16, v168
	v_and_b32_e32 v95, 0xffff0000, v168
	v_pk_add_f32 v[88:89], v[88:89], v[94:95]
	v_lshlrev_b32_e32 v94, 16, v169
	v_and_b32_e32 v95, 0xffff0000, v169
	v_pk_add_f32 v[90:91], v[90:91], v[94:95]
	v_cvt_pk_bf16_f32 v88, v88, v89
	v_cvt_pk_bf16_f32 v89, v90, v91
	v_lshlrev_b32_e32 v90, 16, v170
	v_and_b32_e32 v91, 0xffff0000, v170
	v_pk_add_f32 v[80:81], v[80:81], v[90:91]
	v_cvt_pk_bf16_f32 v99, v92, v93
	v_cvt_pk_bf16_f32 v90, v80, v81
	v_lshlrev_b32_e32 v80, 16, v171
	v_and_b32_e32 v81, 0xffff0000, v171
	v_pk_add_f32 v[80:81], v[82:83], v[80:81]
	s_waitcnt vmcnt(9)
	v_lshlrev_b32_e32 v82, 16, v173
	v_cvt_pk_bf16_f32 v91, v80, v81
	v_lshlrev_b32_e32 v80, 16, v172
	v_and_b32_e32 v81, 0xffff0000, v172
	v_and_b32_e32 v83, 0xffff0000, v173
	v_pk_add_f32 v[80:81], v[84:85], v[80:81]
	v_pk_add_f32 v[82:83], v[86:87], v[82:83]
	v_cvt_pk_bf16_f32 v80, v80, v81
	v_cvt_pk_bf16_f32 v81, v82, v83
	v_lshlrev_b32_e32 v82, 16, v174
	v_and_b32_e32 v83, 0xffff0000, v174
	v_pk_add_f32 v[76:77], v[76:77], v[82:83]
	v_lshl_add_u64 v[92:93], s[88:89], 0, v[220:221]
	v_cvt_pk_bf16_f32 v82, v76, v77
	v_lshlrev_b32_e32 v76, 16, v175
	v_and_b32_e32 v77, 0xffff0000, v175
	v_pk_add_f32 v[76:77], v[78:79], v[76:77]
	s_waitcnt vmcnt(8)
	v_lshlrev_b32_e32 v78, 16, v164
	v_and_b32_e32 v79, 0xffff0000, v164
	v_pk_add_f32 v[72:73], v[72:73], v[78:79]
	v_lshlrev_b32_e32 v78, 16, v165
	v_and_b32_e32 v79, 0xffff0000, v165
	v_pk_add_f32 v[74:75], v[74:75], v[78:79]
	v_cvt_pk_bf16_f32 v72, v72, v73
	v_cvt_pk_bf16_f32 v73, v74, v75
	v_lshlrev_b32_e32 v74, 16, v166
	v_and_b32_e32 v75, 0xffff0000, v166
	v_pk_add_f32 v[68:69], v[68:69], v[74:75]
	v_cvt_pk_bf16_f32 v83, v76, v77
	v_cvt_pk_bf16_f32 v74, v68, v69
	v_lshlrev_b32_e32 v68, 16, v167
	v_and_b32_e32 v69, 0xffff0000, v167
	v_pk_add_f32 v[68:69], v[70:71], v[68:69]
	v_lshl_add_u64 v[76:77], s[88:89], 0, v[212:213]
	v_cvt_pk_bf16_f32 v75, v68, v69
	s_waitcnt vmcnt(7)
	v_lshlrev_b32_e32 v68, 16, v160
	v_and_b32_e32 v69, 0xffff0000, v160
	v_pk_add_f32 v[64:65], v[64:65], v[68:69]
	v_lshlrev_b32_e32 v68, 16, v161
	v_and_b32_e32 v69, 0xffff0000, v161
	v_pk_add_f32 v[66:67], v[66:67], v[68:69]
	v_cvt_pk_bf16_f32 v64, v64, v65
	v_cvt_pk_bf16_f32 v65, v66, v67
	v_lshlrev_b32_e32 v66, 16, v162
	v_and_b32_e32 v67, 0xffff0000, v162
	v_pk_add_f32 v[60:61], v[60:61], v[66:67]
	v_lshl_add_u64 v[108:109], v[108:109], 0, v[202:203]
	v_cvt_pk_bf16_f32 v66, v60, v61
	v_lshlrev_b32_e32 v60, 16, v163
	v_and_b32_e32 v61, 0xffff0000, v163
	v_pk_add_f32 v[60:61], v[62:63], v[60:61]
	s_waitcnt vmcnt(6)
; __device__ __forceinline__ unsigned cvt_pk_bf16(float lo, float hi) { const f32x2 v = {lo, hi}; const bf16v2_ r = __builtin_convertvector(v, bf16v2_); return __builtin_bit_cast(unsigned, r); }
; __device__ __forceinline__ float bflo(unsigned w) { return __uint_as_float(w << 16); }
; __device__ __forceinline__ float bfhi(unsigned w) { return __uint_as_float(w & 0xffff0000u); }
;     __device__ __forceinline__ void operator()(const f32x4 (&acc)[2][2][4][2], const Unit& u, int wr, int wc, int, int) const {
;     ...
; #pragma unroll
;         for (int ai = 0; ai < 2; ++ai)
; #pragma unroll
;             for (int m = 0; m < 4; ++m)
; #pragma unroll
;                 for (int bj = 0; bj < 2; ++bj) { const u32x4 c = cin[ai][m][bj]; const f32x4 v0 = acc[ai][bj][m][0], v1 = acc[ai][bj][m][1];
;                     u32x4 w; w.x = cvt_pk_bf16(bflo(c.x) + v0[0], bfhi(c.x) + v0[1]); w.y = cvt_pk_bf16(bflo(c.y) + v0[2], bfhi(c.y) + v0[3]);
;                     w.z = cvt_pk_bf16(bflo(c.z) + v1[0], bfhi(c.z) + v1[1]); w.w = cvt_pk_bf16(bflo(c.w) + v1[2], bfhi(c.w) + v1[3]);
;                     *(u32x4*)(C + (size_t)(row0 + ai * HALF + m * 16) * ldc + col0 + bj * HALF) = w; }
; template <class Epi, class Sched>
; __device__ __forceinline__ void gemm_phase(LAS unsigned char* lds, const Gemm g, const Sched& S, const Epi& E) {
;     ...
;         if (!has_next) break;
; #pragma unroll
;         for (int a = 0; a < 2; ++a)
; #pragma unroll
;             for (int b = 0; b < 2; ++b)
; #pragma unroll
;                 for (int m = 0; m < 4; ++m)
; #pragma unroll
;                     for (int n = 0; n < 2; ++n) acc[a][b][m][n] = (f32x4){0.f, 0.f, 0.f, 0.f};
;         cur = nxt; cA = nA; cB = nB; ++ui;
	v_lshlrev_b32_e32 v62, 16, v156
	v_and_b32_e32 v63, 0xffff0000, v156
	v_pk_add_f32 v[56:57], v[56:57], v[62:63]
	v_lshlrev_b32_e32 v62, 16, v157
	v_and_b32_e32 v63, 0xffff0000, v157
	v_pk_add_f32 v[58:59], v[58:59], v[62:63]
	v_cvt_pk_bf16_f32 v56, v56, v57
	v_cvt_pk_bf16_f32 v57, v58, v59
	v_lshlrev_b32_e32 v58, 16, v158
	v_and_b32_e32 v59, 0xffff0000, v158
	v_pk_add_f32 v[48:49], v[48:49], v[58:59]
	v_cvt_pk_bf16_f32 v67, v60, v61
	v_cvt_pk_bf16_f32 v58, v48, v49
	v_lshlrev_b32_e32 v48, 16, v159
	v_and_b32_e32 v49, 0xffff0000, v159
	v_pk_add_f32 v[48:49], v[50:51], v[48:49]
	s_waitcnt vmcnt(5)
	v_lshlrev_b32_e32 v50, 16, v153
	v_cvt_pk_bf16_f32 v59, v48, v49
	v_lshlrev_b32_e32 v48, 16, v152
	v_and_b32_e32 v49, 0xffff0000, v152
	v_and_b32_e32 v51, 0xffff0000, v153
	v_pk_add_f32 v[48:49], v[52:53], v[48:49]
	v_pk_add_f32 v[50:51], v[54:55], v[50:51]
	v_cvt_pk_bf16_f32 v48, v48, v49
	v_cvt_pk_bf16_f32 v49, v50, v51
	v_lshlrev_b32_e32 v50, 16, v154
	v_and_b32_e32 v51, 0xffff0000, v154
	v_pk_add_f32 v[44:45], v[44:45], v[50:51]
	v_lshl_add_u64 v[60:61], s[88:89], 0, v[210:211]
	v_cvt_pk_bf16_f32 v50, v44, v45
	v_lshlrev_b32_e32 v44, 16, v155
	v_and_b32_e32 v45, 0xffff0000, v155
	v_pk_add_f32 v[44:45], v[46:47], v[44:45]
	s_waitcnt vmcnt(4)
	v_lshlrev_b32_e32 v46, 16, v148
	v_and_b32_e32 v47, 0xffff0000, v148
	v_pk_add_f32 v[40:41], v[40:41], v[46:47]
	v_lshlrev_b32_e32 v46, 16, v149
	v_and_b32_e32 v47, 0xffff0000, v149
	v_pk_add_f32 v[42:43], v[42:43], v[46:47]
	v_cvt_pk_bf16_f32 v40, v40, v41
	v_cvt_pk_bf16_f32 v41, v42, v43
	v_lshlrev_b32_e32 v42, 16, v150
	v_and_b32_e32 v43, 0xffff0000, v150
	v_pk_add_f32 v[32:33], v[32:33], v[42:43]
	v_cvt_pk_bf16_f32 v51, v44, v45
	v_cvt_pk_bf16_f32 v42, v32, v33
	v_lshlrev_b32_e32 v32, 16, v151
	v_and_b32_e32 v33, 0xffff0000, v151
	v_pk_add_f32 v[32:33], v[34:35], v[32:33]
	s_waitcnt vmcnt(3)
	v_lshlrev_b32_e32 v34, 16, v145
	v_cvt_pk_bf16_f32 v43, v32, v33
	v_lshlrev_b32_e32 v32, 16, v144
	v_and_b32_e32 v33, 0xffff0000, v144
	v_and_b32_e32 v35, 0xffff0000, v145
	v_pk_add_f32 v[32:33], v[36:37], v[32:33]
	v_pk_add_f32 v[34:35], v[38:39], v[34:35]
	v_cvt_pk_bf16_f32 v32, v32, v33
	v_cvt_pk_bf16_f32 v33, v34, v35
	v_lshlrev_b32_e32 v34, 16, v146
	v_and_b32_e32 v35, 0xffff0000, v146
	v_pk_add_f32 v[28:29], v[28:29], v[34:35]
	v_lshl_add_u64 v[44:45], s[88:89], 0, v[208:209]
	v_cvt_pk_bf16_f32 v34, v28, v29
	v_lshlrev_b32_e32 v28, 16, v147
	v_and_b32_e32 v29, 0xffff0000, v147
	v_pk_add_f32 v[28:29], v[30:31], v[28:29]
	s_waitcnt vmcnt(2)
	v_lshlrev_b32_e32 v30, 16, v140
	v_and_b32_e32 v31, 0xffff0000, v140
	v_pk_add_f32 v[24:25], v[24:25], v[30:31]
	v_lshlrev_b32_e32 v30, 16, v141
	v_and_b32_e32 v31, 0xffff0000, v141
	v_pk_add_f32 v[26:27], v[26:27], v[30:31]
	v_cvt_pk_bf16_f32 v24, v24, v25
	v_cvt_pk_bf16_f32 v25, v26, v27
	v_lshlrev_b32_e32 v26, 16, v142
	v_and_b32_e32 v27, 0xffff0000, v142
	v_pk_add_f32 v[16:17], v[16:17], v[26:27]
	v_cvt_pk_bf16_f32 v35, v28, v29
	v_cvt_pk_bf16_f32 v26, v16, v17
	v_lshlrev_b32_e32 v16, 16, v143
	v_and_b32_e32 v17, 0xffff0000, v143
	v_pk_add_f32 v[16:17], v[18:19], v[16:17]
	s_waitcnt vmcnt(1)
	v_lshlrev_b32_e32 v18, 16, v137
	v_cvt_pk_bf16_f32 v27, v16, v17
	v_lshlrev_b32_e32 v16, 16, v136
	v_and_b32_e32 v17, 0xffff0000, v136
	v_and_b32_e32 v19, 0xffff0000, v137
	v_pk_add_f32 v[16:17], v[20:21], v[16:17]
	v_pk_add_f32 v[18:19], v[22:23], v[18:19]
	v_cvt_pk_bf16_f32 v16, v16, v17
	v_cvt_pk_bf16_f32 v17, v18, v19
	v_lshlrev_b32_e32 v18, 16, v138
	v_and_b32_e32 v19, 0xffff0000, v138
	v_pk_add_f32 v[12:13], v[12:13], v[18:19]
	v_lshl_add_u64 v[28:29], s[88:89], 0, v[206:207]
	v_cvt_pk_bf16_f32 v18, v12, v13
	v_lshlrev_b32_e32 v12, 16, v139
	v_and_b32_e32 v13, 0xffff0000, v139
	v_pk_add_f32 v[12:13], v[14:15], v[12:13]
	s_waitcnt vmcnt(0)
	v_lshlrev_b32_e32 v14, 16, v132
	v_and_b32_e32 v15, 0xffff0000, v132
	v_pk_add_f32 v[8:9], v[8:9], v[14:15]
	v_lshlrev_b32_e32 v14, 16, v133
	v_and_b32_e32 v15, 0xffff0000, v133
	v_pk_add_f32 v[10:11], v[10:11], v[14:15]
	v_cvt_pk_bf16_f32 v8, v8, v9
	v_cvt_pk_bf16_f32 v9, v10, v11
	v_lshlrev_b32_e32 v10, 16, v134
	v_and_b32_e32 v11, 0xffff0000, v134
	v_pk_add_f32 v[4:5], v[4:5], v[10:11]
	v_cvt_pk_bf16_f32 v19, v12, v13
	v_cvt_pk_bf16_f32 v10, v4, v5
	v_lshlrev_b32_e32 v4, 16, v135
	v_and_b32_e32 v5, 0xffff0000, v135
	v_lshl_add_u64 v[12:13], s[88:89], 0, v[204:205]
	v_pk_add_f32 v[4:5], v[6:7], v[4:5]
	v_lshl_add_u64 v[92:93], v[92:93], 0, v[202:203]
	v_lshl_add_u64 v[76:77], v[76:77], 0, v[202:203]
	v_lshl_add_u64 v[60:61], v[60:61], 0, v[202:203]
	v_lshl_add_u64 v[44:45], v[44:45], 0, v[202:203]
	v_lshl_add_u64 v[28:29], v[28:29], 0, v[202:203]
	v_lshl_add_u64 v[12:13], v[12:13], 0, v[202:203]
	v_cvt_pk_bf16_f32 v11, v4, v5
	global_store_dwordx4 v[124:125], v[128:131], off
	global_store_dwordx4 v[124:125], v[120:123], off offset:256
	global_store_dwordx4 v[108:109], v[112:115], off
	global_store_dwordx4 v[108:109], v[104:107], off offset:256
	global_store_dwordx4 v[92:93], v[96:99], off
	global_store_dwordx4 v[92:93], v[88:91], off offset:256
	global_store_dwordx4 v[76:77], v[80:83], off
	global_store_dwordx4 v[76:77], v[72:75], off offset:256
	global_store_dwordx4 v[60:61], v[64:67], off
	global_store_dwordx4 v[60:61], v[56:59], off offset:256
	global_store_dwordx4 v[44:45], v[48:51], off
	global_store_dwordx4 v[44:45], v[40:43], off offset:256
	global_store_dwordx4 v[28:29], v[32:35], off
	global_store_dwordx4 v[28:29], v[24:27], off offset:256
	global_store_dwordx4 v[12:13], v[16:19], off
	global_store_dwordx4 v[12:13], v[8:11], off offset:256
	s_cmpk_lt_u32 s2, 0x100
	s_cbranch_scc1 .Lalign_b_966
	s_barrier
.Lalign_b_966:
	s_cbranch_vccz .LBB0_959
	s_waitcnt vmcnt(0)
	s_cmpk_gt_u32 s2, 0xff
	s_cbranch_scc1 .LBB0_970
	s_barrier

; #define PG8_STAGE(bufoff, gbase, voff) do { _Pragma("unroll") for (int _i = 0; _i < 2; ++_i) \
;         __builtin_amdgcn_global_load_lds((const unsigned*)((const char*)(gbase) + (voff)[_i]), (LAS unsigned*)(lds + (bufoff) + ldsw + _i * 8192), 16, 0, 0); } while (0)
; #define PG8_LDA(dst, b, h) do { _Pragma("unroll") for (int m = 0; m < 4; ++m) _Pragma("unroll") for (int k = 0; k < 2; ++k) dst[m][k] = *(const LAS bf16x8*)(lds + PG8_SA(b, h) + aoff + m * 2048 + k * 1024); } while (0)
; #define PG8_LDB(dst, b, h) do { _Pragma("unroll") for (int n = 0; n < 2; ++n) _Pragma("unroll") for (int k = 0; k < 2; ++k) dst[n][k] = *(const LAS bf16x8*)(lds + PG8_SB(b, h) + boff + n * 2048 + k * 1024); } while (0)
; #define PG8_MMA(ai, bj, At, Bt) do { __builtin_amdgcn_s_setprio(1); _Pragma("unroll") for (int m = 0; m < 4; ++m) _Pragma("unroll") for (int n = 0; n < 2; ++n) _Pragma("unroll") for (int k = 0; k < 2; ++k) \
;         acc[ai][bj][m][n] = __builtin_amdgcn_mfma_f32_16x16x32_bf16(Bt[n][k], At[m][k], acc[ai][bj][m][n], 0, 0, 0); __builtin_amdgcn_s_setprio(0); } while (0)
; #define PG8_WAIT_V(n) asm volatile("s_waitcnt vmcnt(" #n ")" ::: "memory")
; #define PG8_WAIT_L(n) asm volatile("s_waitcnt lgkmcnt(" #n ")" ::: "memory")
; #define PG8_BAR __builtin_amdgcn_s_barrier()
; #define PG8_SCHED __builtin_amdgcn_sched_barrier(0)
; template <class Epi, class Sched>
; __device__ __forceinline__ void gemm_phase(LAS unsigned char* lds, const Gemm g, const Sched& S, const Epi& E) {
;     ...
;             PG8_LDB(B0, 0, 0); PG8_SCHED; PG8_LDA(At, 0, 0); PG8_STAGE(PG8_SA(1, 1), a1 + hstepA, voffA);
;             PG8_WAIT_L(8); PG8_BAR; PG8_WAIT_L(0); PG8_MMA(0, 0, At, B0); PG8_BAR; PG8_SCHED;
;             PG8_LDB(B1, 0, 1); PG8_STAGE(PG8_SB(0, 0), b2, voffB);
;             PG8_BAR; PG8_WAIT_L(0); PG8_MMA(0, 1, At, B1); PG8_BAR;
;             PG8_LDA(At, 0, 1); PG8_STAGE(PG8_SA(0, 0), a2, voffA);
;             PG8_BAR; PG8_WAIT_L(0); PG8_MMA(1, 0, At, B0); PG8_BAR; PG8_SCHED;
;             PG8_STAGE(PG8_SB(0, 1), b2 + hstepB, voffB);
;             PG8_WAIT_V(6); PG8_BAR; PG8_MMA(1, 1, At, B1); PG8_BAR;
.LBB0_1094:
	s_setprio 0
	s_add_u32 s20, s18, 0xfff80080
	s_addc_u32 s21, s19, -1
	s_add_i32 s54, 0, 0x10000
	v_add_u32_e32 v146, s54, v1
	ds_read_b128 v[142:145], v146
	ds_read_b128 v[150:153], v146 offset:1024
	ds_read_b128 v[154:157], v146 offset:2048
	ds_read_b128 v[158:161], v146 offset:3072
	s_cmp_eq_u32 s53, 28
	s_cselect_b32 s25, s5, s21
	s_cselect_b32 s24, s49, s20
	s_cselect_b32 s21, s1, s52
	s_cselect_b32 s20, s50, s51
	ds_read_b128 v[162:165], v148
	ds_read_b128 v[166:169], v148 offset:1024
	ds_read_b128 v[170:173], v148 offset:2048
	ds_read_b128 v[174:177], v148 offset:3072
	ds_read_b128 v[178:181], v148 offset:4096
	ds_read_b128 v[182:185], v148 offset:5120
	ds_read_b128 v[186:189], v148 offset:6144
	ds_read_b128 v[190:193], v148 offset:7168
	s_add_i32 s56, 0, 0x14000
	v_add_u32_e32 v146, s56, v1
	ds_read_b128 v[194:197], v146
	ds_read_b128 v[198:201], v146 offset:1024
	ds_read_b128 v[202:205], v146 offset:2048
	ds_read_b128 v[206:209], v146 offset:3072
	s_add_i32 m0, s31, 0xc000
	s_nop 0
	global_load_lds_dwordx4 v138, s[18:19]
	s_add_i32 m0, s31, 0xe000
	s_nop 0
	global_load_lds_dwordx4 v140, s[18:19]
	s_waitcnt lgkmcnt(0)
	s_setprio 1
	s_barrier
	v_mfma_f32_16x16x32_bf16 v[128:131], v[142:145], v[162:165], v[128:131]
	v_mfma_f32_16x16x32_bf16 v[124:127], v[154:157], v[162:165], v[124:127]
	v_mfma_f32_16x16x32_bf16 v[120:123], v[142:145], v[170:173], v[120:123]
	v_mfma_f32_16x16x32_bf16 v[112:115], v[154:157], v[170:173], v[112:115]
	v_mfma_f32_16x16x32_bf16 v[104:107], v[142:145], v[178:181], v[104:107]
	v_mfma_f32_16x16x32_bf16 v[96:99], v[154:157], v[178:181], v[96:99]
	v_mfma_f32_16x16x32_bf16 v[88:91], v[142:145], v[186:189], v[88:91]
	v_mfma_f32_16x16x32_bf16 v[80:83], v[154:157], v[186:189], v[80:83]
	v_mfma_f32_16x16x32_bf16 v[128:131], v[150:153], v[166:169], v[128:131]
	v_mfma_f32_16x16x32_bf16 v[124:127], v[158:161], v[166:169], v[124:127]
	v_mfma_f32_16x16x32_bf16 v[120:123], v[150:153], v[174:177], v[120:123]
	v_mfma_f32_16x16x32_bf16 v[112:115], v[158:161], v[174:177], v[112:115]
	v_mfma_f32_16x16x32_bf16 v[104:107], v[150:153], v[182:185], v[104:107]
	v_mfma_f32_16x16x32_bf16 v[96:99], v[158:161], v[182:185], v[96:99]
	v_mfma_f32_16x16x32_bf16 v[88:91], v[150:153], v[190:193], v[88:91]
	v_mfma_f32_16x16x32_bf16 v[80:83], v[158:161], v[190:193], v[80:83]
	v_mfma_f32_16x16x32_bf16 v[116:119], v[194:197], v[162:165], v[116:119]
	v_mfma_f32_16x16x32_bf16 v[108:111], v[202:205], v[162:165], v[108:111]
	v_mfma_f32_16x16x32_bf16 v[100:103], v[194:197], v[170:173], v[100:103]
	v_mfma_f32_16x16x32_bf16 v[92:95], v[202:205], v[170:173], v[92:95]
	v_mfma_f32_16x16x32_bf16 v[84:87], v[194:197], v[178:181], v[84:87]
	v_mfma_f32_16x16x32_bf16 v[76:79], v[202:205], v[178:181], v[76:79]
	v_mfma_f32_16x16x32_bf16 v[72:75], v[194:197], v[186:189], v[72:75]
	v_mfma_f32_16x16x32_bf16 v[68:71], v[202:205], v[186:189], v[68:71]
	v_mfma_f32_16x16x32_bf16 v[116:119], v[198:201], v[166:169], v[116:119]
	v_mfma_f32_16x16x32_bf16 v[108:111], v[206:209], v[166:169], v[108:111]
	v_mfma_f32_16x16x32_bf16 v[100:103], v[198:201], v[174:177], v[100:103]
	v_mfma_f32_16x16x32_bf16 v[92:95], v[206:209], v[174:177], v[92:95]
	v_mfma_f32_16x16x32_bf16 v[84:87], v[198:201], v[182:185], v[84:87]
	v_mfma_f32_16x16x32_bf16 v[76:79], v[206:209], v[182:185], v[76:79]
	v_mfma_f32_16x16x32_bf16 v[72:75], v[198:201], v[190:193], v[72:75]
	v_mfma_f32_16x16x32_bf16 v[68:71], v[206:209], v[190:193], v[68:71]
	s_barrier
	s_setprio 0
	ds_read_b128 v[162:165], v148 offset:16384
	ds_read_b128 v[166:169], v148 offset:17408
	ds_read_b128 v[170:173], v148 offset:18432
	ds_read_b128 v[174:177], v148 offset:19456
	ds_read_b128 v[178:181], v148 offset:20480
	ds_read_b128 v[182:185], v148 offset:21504
	ds_read_b128 v[186:189], v148 offset:22528
	ds_read_b128 v[190:193], v148 offset:23552
	s_add_i32 s54, s54, s30
	v_lshl_add_u64 v[146:147], s[20:21], 0, v[2:3]
	s_mov_b32 m0, s54
	v_lshl_add_u64 v[210:211], s[20:21], 0, v[132:133]
	global_load_lds_dwordx4 v[146:147], off
	s_add_i32 m0, s54, 0x2000
	s_nop 0
	global_load_lds_dwordx4 v[210:211], off
	s_mov_b32 m0, s31
	v_lshl_add_u64 v[212:213], s[24:25], 0, v[136:137]
	global_load_lds_dwordx4 v[212:213], off
	v_lshl_add_u64 v[216:217], s[24:25], 0, v[134:135]
	s_mov_b32 m0, s35
	s_nop 0
	global_load_lds_dwordx4 v[216:217], off
	s_add_u32 s54, s20, 0x80000
	s_addc_u32 s55, s21, 0
	s_add_i32 s56, s56, s30
	s_mov_b32 m0, s56
	s_nop 0
	global_load_lds_dwordx4 v2, s[54:55]
	s_add_i32 m0, s56, 0x2000
	s_nop 0
	global_load_lds_dwordx4 v132, s[54:55]
	s_waitcnt lgkmcnt(0)
	s_waitcnt vmcnt(6)
	s_setprio 1
	s_barrier
; #define PG8_STAGE(bufoff, gbase, voff) do { _Pragma("unroll") for (int _i = 0; _i < 2; ++_i) \
;         __builtin_amdgcn_global_load_lds((const unsigned*)((const char*)(gbase) + (voff)[_i]), (LAS unsigned*)(lds + (bufoff) + ldsw + _i * 8192), 16, 0, 0); } while (0)
; #define PG8_LDA(dst, b, h) do { _Pragma("unroll") for (int m = 0; m < 4; ++m) _Pragma("unroll") for (int k = 0; k < 2; ++k) dst[m][k] = *(const LAS bf16x8*)(lds + PG8_SA(b, h) + aoff + m * 2048 + k * 1024); } while (0)
; #define PG8_LDB(dst, b, h) do { _Pragma("unroll") for (int n = 0; n < 2; ++n) _Pragma("unroll") for (int k = 0; k < 2; ++k) dst[n][k] = *(const LAS bf16x8*)(lds + PG8_SB(b, h) + boff + n * 2048 + k * 1024); } while (0)
; #define PG8_MMA(ai, bj, At, Bt) do { __builtin_amdgcn_s_setprio(1); _Pragma("unroll") for (int m = 0; m < 4; ++m) _Pragma("unroll") for (int n = 0; n < 2; ++n) _Pragma("unroll") for (int k = 0; k < 2; ++k) \
;         acc[ai][bj][m][n] = __builtin_amdgcn_mfma_f32_16x16x32_bf16(Bt[n][k], At[m][k], acc[ai][bj][m][n], 0, 0, 0); __builtin_amdgcn_s_setprio(0); } while (0)
; #define PG8_WAIT_V(n) asm volatile("s_waitcnt vmcnt(" #n ")" ::: "memory")
; #define PG8_WAIT_L(n) asm volatile("s_waitcnt lgkmcnt(" #n ")" ::: "memory")
; #define PG8_BAR __builtin_amdgcn_s_barrier()
; #define PG8_SCHED __builtin_amdgcn_sched_barrier(0)
; template <class Epi, class Sched>
; __device__ __forceinline__ void gemm_phase(LAS unsigned char* lds, const Gemm g, const Sched& S, const Epi& E) {
;     ...
;             PG8_BAR; PG8_WAIT_L(0); PG8_MMA(1, 0, At, B0); PG8_BAR; PG8_SCHED;
;             PG8_STAGE(PG8_SB(0, 1), b2 + hstepB, voffB);
;             PG8_WAIT_V(6); PG8_BAR; PG8_MMA(1, 1, At, B1); PG8_BAR;
;             PG8_LDB(B0, 1, 0); PG8_SCHED; PG8_LDA(At, 1, 0); PG8_STAGE(PG8_SA(0, 1), a2 + hstepA, voffA);
;             PG8_WAIT_L(8); PG8_BAR; PG8_WAIT_L(0); PG8_MMA(0, 0, At, B0); PG8_BAR; PG8_SCHED;
;             PG8_LDB(B1, 1, 1); PG8_STAGE(PG8_SB(1, 0), b3, voffB);
;             PG8_BAR; PG8_WAIT_L(0); PG8_MMA(0, 1, At, B1); PG8_BAR;
;             PG8_LDA(At, 1, 1); PG8_STAGE(PG8_SA(1, 0), a3, voffA);
;             PG8_BAR; PG8_WAIT_L(0); PG8_MMA(1, 0, At, B0); PG8_BAR; PG8_SCHED;
	v_mfma_f32_16x16x32_bf16 v[64:67], v[142:145], v[162:165], v[64:67]
	v_mfma_f32_16x16x32_bf16 v[60:63], v[154:157], v[162:165], v[60:63]
	v_mfma_f32_16x16x32_bf16 v[56:59], v[142:145], v[170:173], v[56:59]
	v_mfma_f32_16x16x32_bf16 v[48:51], v[154:157], v[170:173], v[48:51]
	v_mfma_f32_16x16x32_bf16 v[40:43], v[142:145], v[178:181], v[40:43]
	v_mfma_f32_16x16x32_bf16 v[32:35], v[154:157], v[178:181], v[32:35]
	v_mfma_f32_16x16x32_bf16 v[24:27], v[142:145], v[186:189], v[24:27]
	v_mfma_f32_16x16x32_bf16 v[16:19], v[154:157], v[186:189], v[16:19]
	v_mfma_f32_16x16x32_bf16 v[64:67], v[150:153], v[166:169], v[64:67]
	v_mfma_f32_16x16x32_bf16 v[60:63], v[158:161], v[166:169], v[60:63]
	v_mfma_f32_16x16x32_bf16 v[56:59], v[150:153], v[174:177], v[56:59]
	v_mfma_f32_16x16x32_bf16 v[48:51], v[158:161], v[174:177], v[48:51]
	v_mfma_f32_16x16x32_bf16 v[40:43], v[150:153], v[182:185], v[40:43]
	v_mfma_f32_16x16x32_bf16 v[32:35], v[158:161], v[182:185], v[32:35]
	v_mfma_f32_16x16x32_bf16 v[24:27], v[150:153], v[190:193], v[24:27]
	v_mfma_f32_16x16x32_bf16 v[16:19], v[158:161], v[190:193], v[16:19]
	v_mfma_f32_16x16x32_bf16 v[52:55], v[194:197], v[162:165], v[52:55]
	v_mfma_f32_16x16x32_bf16 v[44:47], v[202:205], v[162:165], v[44:47]
	v_mfma_f32_16x16x32_bf16 v[36:39], v[194:197], v[170:173], v[36:39]
	v_mfma_f32_16x16x32_bf16 v[28:31], v[202:205], v[170:173], v[28:31]
	v_mfma_f32_16x16x32_bf16 v[20:23], v[194:197], v[178:181], v[20:23]
	v_mfma_f32_16x16x32_bf16 v[12:15], v[202:205], v[178:181], v[12:15]
	v_mfma_f32_16x16x32_bf16 v[8:11], v[194:197], v[186:189], v[8:11]
	v_mfma_f32_16x16x32_bf16 v[4:7], v[202:205], v[186:189], v[4:7]
	v_mfma_f32_16x16x32_bf16 v[52:55], v[198:201], v[166:169], v[52:55]
	v_mfma_f32_16x16x32_bf16 v[44:47], v[206:209], v[166:169], v[44:47]
	v_mfma_f32_16x16x32_bf16 v[36:39], v[198:201], v[174:177], v[36:39]
	v_mfma_f32_16x16x32_bf16 v[28:31], v[206:209], v[174:177], v[28:31]
	v_mfma_f32_16x16x32_bf16 v[20:23], v[198:201], v[182:185], v[20:23]
	v_mfma_f32_16x16x32_bf16 v[12:15], v[206:209], v[182:185], v[12:15]
	v_mfma_f32_16x16x32_bf16 v[8:11], v[198:201], v[190:193], v[8:11]
	v_mfma_f32_16x16x32_bf16 v[4:7], v[206:209], v[190:193], v[4:7]
	s_barrier
	s_setprio 0
	s_add_i32 s54, 0, 0x18000
	v_add_u32_e32 v149, s54, v1
	ds_read_b128 v[142:145], v149
	ds_read_b128 v[150:153], v149 offset:1024
	ds_read_b128 v[154:157], v149 offset:2048
	ds_read_b128 v[158:161], v149 offset:3072
	s_add_u32 s24, s24, 0x80000
	s_addc_u32 s25, s25, 0
	ds_read_b128 v[162:165], v148 offset:32768
	ds_read_b128 v[166:169], v148 offset:33792
	ds_read_b128 v[170:173], v148 offset:34816
	ds_read_b128 v[174:177], v148 offset:35840
	ds_read_b128 v[178:181], v148 offset:36864
	ds_read_b128 v[182:185], v148 offset:37888
	ds_read_b128 v[186:189], v148 offset:38912
	ds_read_b128 v[190:193], v148 offset:39936
	s_mov_b32 m0, s36
	s_nop 0
	global_load_lds_dwordx4 v136, s[24:25]
	s_mov_b32 m0, s37
	s_nop 0
	global_load_lds_dwordx4 v134, s[24:25]
	s_add_i32 s24, 0, 0x1c000
	v_add_u32_e32 v149, s24, v1
	ds_read_b128 v[194:197], v149
	ds_read_b128 v[198:201], v149 offset:1024
	ds_read_b128 v[202:205], v149 offset:2048
	ds_read_b128 v[206:209], v149 offset:3072
	s_waitcnt lgkmcnt(0)
	s_setprio 1
	s_barrier
	v_mfma_f32_16x16x32_bf16 v[128:131], v[142:145], v[162:165], v[128:131]
	v_mfma_f32_16x16x32_bf16 v[124:127], v[154:157], v[162:165], v[124:127]
	v_mfma_f32_16x16x32_bf16 v[120:123], v[142:145], v[170:173], v[120:123]
	v_mfma_f32_16x16x32_bf16 v[112:115], v[154:157], v[170:173], v[112:115]
	v_mfma_f32_16x16x32_bf16 v[104:107], v[142:145], v[178:181], v[104:107]
	v_mfma_f32_16x16x32_bf16 v[96:99], v[154:157], v[178:181], v[96:99]
	v_mfma_f32_16x16x32_bf16 v[88:91], v[142:145], v[186:189], v[88:91]
	v_mfma_f32_16x16x32_bf16 v[80:83], v[154:157], v[186:189], v[80:83]
	v_mfma_f32_16x16x32_bf16 v[128:131], v[150:153], v[166:169], v[128:131]
	v_mfma_f32_16x16x32_bf16 v[124:127], v[158:161], v[166:169], v[124:127]
	v_mfma_f32_16x16x32_bf16 v[120:123], v[150:153], v[174:177], v[120:123]
	v_mfma_f32_16x16x32_bf16 v[112:115], v[158:161], v[174:177], v[112:115]
	v_mfma_f32_16x16x32_bf16 v[104:107], v[150:153], v[182:185], v[104:107]
	v_mfma_f32_16x16x32_bf16 v[96:99], v[158:161], v[182:185], v[96:99]
	v_mfma_f32_16x16x32_bf16 v[88:91], v[150:153], v[190:193], v[88:91]
	v_mfma_f32_16x16x32_bf16 v[80:83], v[158:161], v[190:193], v[80:83]
	v_mfma_f32_16x16x32_bf16 v[116:119], v[194:197], v[162:165], v[116:119]
	v_mfma_f32_16x16x32_bf16 v[108:111], v[202:205], v[162:165], v[108:111]
	v_mfma_f32_16x16x32_bf16 v[100:103], v[194:197], v[170:173], v[100:103]
	v_mfma_f32_16x16x32_bf16 v[92:95], v[202:205], v[170:173], v[92:95]
	v_mfma_f32_16x16x32_bf16 v[84:87], v[194:197], v[178:181], v[84:87]
	v_mfma_f32_16x16x32_bf16 v[76:79], v[202:205], v[178:181], v[76:79]
	v_mfma_f32_16x16x32_bf16 v[72:75], v[194:197], v[186:189], v[72:75]
	v_mfma_f32_16x16x32_bf16 v[68:71], v[202:205], v[186:189], v[68:71]
	v_mfma_f32_16x16x32_bf16 v[116:119], v[198:201], v[166:169], v[116:119]
	v_mfma_f32_16x16x32_bf16 v[108:111], v[206:209], v[166:169], v[108:111]
	v_mfma_f32_16x16x32_bf16 v[100:103], v[198:201], v[174:177], v[100:103]
	v_mfma_f32_16x16x32_bf16 v[92:95], v[206:209], v[174:177], v[92:95]
	v_mfma_f32_16x16x32_bf16 v[84:87], v[198:201], v[182:185], v[84:87]
	v_mfma_f32_16x16x32_bf16 v[76:79], v[206:209], v[182:185], v[76:79]
	v_mfma_f32_16x16x32_bf16 v[72:75], v[198:201], v[190:193], v[72:75]
	v_mfma_f32_16x16x32_bf16 v[68:71], v[206:209], v[190:193], v[68:71]
	s_barrier
; __device__ __forceinline__ int opaque_tid() { int t = threadIdx.x; asm volatile("" : "+v"(t)); return t; }
; #define PG8_STAGE(bufoff, gbase, voff) do { _Pragma("unroll") for (int _i = 0; _i < 2; ++_i) \
;         __builtin_amdgcn_global_load_lds((const unsigned*)((const char*)(gbase) + (voff)[_i]), (LAS unsigned*)(lds + (bufoff) + ldsw + _i * 8192), 16, 0, 0); } while (0)
; #define PG8_MMA(ai, bj, At, Bt) do { __builtin_amdgcn_s_setprio(1); _Pragma("unroll") for (int m = 0; m < 4; ++m) _Pragma("unroll") for (int n = 0; n < 2; ++n) _Pragma("unroll") for (int k = 0; k < 2; ++k) \
;         acc[ai][bj][m][n] = __builtin_amdgcn_mfma_f32_16x16x32_bf16(Bt[n][k], At[m][k], acc[ai][bj][m][n], 0, 0, 0); __builtin_amdgcn_s_setprio(0); } while (0)
; #define PG8_WAIT_V(n) asm volatile("s_waitcnt vmcnt(" #n ")" ::: "memory")
; #define PG8_WAIT_L(n) asm volatile("s_waitcnt lgkmcnt(" #n ")" ::: "memory")
; #define PG8_BAR __builtin_amdgcn_s_barrier()
; #define PG8_SCHED __builtin_amdgcn_sched_barrier(0)
;     __device__ __forceinline__ void operator()(const f32x4 (&acc)[2][2][4][2], const Unit& u, int wr, int wc, int ui, int) const {
;         const int ol_ = opaque_tid() & 63, fr = ol_ & 15, fq = ol_ >> 4;
;         const int row0 = u.pm * BM + wr * 64 + fr, col0 = u.pn * BM + wc * 32 + 8 * fq;
;         float r_[2][4];
;         if (rs) rs_read(r_, ui, wr, fr);
; template <class Epi, class Sched>
; __device__ __forceinline__ void gemm_phase(LAS unsigned char* lds, const Gemm g, const Sched& S, const Epi& E) {
;     ...
;             PG8_BAR; PG8_WAIT_L(0); PG8_MMA(1, 0, At, B0); PG8_BAR; PG8_SCHED;
;             PG8_STAGE(PG8_SB(1, 1), b3 + hstepB, voffB);
;             PG8_WAIT_V(6); PG8_BAR; PG8_MMA(1, 1, At, B1); PG8_BAR;
	s_setprio 0
	ds_read_b128 v[162:165], v148 offset:49152
	ds_read_b128 v[166:169], v148 offset:50176
	ds_read_b128 v[170:173], v148 offset:51200
	ds_read_b128 v[174:177], v148 offset:52224
	ds_read_b128 v[178:181], v148 offset:53248
	ds_read_b128 v[182:185], v148 offset:54272
	ds_read_b128 v[186:189], v148 offset:55296
	ds_read_b128 v[190:193], v148 offset:56320
	s_add_i32 s25, s54, s30
	v_lshl_add_u64 v[146:147], v[146:147], 0, s[8:9]
	s_mov_b32 m0, s25
	s_nop 0
	global_load_lds_dwordx4 v[146:147], off
	v_lshl_add_u64 v[146:147], v[210:211], 0, s[8:9]
	s_add_i32 m0, s25, 0x2000
	s_nop 0
	global_load_lds_dwordx4 v[146:147], off
	s_mov_b32 m0, s42
	v_lshl_add_u64 v[146:147], v[212:213], 0, s[8:9]
	global_load_lds_dwordx4 v[146:147], off
	v_lshl_add_u64 v[146:147], v[216:217], 0, s[8:9]
	s_mov_b32 m0, s43
	s_nop 0
	global_load_lds_dwordx4 v[146:147], off
	s_add_u32 s20, s20, 0x80080
	s_addc_u32 s21, s21, 0
	s_add_i32 s24, s24, s30
	s_mov_b32 m0, s24
	s_nop 0
	global_load_lds_dwordx4 v2, s[20:21]
	s_add_i32 m0, s24, 0x2000
	s_nop 0
	global_load_lds_dwordx4 v132, s[20:21]
	s_add_i32 s53, s53, 2
	s_add_u32 s18, s18, 0x100
	s_addc_u32 s19, s19, 0
	s_add_u32 s51, s51, 0x100
	s_addc_u32 s52, s52, 0
	s_cmp_gt_u32 s53, 29
	s_waitcnt lgkmcnt(0)
	s_waitcnt vmcnt(6)
	s_setprio 1
	s_barrier
	v_mfma_f32_16x16x32_bf16 v[64:67], v[142:145], v[162:165], v[64:67]
	v_mfma_f32_16x16x32_bf16 v[60:63], v[154:157], v[162:165], v[60:63]
	v_mfma_f32_16x16x32_bf16 v[56:59], v[142:145], v[170:173], v[56:59]
	v_mfma_f32_16x16x32_bf16 v[48:51], v[154:157], v[170:173], v[48:51]
	v_mfma_f32_16x16x32_bf16 v[40:43], v[142:145], v[178:181], v[40:43]
	v_mfma_f32_16x16x32_bf16 v[32:35], v[154:157], v[178:181], v[32:35]
	v_mfma_f32_16x16x32_bf16 v[24:27], v[142:145], v[186:189], v[24:27]
	v_mfma_f32_16x16x32_bf16 v[16:19], v[154:157], v[186:189], v[16:19]
	v_mfma_f32_16x16x32_bf16 v[64:67], v[150:153], v[166:169], v[64:67]
	v_mfma_f32_16x16x32_bf16 v[60:63], v[158:161], v[166:169], v[60:63]
	v_mfma_f32_16x16x32_bf16 v[56:59], v[150:153], v[174:177], v[56:59]
	v_mfma_f32_16x16x32_bf16 v[48:51], v[158:161], v[174:177], v[48:51]
	v_mfma_f32_16x16x32_bf16 v[40:43], v[150:153], v[182:185], v[40:43]
	v_mfma_f32_16x16x32_bf16 v[32:35], v[158:161], v[182:185], v[32:35]
	v_mfma_f32_16x16x32_bf16 v[24:27], v[150:153], v[190:193], v[24:27]
	v_mfma_f32_16x16x32_bf16 v[16:19], v[158:161], v[190:193], v[16:19]
	v_mfma_f32_16x16x32_bf16 v[52:55], v[194:197], v[162:165], v[52:55]
	v_mfma_f32_16x16x32_bf16 v[44:47], v[202:205], v[162:165], v[44:47]
	v_mfma_f32_16x16x32_bf16 v[36:39], v[194:197], v[170:173], v[36:39]
	v_mfma_f32_16x16x32_bf16 v[28:31], v[202:205], v[170:173], v[28:31]
	v_mfma_f32_16x16x32_bf16 v[20:23], v[194:197], v[178:181], v[20:23]
	v_mfma_f32_16x16x32_bf16 v[12:15], v[202:205], v[178:181], v[12:15]
	v_mfma_f32_16x16x32_bf16 v[8:11], v[194:197], v[186:189], v[8:11]
	v_mfma_f32_16x16x32_bf16 v[4:7], v[202:205], v[186:189], v[4:7]
	v_mfma_f32_16x16x32_bf16 v[52:55], v[198:201], v[166:169], v[52:55]
	v_mfma_f32_16x16x32_bf16 v[44:47], v[206:209], v[166:169], v[44:47]
	v_mfma_f32_16x16x32_bf16 v[36:39], v[198:201], v[174:177], v[36:39]
	v_mfma_f32_16x16x32_bf16 v[28:31], v[206:209], v[174:177], v[28:31]
	v_mfma_f32_16x16x32_bf16 v[20:23], v[198:201], v[182:185], v[20:23]
	v_mfma_f32_16x16x32_bf16 v[12:15], v[206:209], v[182:185], v[12:15]
	v_mfma_f32_16x16x32_bf16 v[8:11], v[198:201], v[190:193], v[8:11]
	v_mfma_f32_16x16x32_bf16 v[4:7], v[206:209], v[190:193], v[4:7]
	s_barrier
	s_cbranch_scc0 .LBB0_1094
	s_setprio 0
	s_cmpk_gt_u32 s2, 0xff
	s_cbranch_scc1 .Lalign_a_1094
	s_barrier
.Lalign_a_1094:
	s_lshl_b32 s1, s48, 10
	v_mov_b32_e32 v144, v0
	s_and_b32 s1, s1, 0x400
	s_add_i32 s1, s44, s1
	v_and_b32_e32 v145, 15, v144
	v_lshl_add_u32 v142, v145, 2, s1
	s_lshl_b32 s1, s47, 8
	v_lshrrev_b32_e32 v144, 1, v144
	v_and_or_b32 v144, v144, 24, s1
	ds_read2_b32 v[150:151], v142 offset1:16
	ds_read2_b32 v[152:153], v142 offset0:32 offset1:48
	ds_read2_b32 v[154:155], v142 offset0:128 offset1:144
	ds_read2_b32 v[142:143], v142 offset0:160 offset1:176
	v_or_b32_e32 v146, s39, v144
	v_or_b32_e32 v144, s38, v145
	v_lshl_add_u32 v149, s46, 8, v144
	v_ashrrev_i32_e32 v147, 31, v146
	v_mov_b64_e32 v[144:145], s[92:93]
	v_mad_i64_i32 v[156:157], s[18:19], v149, s11, v[144:145]
	v_lshlrev_b64 v[146:147], 1, v[146:147]
	s_waitcnt lgkmcnt(0)
; __device__ __forceinline__ unsigned cvt_pk_bf16(float lo, float hi) { const f32x2 v = {lo, hi}; const bf16v2_ r = __builtin_convertvector(v, bf16v2_); return __builtin_bit_cast(unsigned, r); }
;     __device__ __forceinline__ void operator()(const f32x4 (&acc)[2][2][4][2], const Unit& u, int wr, int wc, int ui, int) const {
;     ...
;         for (int ai = 0; ai < 2; ++ai)
; #pragma unroll
;             for (int m = 0; m < 4; ++m) { bf16_t* rowp = O + (size_t)(row0 + ai * HALF + m * 16) * ldc + col0; const float r = r_[ai][m];
; #pragma unroll
;                 for (int bj = 0; bj < 2; ++bj) { const f32x4 v0 = acc[ai][bj][m][0] * r, v1 = acc[ai][bj][m][1] * r;
;                     u32x4 w; w.x = cvt_pk_bf16(v0[0], v0[1]); w.y = cvt_pk_bf16(v0[2], v0[3]); w.z = cvt_pk_bf16(v1[0], v1[1]); w.w = cvt_pk_bf16(v1[2], v1[3]);
;                     *(u32x4*)(rowp + bj * HALF) = w; } }
	v_pk_mul_f32 v[130:131], v[130:131], v[150:151] op_sel_hi:[1,0]
	v_pk_mul_f32 v[128:129], v[128:129], v[150:151] op_sel_hi:[1,0]
	v_pk_mul_f32 v[158:159], v[126:127], v[150:151] op_sel_hi:[1,0]
	v_pk_mul_f32 v[126:127], v[124:125], v[150:151] op_sel_hi:[1,0]
	v_lshl_add_u64 v[156:157], v[156:157], 0, v[146:147]
	v_cvt_pk_bf16_f32 v124, v128, v129
	v_cvt_pk_bf16_f32 v125, v130, v131
	v_cvt_pk_bf16_f32 v126, v126, v127
	v_cvt_pk_bf16_f32 v127, v158, v159
	global_store_dwordx4 v[156:157], v[124:127], off
	v_pk_mul_f32 v[118:119], v[118:119], v[150:151] op_sel_hi:[1,0]
	v_pk_mul_f32 v[116:117], v[116:117], v[150:151] op_sel_hi:[1,0]
	v_pk_mul_f32 v[124:125], v[110:111], v[150:151] op_sel_hi:[1,0]
	v_pk_mul_f32 v[110:111], v[108:109], v[150:151] op_sel_hi:[1,0]
	v_cvt_pk_bf16_f32 v108, v116, v117
	v_cvt_pk_bf16_f32 v109, v118, v119
	v_cvt_pk_bf16_f32 v110, v110, v111
	v_cvt_pk_bf16_f32 v111, v124, v125
	global_store_dwordx4 v[156:157], v[108:111], off offset:256
	v_mov_b32_e32 v118, v151
	v_pk_mul_f32 v[114:115], v[114:115], v[118:119] op_sel_hi:[1,0]
	v_or_b32_e32 v108, 16, v149
	v_mad_i64_i32 v[108:109], s[18:19], v108, s11, v[144:145]
	v_lshl_add_u64 v[116:117], v[108:109], 0, v[146:147]
	v_pk_mul_f32 v[110:111], v[122:123], v[118:119] op_sel_hi:[1,0]
	v_pk_mul_f32 v[108:109], v[120:121], v[118:119] op_sel_hi:[1,0]
	v_pk_mul_f32 v[112:113], v[112:113], v[118:119] op_sel_hi:[1,0]
	v_cvt_pk_bf16_f32 v108, v108, v109
	v_cvt_pk_bf16_f32 v109, v110, v111
	v_cvt_pk_bf16_f32 v110, v112, v113
	v_cvt_pk_bf16_f32 v111, v114, v115
	global_store_dwordx4 v[116:117], v[108:111], off
	v_pk_mul_f32 v[102:103], v[102:103], v[118:119] op_sel_hi:[1,0]
	v_pk_mul_f32 v[100:101], v[100:101], v[118:119] op_sel_hi:[1,0]
	v_pk_mul_f32 v[108:109], v[94:95], v[118:119] op_sel_hi:[1,0]
	v_pk_mul_f32 v[94:95], v[92:93], v[118:119] op_sel_hi:[1,0]
	v_cvt_pk_bf16_f32 v92, v100, v101
	v_cvt_pk_bf16_f32 v93, v102, v103
	v_cvt_pk_bf16_f32 v94, v94, v95
	v_cvt_pk_bf16_f32 v95, v108, v109
	global_store_dwordx4 v[116:117], v[92:95], off offset:256
	v_pk_mul_f32 v[98:99], v[98:99], v[152:153] op_sel_hi:[1,0]
	v_pk_mul_f32 v[96:97], v[96:97], v[152:153] op_sel_hi:[1,0]
	v_or_b32_e32 v92, 32, v149
	v_mad_i64_i32 v[92:93], s[18:19], v92, s11, v[144:145]
	v_lshl_add_u64 v[100:101], v[92:93], 0, v[146:147]
	v_pk_mul_f32 v[94:95], v[106:107], v[152:153] op_sel_hi:[1,0]
	v_pk_mul_f32 v[92:93], v[104:105], v[152:153] op_sel_hi:[1,0]
	v_pk_mul_f32 v[86:87], v[86:87], v[152:153] op_sel_hi:[1,0]
	v_cvt_pk_bf16_f32 v92, v92, v93
	v_cvt_pk_bf16_f32 v93, v94, v95
	v_cvt_pk_bf16_f32 v94, v96, v97
	v_cvt_pk_bf16_f32 v95, v98, v99
	global_store_dwordx4 v[100:101], v[92:95], off
	v_pk_mul_f32 v[84:85], v[84:85], v[152:153] op_sel_hi:[1,0]
	v_pk_mul_f32 v[66:67], v[66:67], v[154:155] op_sel_hi:[1,0]
	v_pk_mul_f32 v[92:93], v[78:79], v[152:153] op_sel_hi:[1,0]
	v_pk_mul_f32 v[78:79], v[76:77], v[152:153] op_sel_hi:[1,0]
	v_cvt_pk_bf16_f32 v76, v84, v85
	v_cvt_pk_bf16_f32 v77, v86, v87
	v_cvt_pk_bf16_f32 v78, v78, v79
	v_cvt_pk_bf16_f32 v79, v92, v93
	global_store_dwordx4 v[100:101], v[76:79], off offset:256
	v_mov_b32_e32 v86, v153
	v_pk_mul_f32 v[82:83], v[82:83], v[86:87] op_sel_hi:[1,0]
	v_or_b32_e32 v76, 48, v149
	v_mad_i64_i32 v[76:77], s[18:19], v76, s11, v[144:145]
	v_lshl_add_u64 v[84:85], v[76:77], 0, v[146:147]
	v_pk_mul_f32 v[78:79], v[90:91], v[86:87] op_sel_hi:[1,0]
	v_pk_mul_f32 v[76:77], v[88:89], v[86:87] op_sel_hi:[1,0]
	v_pk_mul_f32 v[80:81], v[80:81], v[86:87] op_sel_hi:[1,0]
	v_cvt_pk_bf16_f32 v76, v76, v77
	v_cvt_pk_bf16_f32 v77, v78, v79
	v_cvt_pk_bf16_f32 v78, v80, v81
	v_cvt_pk_bf16_f32 v79, v82, v83
	global_store_dwordx4 v[84:85], v[76:79], off
	v_pk_mul_f32 v[74:75], v[74:75], v[86:87] op_sel_hi:[1,0]
	v_pk_mul_f32 v[72:73], v[72:73], v[86:87] op_sel_hi:[1,0]
	v_pk_mul_f32 v[76:77], v[70:71], v[86:87] op_sel_hi:[1,0]
	v_pk_mul_f32 v[70:71], v[68:69], v[86:87] op_sel_hi:[1,0]
	v_cvt_pk_bf16_f32 v68, v72, v73
	v_cvt_pk_bf16_f32 v69, v74, v75
	v_cvt_pk_bf16_f32 v70, v70, v71
	v_cvt_pk_bf16_f32 v71, v76, v77
	global_store_dwordx4 v[84:85], v[68:71], off offset:256
; __device__ __forceinline__ unsigned cvt_pk_bf16(float lo, float hi) { const f32x2 v = {lo, hi}; const bf16v2_ r = __builtin_convertvector(v, bf16v2_); return __builtin_bit_cast(unsigned, r); }
;     __device__ __forceinline__ void operator()(const f32x4 (&acc)[2][2][4][2], const Unit& u, int wr, int wc, int ui, int) const {
;     ...
;         for (int ai = 0; ai < 2; ++ai)
; #pragma unroll
;             for (int m = 0; m < 4; ++m) { bf16_t* rowp = O + (size_t)(row0 + ai * HALF + m * 16) * ldc + col0; const float r = r_[ai][m];
; #pragma unroll
;                 for (int bj = 0; bj < 2; ++bj) { const f32x4 v0 = acc[ai][bj][m][0] * r, v1 = acc[ai][bj][m][1] * r;
;                     u32x4 w; w.x = cvt_pk_bf16(v0[0], v0[1]); w.y = cvt_pk_bf16(v0[2], v0[3]); w.z = cvt_pk_bf16(v1[0], v1[1]); w.w = cvt_pk_bf16(v1[2], v1[3]);
;                     *(u32x4*)(rowp + bj * HALF) = w; } }
	v_pk_mul_f32 v[64:65], v[64:65], v[154:155] op_sel_hi:[1,0]
	v_pk_mul_f32 v[54:55], v[54:55], v[154:155] op_sel_hi:[1,0]
	v_add_u32_e32 v68, 0x80, v149
	v_mad_i64_i32 v[68:69], s[18:19], v68, s11, v[144:145]
	v_pk_mul_f32 v[70:71], v[62:63], v[154:155] op_sel_hi:[1,0]
	v_pk_mul_f32 v[62:63], v[60:61], v[154:155] op_sel_hi:[1,0]
	v_lshl_add_u64 v[68:69], v[68:69], 0, v[146:147]
	v_cvt_pk_bf16_f32 v60, v64, v65
	v_cvt_pk_bf16_f32 v61, v66, v67
	v_cvt_pk_bf16_f32 v62, v62, v63
	v_cvt_pk_bf16_f32 v63, v70, v71
	global_store_dwordx4 v[68:69], v[60:63], off
	v_pk_mul_f32 v[52:53], v[52:53], v[154:155] op_sel_hi:[1,0]
	v_pk_mul_f32 v[34:35], v[34:35], v[142:143] op_sel_hi:[1,0]
	v_pk_mul_f32 v[60:61], v[46:47], v[154:155] op_sel_hi:[1,0]
	v_pk_mul_f32 v[46:47], v[44:45], v[154:155] op_sel_hi:[1,0]
	v_cvt_pk_bf16_f32 v44, v52, v53
	v_cvt_pk_bf16_f32 v45, v54, v55
	v_cvt_pk_bf16_f32 v46, v46, v47
	v_cvt_pk_bf16_f32 v47, v60, v61
	global_store_dwordx4 v[68:69], v[44:47], off offset:256
	v_mov_b32_e32 v54, v155
	v_pk_mul_f32 v[50:51], v[50:51], v[54:55] op_sel_hi:[1,0]
	v_add_u32_e32 v44, 0x90, v149
	v_mad_i64_i32 v[44:45], s[18:19], v44, s11, v[144:145]
	v_lshl_add_u64 v[52:53], v[44:45], 0, v[146:147]
	v_pk_mul_f32 v[46:47], v[58:59], v[54:55] op_sel_hi:[1,0]
	v_pk_mul_f32 v[44:45], v[56:57], v[54:55] op_sel_hi:[1,0]
	v_pk_mul_f32 v[48:49], v[48:49], v[54:55] op_sel_hi:[1,0]
	v_cvt_pk_bf16_f32 v44, v44, v45
	v_cvt_pk_bf16_f32 v45, v46, v47
	v_cvt_pk_bf16_f32 v46, v48, v49
	v_cvt_pk_bf16_f32 v47, v50, v51
	global_store_dwordx4 v[52:53], v[44:47], off
	v_pk_mul_f32 v[38:39], v[38:39], v[54:55] op_sel_hi:[1,0]
	v_pk_mul_f32 v[36:37], v[36:37], v[54:55] op_sel_hi:[1,0]
	v_pk_mul_f32 v[44:45], v[30:31], v[54:55] op_sel_hi:[1,0]
	v_pk_mul_f32 v[30:31], v[28:29], v[54:55] op_sel_hi:[1,0]
	v_cvt_pk_bf16_f32 v28, v36, v37
	v_cvt_pk_bf16_f32 v29, v38, v39
	v_cvt_pk_bf16_f32 v30, v30, v31
	v_cvt_pk_bf16_f32 v31, v44, v45
	global_store_dwordx4 v[52:53], v[28:31], off offset:256
	v_pk_mul_f32 v[32:33], v[32:33], v[142:143] op_sel_hi:[1,0]
	v_pk_mul_f32 v[22:23], v[22:23], v[142:143] op_sel_hi:[1,0]
	v_add_u32_e32 v28, 0xa0, v149
	v_mad_i64_i32 v[28:29], s[18:19], v28, s11, v[144:145]
	v_lshl_add_u64 v[36:37], v[28:29], 0, v[146:147]
	v_pk_mul_f32 v[30:31], v[42:43], v[142:143] op_sel_hi:[1,0]
	v_pk_mul_f32 v[28:29], v[40:41], v[142:143] op_sel_hi:[1,0]
	v_pk_mul_f32 v[20:21], v[20:21], v[142:143] op_sel_hi:[1,0]
	v_cvt_pk_bf16_f32 v28, v28, v29
	v_cvt_pk_bf16_f32 v29, v30, v31
	v_cvt_pk_bf16_f32 v30, v32, v33
	v_cvt_pk_bf16_f32 v31, v34, v35
	global_store_dwordx4 v[36:37], v[28:31], off
	s_and_b64 vcc, exec, s[40:41]
	s_mov_b32 s47, s0
	v_pk_mul_f32 v[28:29], v[14:15], v[142:143] op_sel_hi:[1,0]
	v_pk_mul_f32 v[14:15], v[12:13], v[142:143] op_sel_hi:[1,0]
	v_cvt_pk_bf16_f32 v12, v20, v21
	v_cvt_pk_bf16_f32 v13, v22, v23
	v_cvt_pk_bf16_f32 v14, v14, v15
	v_cvt_pk_bf16_f32 v15, v28, v29
	global_store_dwordx4 v[36:37], v[12:15], off offset:256
	v_mov_b32_e32 v22, v143
	v_pk_mul_f32 v[18:19], v[18:19], v[22:23] op_sel_hi:[1,0]
	v_add_u32_e32 v12, 0xb0, v149
	v_mad_i64_i32 v[12:13], s[18:19], v12, s11, v[144:145]
	v_lshl_add_u64 v[20:21], v[12:13], 0, v[146:147]
	v_pk_mul_f32 v[14:15], v[26:27], v[22:23] op_sel_hi:[1,0]
	v_pk_mul_f32 v[12:13], v[24:25], v[22:23] op_sel_hi:[1,0]
	v_pk_mul_f32 v[16:17], v[16:17], v[22:23] op_sel_hi:[1,0]
	v_cvt_pk_bf16_f32 v12, v12, v13
	v_cvt_pk_bf16_f32 v13, v14, v15
	v_cvt_pk_bf16_f32 v14, v16, v17
	v_cvt_pk_bf16_f32 v15, v18, v19
	global_store_dwordx4 v[20:21], v[12:15], off
	v_pk_mul_f32 v[10:11], v[10:11], v[22:23] op_sel_hi:[1,0]
	v_pk_mul_f32 v[8:9], v[8:9], v[22:23] op_sel_hi:[1,0]
	v_pk_mul_f32 v[12:13], v[6:7], v[22:23] op_sel_hi:[1,0]
	v_pk_mul_f32 v[6:7], v[4:5], v[22:23] op_sel_hi:[1,0]
	v_cvt_pk_bf16_f32 v4, v8, v9
	v_cvt_pk_bf16_f32 v5, v10, v11
	v_cvt_pk_bf16_f32 v6, v6, v7
	v_cvt_pk_bf16_f32 v7, v12, v13
	s_mov_b32 s46, s4
	s_mov_b64 s[20:21], s[14:15]
	s_mov_b64 s[18:19], s[6:7]
	s_mov_b32 s48, s45
	global_store_dwordx4 v[20:21], v[4:7], off offset:256
	s_cmpk_lt_u32 s2, 0x100
	s_cbranch_scc1 .Lalign_b_1094
	s_barrier

; #define PG8_STAGE(bufoff, gbase, voff) do { _Pragma("unroll") for (int _i = 0; _i < 2; ++_i) \
;         __builtin_amdgcn_global_load_lds((const unsigned*)((const char*)(gbase) + (voff)[_i]), (LAS unsigned*)(lds + (bufoff) + ldsw + _i * 8192), 16, 0, 0); } while (0)
; #define PG8_LDA(dst, b, h) do { _Pragma("unroll") for (int m = 0; m < 4; ++m) _Pragma("unroll") for (int k = 0; k < 2; ++k) dst[m][k] = *(const LAS bf16x8*)(lds + PG8_SA(b, h) + aoff + m * 2048 + k * 1024); } while (0)
; #define PG8_LDB(dst, b, h) do { _Pragma("unroll") for (int n = 0; n < 2; ++n) _Pragma("unroll") for (int k = 0; k < 2; ++k) dst[n][k] = *(const LAS bf16x8*)(lds + PG8_SB(b, h) + boff + n * 2048 + k * 1024); } while (0)
; #define PG8_MMA(ai, bj, At, Bt) do { __builtin_amdgcn_s_setprio(1); _Pragma("unroll") for (int m = 0; m < 4; ++m) _Pragma("unroll") for (int n = 0; n < 2; ++n) _Pragma("unroll") for (int k = 0; k < 2; ++k) \
;         acc[ai][bj][m][n] = __builtin_amdgcn_mfma_f32_16x16x32_bf16(Bt[n][k], At[m][k], acc[ai][bj][m][n], 0, 0, 0); __builtin_amdgcn_s_setprio(0); } while (0)
; #define PG8_WAIT_V(n) asm volatile("s_waitcnt vmcnt(" #n ")" ::: "memory")
; #define PG8_WAIT_L(n) asm volatile("s_waitcnt lgkmcnt(" #n ")" ::: "memory")
; #define PG8_BAR __builtin_amdgcn_s_barrier()
; #define PG8_SCHED __builtin_amdgcn_sched_barrier(0)
; template <class Epi, class Sched>
; __device__ __forceinline__ void gemm_phase(LAS unsigned char* lds, const Gemm g, const Sched& S, const Epi& E) {
;     ...
;             PG8_LDB(B0, 0, 0); PG8_SCHED; PG8_LDA(At, 0, 0); PG8_STAGE(PG8_SA(1, 1), a1 + hstepA, voffA);
;             PG8_WAIT_L(8); PG8_BAR; PG8_WAIT_L(0); PG8_MMA(0, 0, At, B0); PG8_BAR; PG8_SCHED;
;             PG8_LDB(B1, 0, 1); PG8_STAGE(PG8_SB(0, 0), b2, voffB);
;             PG8_BAR; PG8_WAIT_L(0); PG8_MMA(0, 1, At, B1); PG8_BAR;
;             PG8_LDA(At, 0, 1); PG8_STAGE(PG8_SA(0, 0), a2, voffA);
;             PG8_BAR; PG8_WAIT_L(0); PG8_MMA(1, 0, At, B0); PG8_BAR; PG8_SCHED;
;             PG8_STAGE(PG8_SB(0, 1), b2 + hstepB, voffB);
;             PG8_WAIT_V(6); PG8_BAR; PG8_MMA(1, 1, At, B1); PG8_BAR;
.LBB0_1396:
	s_setprio 0
	s_add_u32 s20, s6, 0xfff80080
	s_addc_u32 s21, s7, -1
	s_add_i32 s52, 0, 0x10000
	v_add_u32_e32 v144, s52, v1
	ds_read_b128 v[132:135], v144
	ds_read_b128 v[136:139], v144 offset:1024
	ds_read_b128 v[140:143], v144 offset:2048
	ds_read_b128 v[144:147], v144 offset:3072
	s_cmp_eq_u32 s51, 28
	s_cselect_b32 s25, s15, s21
	s_cselect_b32 s24, s47, s20
	s_cselect_b32 s21, s1, s50
	s_cselect_b32 s20, s48, s49
	ds_read_b128 v[148:151], v224
	ds_read_b128 v[152:155], v224 offset:1024
	ds_read_b128 v[156:159], v224 offset:2048
	ds_read_b128 v[160:163], v224 offset:3072
	ds_read_b128 v[164:167], v224 offset:4096
	ds_read_b128 v[168:171], v224 offset:5120
	ds_read_b128 v[172:175], v224 offset:6144
	ds_read_b128 v[176:179], v224 offset:7168
	s_add_i32 s54, 0, 0x14000
	v_add_u32_e32 v202, s54, v1
	ds_read_b128 v[180:183], v202
	ds_read_b128 v[184:187], v202 offset:1024
	ds_read_b128 v[188:191], v202 offset:2048
	ds_read_b128 v[202:205], v202 offset:3072
	s_add_i32 m0, s31, 0xc000
	s_nop 0
	global_load_lds_dwordx4 v198, s[6:7]
	s_add_i32 m0, s31, 0xe000
	s_nop 0
	global_load_lds_dwordx4 v200, s[6:7]
	s_waitcnt lgkmcnt(0)
	s_setprio 1
	s_barrier
	v_mfma_f32_16x16x32_bf16 v[128:131], v[132:135], v[148:151], v[128:131]
	v_mfma_f32_16x16x32_bf16 v[124:127], v[140:143], v[148:151], v[124:127]
	v_mfma_f32_16x16x32_bf16 v[112:115], v[132:135], v[156:159], v[112:115]
	v_mfma_f32_16x16x32_bf16 v[108:111], v[140:143], v[156:159], v[108:111]
	v_mfma_f32_16x16x32_bf16 v[100:103], v[132:135], v[164:167], v[100:103]
	v_mfma_f32_16x16x32_bf16 v[92:95], v[140:143], v[164:167], v[92:95]
	v_mfma_f32_16x16x32_bf16 v[84:87], v[132:135], v[172:175], v[84:87]
	v_mfma_f32_16x16x32_bf16 v[76:79], v[140:143], v[172:175], v[76:79]
	v_mfma_f32_16x16x32_bf16 v[128:131], v[136:139], v[152:155], v[128:131]
	v_mfma_f32_16x16x32_bf16 v[124:127], v[144:147], v[152:155], v[124:127]
	v_mfma_f32_16x16x32_bf16 v[112:115], v[136:139], v[160:163], v[112:115]
	v_mfma_f32_16x16x32_bf16 v[108:111], v[144:147], v[160:163], v[108:111]
	v_mfma_f32_16x16x32_bf16 v[100:103], v[136:139], v[168:171], v[100:103]
	v_mfma_f32_16x16x32_bf16 v[92:95], v[144:147], v[168:171], v[92:95]
	v_mfma_f32_16x16x32_bf16 v[84:87], v[136:139], v[176:179], v[84:87]
	v_mfma_f32_16x16x32_bf16 v[76:79], v[144:147], v[176:179], v[76:79]
	v_mfma_f32_16x16x32_bf16 v[120:123], v[180:183], v[148:151], v[120:123]
	v_mfma_f32_16x16x32_bf16 v[116:119], v[188:191], v[148:151], v[116:119]
	v_mfma_f32_16x16x32_bf16 v[104:107], v[180:183], v[156:159], v[104:107]
	v_mfma_f32_16x16x32_bf16 v[96:99], v[188:191], v[156:159], v[96:99]
	v_mfma_f32_16x16x32_bf16 v[88:91], v[180:183], v[164:167], v[88:91]
	v_mfma_f32_16x16x32_bf16 v[80:83], v[188:191], v[164:167], v[80:83]
	v_mfma_f32_16x16x32_bf16 v[72:75], v[180:183], v[172:175], v[72:75]
	v_mfma_f32_16x16x32_bf16 v[68:71], v[188:191], v[172:175], v[68:71]
	v_mfma_f32_16x16x32_bf16 v[120:123], v[184:187], v[152:155], v[120:123]
	v_mfma_f32_16x16x32_bf16 v[116:119], v[202:205], v[152:155], v[116:119]
	v_mfma_f32_16x16x32_bf16 v[104:107], v[184:187], v[160:163], v[104:107]
	v_mfma_f32_16x16x32_bf16 v[96:99], v[202:205], v[160:163], v[96:99]
	v_mfma_f32_16x16x32_bf16 v[88:91], v[184:187], v[168:171], v[88:91]
	v_mfma_f32_16x16x32_bf16 v[80:83], v[202:205], v[168:171], v[80:83]
	v_mfma_f32_16x16x32_bf16 v[72:75], v[184:187], v[176:179], v[72:75]
	v_mfma_f32_16x16x32_bf16 v[68:71], v[202:205], v[176:179], v[68:71]
	s_barrier
	s_setprio 0
	ds_read_b128 v[148:151], v224 offset:16384
	ds_read_b128 v[152:155], v224 offset:17408
	ds_read_b128 v[156:159], v224 offset:18432
	ds_read_b128 v[160:163], v224 offset:19456
	ds_read_b128 v[164:167], v224 offset:20480
	ds_read_b128 v[168:171], v224 offset:21504
	ds_read_b128 v[172:175], v224 offset:22528
	ds_read_b128 v[176:179], v224 offset:23552
	s_add_i32 s52, s52, s30
	v_lshl_add_u64 v[206:207], s[20:21], 0, v[2:3]
	s_mov_b32 m0, s52
	s_nop 0
	global_load_lds_dwordx4 v[206:207], off
	v_lshl_add_u64 v[208:209], s[20:21], 0, v[192:193]
	s_add_i32 m0, s52, 0x2000
	s_nop 0
	global_load_lds_dwordx4 v[208:209], off
	s_mov_b32 m0, s31
	v_lshl_add_u64 v[210:211], s[24:25], 0, v[196:197]
	global_load_lds_dwordx4 v[210:211], off
	v_lshl_add_u64 v[212:213], s[24:25], 0, v[194:195]
	s_mov_b32 m0, s35
	s_nop 0
	global_load_lds_dwordx4 v[212:213], off
	s_add_u32 s52, s20, 0x80000
	s_addc_u32 s53, s21, 0
	s_add_i32 s54, s54, s30
	s_mov_b32 m0, s54
	s_nop 0
	global_load_lds_dwordx4 v2, s[52:53]
	s_add_i32 m0, s54, 0x2000
	s_nop 0
	global_load_lds_dwordx4 v192, s[52:53]
	s_waitcnt lgkmcnt(0)
	s_waitcnt vmcnt(6)
	s_setprio 1
	s_barrier
; #define PG8_STAGE(bufoff, gbase, voff) do { _Pragma("unroll") for (int _i = 0; _i < 2; ++_i) \
;         __builtin_amdgcn_global_load_lds((const unsigned*)((const char*)(gbase) + (voff)[_i]), (LAS unsigned*)(lds + (bufoff) + ldsw + _i * 8192), 16, 0, 0); } while (0)
; #define PG8_LDA(dst, b, h) do { _Pragma("unroll") for (int m = 0; m < 4; ++m) _Pragma("unroll") for (int k = 0; k < 2; ++k) dst[m][k] = *(const LAS bf16x8*)(lds + PG8_SA(b, h) + aoff + m * 2048 + k * 1024); } while (0)
; #define PG8_LDB(dst, b, h) do { _Pragma("unroll") for (int n = 0; n < 2; ++n) _Pragma("unroll") for (int k = 0; k < 2; ++k) dst[n][k] = *(const LAS bf16x8*)(lds + PG8_SB(b, h) + boff + n * 2048 + k * 1024); } while (0)
; #define PG8_MMA(ai, bj, At, Bt) do { __builtin_amdgcn_s_setprio(1); _Pragma("unroll") for (int m = 0; m < 4; ++m) _Pragma("unroll") for (int n = 0; n < 2; ++n) _Pragma("unroll") for (int k = 0; k < 2; ++k) \
;         acc[ai][bj][m][n] = __builtin_amdgcn_mfma_f32_16x16x32_bf16(Bt[n][k], At[m][k], acc[ai][bj][m][n], 0, 0, 0); __builtin_amdgcn_s_setprio(0); } while (0)
; #define PG8_WAIT_V(n) asm volatile("s_waitcnt vmcnt(" #n ")" ::: "memory")
; #define PG8_WAIT_L(n) asm volatile("s_waitcnt lgkmcnt(" #n ")" ::: "memory")
; #define PG8_BAR __builtin_amdgcn_s_barrier()
; #define PG8_SCHED __builtin_amdgcn_sched_barrier(0)
; template <class Epi, class Sched>
; __device__ __forceinline__ void gemm_phase(LAS unsigned char* lds, const Gemm g, const Sched& S, const Epi& E) {
;     ...
;             PG8_WAIT_V(6); PG8_BAR; PG8_MMA(1, 1, At, B1); PG8_BAR;
;             PG8_LDB(B0, 1, 0); PG8_SCHED; PG8_LDA(At, 1, 0); PG8_STAGE(PG8_SA(0, 1), a2 + hstepA, voffA);
;             PG8_WAIT_L(8); PG8_BAR; PG8_WAIT_L(0); PG8_MMA(0, 0, At, B0); PG8_BAR; PG8_SCHED;
;             PG8_LDB(B1, 1, 1); PG8_STAGE(PG8_SB(1, 0), b3, voffB);
;             PG8_BAR; PG8_WAIT_L(0); PG8_MMA(0, 1, At, B1); PG8_BAR;
;             PG8_LDA(At, 1, 1); PG8_STAGE(PG8_SA(1, 0), a3, voffA);
;             PG8_BAR; PG8_WAIT_L(0); PG8_MMA(1, 0, At, B0); PG8_BAR; PG8_SCHED;
	v_mfma_f32_16x16x32_bf16 v[64:67], v[132:135], v[148:151], v[64:67]
	v_mfma_f32_16x16x32_bf16 v[60:63], v[140:143], v[148:151], v[60:63]
	v_mfma_f32_16x16x32_bf16 v[52:55], v[132:135], v[156:159], v[52:55]
	v_mfma_f32_16x16x32_bf16 v[44:47], v[140:143], v[156:159], v[44:47]
	v_mfma_f32_16x16x32_bf16 v[36:39], v[132:135], v[164:167], v[36:39]
	v_mfma_f32_16x16x32_bf16 v[28:31], v[140:143], v[164:167], v[28:31]
	v_mfma_f32_16x16x32_bf16 v[20:23], v[132:135], v[172:175], v[20:23]
	v_mfma_f32_16x16x32_bf16 v[12:15], v[140:143], v[172:175], v[12:15]
	v_mfma_f32_16x16x32_bf16 v[64:67], v[136:139], v[152:155], v[64:67]
	v_mfma_f32_16x16x32_bf16 v[60:63], v[144:147], v[152:155], v[60:63]
	v_mfma_f32_16x16x32_bf16 v[52:55], v[136:139], v[160:163], v[52:55]
	v_mfma_f32_16x16x32_bf16 v[44:47], v[144:147], v[160:163], v[44:47]
	v_mfma_f32_16x16x32_bf16 v[36:39], v[136:139], v[168:171], v[36:39]
	v_mfma_f32_16x16x32_bf16 v[28:31], v[144:147], v[168:171], v[28:31]
	v_mfma_f32_16x16x32_bf16 v[20:23], v[136:139], v[176:179], v[20:23]
	v_mfma_f32_16x16x32_bf16 v[12:15], v[144:147], v[176:179], v[12:15]
	v_mfma_f32_16x16x32_bf16 v[56:59], v[180:183], v[148:151], v[56:59]
	v_mfma_f32_16x16x32_bf16 v[48:51], v[188:191], v[148:151], v[48:51]
	v_mfma_f32_16x16x32_bf16 v[40:43], v[180:183], v[156:159], v[40:43]
	v_mfma_f32_16x16x32_bf16 v[32:35], v[188:191], v[156:159], v[32:35]
	v_mfma_f32_16x16x32_bf16 v[24:27], v[180:183], v[164:167], v[24:27]
	v_mfma_f32_16x16x32_bf16 v[16:19], v[188:191], v[164:167], v[16:19]
	v_mfma_f32_16x16x32_bf16 v[8:11], v[180:183], v[172:175], v[8:11]
	v_mfma_f32_16x16x32_bf16 v[4:7], v[188:191], v[172:175], v[4:7]
	v_mfma_f32_16x16x32_bf16 v[56:59], v[184:187], v[152:155], v[56:59]
	v_mfma_f32_16x16x32_bf16 v[48:51], v[202:205], v[152:155], v[48:51]
	v_mfma_f32_16x16x32_bf16 v[40:43], v[184:187], v[160:163], v[40:43]
	v_mfma_f32_16x16x32_bf16 v[32:35], v[202:205], v[160:163], v[32:35]
	v_mfma_f32_16x16x32_bf16 v[24:27], v[184:187], v[168:171], v[24:27]
	v_mfma_f32_16x16x32_bf16 v[16:19], v[202:205], v[168:171], v[16:19]
	v_mfma_f32_16x16x32_bf16 v[8:11], v[184:187], v[176:179], v[8:11]
	v_mfma_f32_16x16x32_bf16 v[4:7], v[202:205], v[176:179], v[4:7]
	s_barrier
	s_setprio 0
	s_add_i32 s52, 0, 0x18000
	v_add_u32_e32 v144, s52, v1
	ds_read_b128 v[132:135], v144
	ds_read_b128 v[136:139], v144 offset:1024
	ds_read_b128 v[140:143], v144 offset:2048
	ds_read_b128 v[144:147], v144 offset:3072
	s_add_u32 s24, s24, 0x80000
	s_addc_u32 s25, s25, 0
	ds_read_b128 v[148:151], v224 offset:32768
	ds_read_b128 v[152:155], v224 offset:33792
	ds_read_b128 v[156:159], v224 offset:34816
	ds_read_b128 v[160:163], v224 offset:35840
	ds_read_b128 v[164:167], v224 offset:36864
	ds_read_b128 v[168:171], v224 offset:37888
	ds_read_b128 v[172:175], v224 offset:38912
	ds_read_b128 v[176:179], v224 offset:39936
	s_mov_b32 m0, s36
	s_nop 0
	global_load_lds_dwordx4 v196, s[24:25]
	s_mov_b32 m0, s37
	s_nop 0
	global_load_lds_dwordx4 v194, s[24:25]
	s_add_i32 s24, 0, 0x1c000
	v_add_u32_e32 v202, s24, v1
	ds_read_b128 v[180:183], v202
	ds_read_b128 v[184:187], v202 offset:1024
	ds_read_b128 v[188:191], v202 offset:2048
	ds_read_b128 v[202:205], v202 offset:3072
	s_waitcnt lgkmcnt(0)
	s_setprio 1
	s_barrier
	v_mfma_f32_16x16x32_bf16 v[128:131], v[132:135], v[148:151], v[128:131]
	v_mfma_f32_16x16x32_bf16 v[124:127], v[140:143], v[148:151], v[124:127]
	v_mfma_f32_16x16x32_bf16 v[112:115], v[132:135], v[156:159], v[112:115]
	v_mfma_f32_16x16x32_bf16 v[108:111], v[140:143], v[156:159], v[108:111]
	v_mfma_f32_16x16x32_bf16 v[100:103], v[132:135], v[164:167], v[100:103]
	v_mfma_f32_16x16x32_bf16 v[92:95], v[140:143], v[164:167], v[92:95]
	v_mfma_f32_16x16x32_bf16 v[84:87], v[132:135], v[172:175], v[84:87]
	v_mfma_f32_16x16x32_bf16 v[76:79], v[140:143], v[172:175], v[76:79]
	v_mfma_f32_16x16x32_bf16 v[128:131], v[136:139], v[152:155], v[128:131]
	v_mfma_f32_16x16x32_bf16 v[124:127], v[144:147], v[152:155], v[124:127]
	v_mfma_f32_16x16x32_bf16 v[112:115], v[136:139], v[160:163], v[112:115]
	v_mfma_f32_16x16x32_bf16 v[108:111], v[144:147], v[160:163], v[108:111]
	v_mfma_f32_16x16x32_bf16 v[100:103], v[136:139], v[168:171], v[100:103]
	v_mfma_f32_16x16x32_bf16 v[92:95], v[144:147], v[168:171], v[92:95]
	v_mfma_f32_16x16x32_bf16 v[84:87], v[136:139], v[176:179], v[84:87]
	v_mfma_f32_16x16x32_bf16 v[76:79], v[144:147], v[176:179], v[76:79]
	v_mfma_f32_16x16x32_bf16 v[120:123], v[180:183], v[148:151], v[120:123]
	v_mfma_f32_16x16x32_bf16 v[116:119], v[188:191], v[148:151], v[116:119]
	v_mfma_f32_16x16x32_bf16 v[104:107], v[180:183], v[156:159], v[104:107]
	v_mfma_f32_16x16x32_bf16 v[96:99], v[188:191], v[156:159], v[96:99]
	v_mfma_f32_16x16x32_bf16 v[88:91], v[180:183], v[164:167], v[88:91]
	v_mfma_f32_16x16x32_bf16 v[80:83], v[188:191], v[164:167], v[80:83]
	v_mfma_f32_16x16x32_bf16 v[72:75], v[180:183], v[172:175], v[72:75]
	v_mfma_f32_16x16x32_bf16 v[68:71], v[188:191], v[172:175], v[68:71]
	v_mfma_f32_16x16x32_bf16 v[120:123], v[184:187], v[152:155], v[120:123]
	v_mfma_f32_16x16x32_bf16 v[116:119], v[202:205], v[152:155], v[116:119]
	v_mfma_f32_16x16x32_bf16 v[104:107], v[184:187], v[160:163], v[104:107]
	v_mfma_f32_16x16x32_bf16 v[96:99], v[202:205], v[160:163], v[96:99]
	v_mfma_f32_16x16x32_bf16 v[88:91], v[184:187], v[168:171], v[88:91]
	v_mfma_f32_16x16x32_bf16 v[80:83], v[202:205], v[168:171], v[80:83]
	v_mfma_f32_16x16x32_bf16 v[72:75], v[184:187], v[176:179], v[72:75]
	v_mfma_f32_16x16x32_bf16 v[68:71], v[202:205], v[176:179], v[68:71]
	s_barrier
; __device__ __forceinline__ int opaque_tid() { int t = threadIdx.x; asm volatile("" : "+v"(t)); return t; }
; #define PG8_STAGE(bufoff, gbase, voff) do { _Pragma("unroll") for (int _i = 0; _i < 2; ++_i) \
;         __builtin_amdgcn_global_load_lds((const unsigned*)((const char*)(gbase) + (voff)[_i]), (LAS unsigned*)(lds + (bufoff) + ldsw + _i * 8192), 16, 0, 0); } while (0)
; #define PG8_MMA(ai, bj, At, Bt) do { __builtin_amdgcn_s_setprio(1); _Pragma("unroll") for (int m = 0; m < 4; ++m) _Pragma("unroll") for (int n = 0; n < 2; ++n) _Pragma("unroll") for (int k = 0; k < 2; ++k) \
;         acc[ai][bj][m][n] = __builtin_amdgcn_mfma_f32_16x16x32_bf16(Bt[n][k], At[m][k], acc[ai][bj][m][n], 0, 0, 0); __builtin_amdgcn_s_setprio(0); } while (0)
; #define PG8_WAIT_V(n) asm volatile("s_waitcnt vmcnt(" #n ")" ::: "memory")
; #define PG8_WAIT_L(n) asm volatile("s_waitcnt lgkmcnt(" #n ")" ::: "memory")
; #define PG8_BAR __builtin_amdgcn_s_barrier()
; #define PG8_SCHED __builtin_amdgcn_sched_barrier(0)
;     __device__ __forceinline__ void operator()(const f32x4 (&acc)[2][2][4][2], const Unit& u, int wr, int wc, int, int) const {
;         const int ol_ = opaque_tid() & 63, fr = ol_ & 15, fq = ol_ >> 4;
;         const int row0 = u.pm * BM + wr * 64 + fr, col0 = u.pn * BM + wc * 32 + 8 * fq;
;         u32x4 cin[2][4][2];
; #pragma unroll
;         for (int ai = 0; ai < 2; ++ai)
; #pragma unroll
;             for (int m = 0; m < 4; ++m)
; #pragma unroll
;                 for (int bj = 0; bj < 2; ++bj) cin[ai][m][bj] = *(const u32x4*)(C + (size_t)(row0 + ai * HALF + m * 16) * ldc + col0 + bj * HALF);
; template <class Epi, class Sched>
; __device__ __forceinline__ void gemm_phase(LAS unsigned char* lds, const Gemm g, const Sched& S, const Epi& E) {
;     ...
;             PG8_BAR; PG8_WAIT_L(0); PG8_MMA(1, 0, At, B0); PG8_BAR; PG8_SCHED;
;             PG8_STAGE(PG8_SB(1, 1), b3 + hstepB, voffB);
;             PG8_WAIT_V(6); PG8_BAR; PG8_MMA(1, 1, At, B1); PG8_BAR;
	s_setprio 0
	ds_read_b128 v[148:151], v224 offset:49152
	ds_read_b128 v[152:155], v224 offset:50176
	ds_read_b128 v[156:159], v224 offset:51200
	ds_read_b128 v[160:163], v224 offset:52224
	ds_read_b128 v[164:167], v224 offset:53248
	ds_read_b128 v[168:171], v224 offset:54272
	ds_read_b128 v[172:175], v224 offset:55296
	ds_read_b128 v[176:179], v224 offset:56320
	s_add_i32 s25, s52, s30
	v_lshl_add_u64 v[206:207], v[206:207], 0, s[8:9]
	s_mov_b32 m0, s25
	s_nop 0
	global_load_lds_dwordx4 v[206:207], off
	v_lshl_add_u64 v[206:207], v[208:209], 0, s[8:9]
	s_add_i32 m0, s25, 0x2000
	s_nop 0
	global_load_lds_dwordx4 v[206:207], off
	s_mov_b32 m0, s42
	v_lshl_add_u64 v[206:207], v[210:211], 0, s[8:9]
	global_load_lds_dwordx4 v[206:207], off
	v_lshl_add_u64 v[206:207], v[212:213], 0, s[8:9]
	s_mov_b32 m0, s43
	s_nop 0
	global_load_lds_dwordx4 v[206:207], off
	s_add_u32 s20, s20, 0x80080
	s_addc_u32 s21, s21, 0
	s_add_i32 s24, s24, s30
	s_mov_b32 m0, s24
	s_nop 0
	global_load_lds_dwordx4 v2, s[20:21]
	s_add_i32 m0, s24, 0x2000
	s_nop 0
	global_load_lds_dwordx4 v192, s[20:21]
	s_add_i32 s51, s51, 2
	s_add_u32 s6, s6, 0x100
	s_addc_u32 s7, s7, 0
	s_add_u32 s49, s49, 0x100
	s_addc_u32 s50, s50, 0
	s_cmp_gt_u32 s51, 29
	s_waitcnt lgkmcnt(0)
	s_waitcnt vmcnt(6)
	s_setprio 1
	s_barrier
	v_mfma_f32_16x16x32_bf16 v[64:67], v[132:135], v[148:151], v[64:67]
	v_mfma_f32_16x16x32_bf16 v[60:63], v[140:143], v[148:151], v[60:63]
	v_mfma_f32_16x16x32_bf16 v[52:55], v[132:135], v[156:159], v[52:55]
	v_mfma_f32_16x16x32_bf16 v[44:47], v[140:143], v[156:159], v[44:47]
	v_mfma_f32_16x16x32_bf16 v[36:39], v[132:135], v[164:167], v[36:39]
	v_mfma_f32_16x16x32_bf16 v[28:31], v[140:143], v[164:167], v[28:31]
	v_mfma_f32_16x16x32_bf16 v[20:23], v[132:135], v[172:175], v[20:23]
	v_mfma_f32_16x16x32_bf16 v[12:15], v[140:143], v[172:175], v[12:15]
	v_mfma_f32_16x16x32_bf16 v[64:67], v[136:139], v[152:155], v[64:67]
	v_mfma_f32_16x16x32_bf16 v[60:63], v[144:147], v[152:155], v[60:63]
	v_mfma_f32_16x16x32_bf16 v[52:55], v[136:139], v[160:163], v[52:55]
	v_mfma_f32_16x16x32_bf16 v[44:47], v[144:147], v[160:163], v[44:47]
	v_mfma_f32_16x16x32_bf16 v[36:39], v[136:139], v[168:171], v[36:39]
	v_mfma_f32_16x16x32_bf16 v[28:31], v[144:147], v[168:171], v[28:31]
	v_mfma_f32_16x16x32_bf16 v[20:23], v[136:139], v[176:179], v[20:23]
	v_mfma_f32_16x16x32_bf16 v[12:15], v[144:147], v[176:179], v[12:15]
	v_mfma_f32_16x16x32_bf16 v[56:59], v[180:183], v[148:151], v[56:59]
	v_mfma_f32_16x16x32_bf16 v[48:51], v[188:191], v[148:151], v[48:51]
	v_mfma_f32_16x16x32_bf16 v[40:43], v[180:183], v[156:159], v[40:43]
	v_mfma_f32_16x16x32_bf16 v[32:35], v[188:191], v[156:159], v[32:35]
	v_mfma_f32_16x16x32_bf16 v[24:27], v[180:183], v[164:167], v[24:27]
	v_mfma_f32_16x16x32_bf16 v[16:19], v[188:191], v[164:167], v[16:19]
	v_mfma_f32_16x16x32_bf16 v[8:11], v[180:183], v[172:175], v[8:11]
	v_mfma_f32_16x16x32_bf16 v[4:7], v[188:191], v[172:175], v[4:7]
	v_mfma_f32_16x16x32_bf16 v[56:59], v[184:187], v[152:155], v[56:59]
	v_mfma_f32_16x16x32_bf16 v[48:51], v[202:205], v[152:155], v[48:51]
	v_mfma_f32_16x16x32_bf16 v[40:43], v[184:187], v[160:163], v[40:43]
	v_mfma_f32_16x16x32_bf16 v[32:35], v[202:205], v[160:163], v[32:35]
	v_mfma_f32_16x16x32_bf16 v[24:27], v[184:187], v[168:171], v[24:27]
	v_mfma_f32_16x16x32_bf16 v[16:19], v[202:205], v[168:171], v[16:19]
	v_mfma_f32_16x16x32_bf16 v[8:11], v[184:187], v[176:179], v[8:11]
	v_mfma_f32_16x16x32_bf16 v[4:7], v[202:205], v[176:179], v[4:7]
	s_barrier
	s_cbranch_scc0 .LBB0_1396
	s_setprio 0
	s_cmpk_gt_u32 s2, 0xff
	s_cbranch_scc1 .Lalign_a_1396
	s_barrier
.Lalign_a_1396:
	v_mov_b32_e32 v133, v0
	s_lshl_b32 s1, s46, 8
	s_add_i32 s1, s1, s38
	v_and_or_b32 v132, v133, 15, s1
	s_lshl_b32 s1, s45, 8
	v_lshrrev_b32_e32 v133, 1, v133
	v_and_or_b32 v133, v133, 24, s1
	v_or_b32_e32 v134, s39, v133
	v_ashrrev_i32_e32 v135, 31, v134
	v_lshlrev_b64 v[202:203], 1, v[134:135]
	v_ashrrev_i32_e32 v133, 31, v132
	v_lshl_add_u64 v[134:135], s[88:89], 0, v[202:203]
	v_lshlrev_b64 v[216:217], 12, v[132:133]
	v_lshl_add_u64 v[136:137], v[134:135], 0, v[216:217]
	global_load_dwordx4 v[226:229], v[136:137], off
	global_load_dwordx4 v[188:191], v[136:137], off offset:256
	v_or_b32_e32 v136, 16, v132
	v_ashrrev_i32_e32 v137, 31, v136
	v_lshlrev_b64 v[222:223], 12, v[136:137]
	v_lshl_add_u64 v[136:137], v[134:135], 0, v[222:223]
	global_load_dwordx4 v[184:187], v[136:137], off
	global_load_dwordx4 v[180:183], v[136:137], off offset:256
	v_or_b32_e32 v136, 32, v132
	v_ashrrev_i32_e32 v137, 31, v136
	v_lshlrev_b64 v[220:221], 12, v[136:137]
	v_lshl_add_u64 v[136:137], v[134:135], 0, v[220:221]
	global_load_dwordx4 v[176:179], v[136:137], off
	global_load_dwordx4 v[168:171], v[136:137], off offset:256
	v_or_b32_e32 v132, 48, v132
	v_ashrrev_i32_e32 v133, 31, v132
	v_lshlrev_b64 v[212:213], 12, v[132:133]
	v_lshl_add_u64 v[132:133], v[134:135], 0, v[212:213]
	global_load_dwordx4 v[172:175], v[132:133], off
	global_load_dwordx4 v[164:167], v[132:133], off offset:256
	s_mov_b64 s[6:7], 0x80000
	v_lshl_add_u64 v[210:211], v[216:217], 0, s[6:7]
	v_lshl_add_u64 v[132:133], v[134:135], 0, v[210:211]
	global_load_dwordx4 v[160:163], v[132:133], off
	global_load_dwordx4 v[156:159], v[132:133], off offset:256
	s_mov_b64 s[6:7], 0x90000
	v_lshl_add_u64 v[208:209], v[216:217], 0, s[6:7]
	v_lshl_add_u64 v[132:133], v[134:135], 0, v[208:209]
	global_load_dwordx4 v[152:155], v[132:133], off
	global_load_dwordx4 v[148:151], v[132:133], off offset:256
	s_mov_b64 s[6:7], 0xa0000
	v_lshl_add_u64 v[206:207], v[216:217], 0, s[6:7]
	v_lshl_add_u64 v[132:133], v[134:135], 0, v[206:207]
	global_load_dwordx4 v[144:147], v[132:133], off
	global_load_dwordx4 v[140:143], v[132:133], off offset:256
	s_mov_b64 s[6:7], 0xb0000
	v_lshl_add_u64 v[204:205], v[216:217], 0, s[6:7]
	v_lshl_add_u64 v[132:133], v[134:135], 0, v[204:205]
	global_load_dwordx4 v[136:139], v[132:133], off
	s_nop 0
	global_load_dwordx4 v[132:135], v[132:133], off offset:256
	s_and_b64 vcc, exec, s[40:41]
	s_mov_b32 s45, s0
	s_mov_b32 s46, s14
	s_mov_b64 s[20:21], s[18:19]
	s_mov_b64 s[6:7], s[4:5]
	s_waitcnt vmcnt(15)
; __device__ __forceinline__ unsigned cvt_pk_bf16(float lo, float hi) { const f32x2 v = {lo, hi}; const bf16v2_ r = __builtin_convertvector(v, bf16v2_); return __builtin_bit_cast(unsigned, r); }
; __device__ __forceinline__ float bflo(unsigned w) { return __uint_as_float(w << 16); }
; __device__ __forceinline__ float bfhi(unsigned w) { return __uint_as_float(w & 0xffff0000u); }
;     __device__ __forceinline__ void operator()(const f32x4 (&acc)[2][2][4][2], const Unit& u, int wr, int wc, int, int) const {
;     ...
; #pragma unroll
;         for (int ai = 0; ai < 2; ++ai)
; #pragma unroll
;             for (int m = 0; m < 4; ++m)
; #pragma unroll
;                 for (int bj = 0; bj < 2; ++bj) { const u32x4 c = cin[ai][m][bj]; const f32x4 v0 = acc[ai][bj][m][0], v1 = acc[ai][bj][m][1];
;                     u32x4 w; w.x = cvt_pk_bf16(bflo(c.x) + v0[0], bfhi(c.x) + v0[1]); w.y = cvt_pk_bf16(bflo(c.y) + v0[2], bfhi(c.y) + v0[3]);
;                     w.z = cvt_pk_bf16(bflo(c.z) + v1[0], bfhi(c.z) + v1[1]); w.w = cvt_pk_bf16(bflo(c.w) + v1[2], bfhi(c.w) + v1[3]);
;                     *(u32x4*)(C + (size_t)(row0 + ai * HALF + m * 16) * ldc + col0 + bj * HALF) = w; }
	v_lshlrev_b32_e32 v218, 16, v226
	v_and_b32_e32 v219, 0xffff0000, v226
	v_pk_add_f32 v[128:129], v[128:129], v[218:219]
	v_lshlrev_b32_e32 v218, 16, v227
	v_and_b32_e32 v219, 0xffff0000, v227
	v_pk_add_f32 v[130:131], v[130:131], v[218:219]
	v_cvt_pk_bf16_f32 v128, v128, v129
	v_cvt_pk_bf16_f32 v129, v130, v131
	v_lshlrev_b32_e32 v130, 16, v228
	v_and_b32_e32 v131, 0xffff0000, v228
	v_pk_add_f32 v[124:125], v[124:125], v[130:131]
	s_nop 0
	v_cvt_pk_bf16_f32 v130, v124, v125
	v_lshlrev_b32_e32 v124, 16, v229
	v_and_b32_e32 v125, 0xffff0000, v229
	v_pk_add_f32 v[124:125], v[126:127], v[124:125]
	s_waitcnt vmcnt(14)
	v_lshlrev_b32_e32 v126, 16, v188
	v_and_b32_e32 v127, 0xffff0000, v188
	v_pk_add_f32 v[120:121], v[120:121], v[126:127]
	v_lshlrev_b32_e32 v126, 16, v189
	v_and_b32_e32 v127, 0xffff0000, v189
	v_pk_add_f32 v[122:123], v[122:123], v[126:127]
	v_cvt_pk_bf16_f32 v120, v120, v121
	v_cvt_pk_bf16_f32 v121, v122, v123
	v_lshlrev_b32_e32 v122, 16, v190
	v_and_b32_e32 v123, 0xffff0000, v190
	v_pk_add_f32 v[116:117], v[116:117], v[122:123]
	v_cvt_pk_bf16_f32 v131, v124, v125
	v_cvt_pk_bf16_f32 v122, v116, v117
	v_lshlrev_b32_e32 v116, 16, v191
	v_and_b32_e32 v117, 0xffff0000, v191
	v_pk_add_f32 v[116:117], v[118:119], v[116:117]
	v_lshl_add_u64 v[124:125], s[88:89], 0, v[216:217]
	v_cvt_pk_bf16_f32 v123, v116, v117
	s_waitcnt vmcnt(13)
	v_lshlrev_b32_e32 v116, 16, v184
	v_and_b32_e32 v117, 0xffff0000, v184
	v_pk_add_f32 v[112:113], v[112:113], v[116:117]
	v_lshlrev_b32_e32 v116, 16, v185
	v_and_b32_e32 v117, 0xffff0000, v185
	v_pk_add_f32 v[114:115], v[114:115], v[116:117]
	v_cvt_pk_bf16_f32 v112, v112, v113
	v_cvt_pk_bf16_f32 v113, v114, v115
	v_lshlrev_b32_e32 v114, 16, v186
	v_and_b32_e32 v115, 0xffff0000, v186
	v_pk_add_f32 v[108:109], v[108:109], v[114:115]
	v_lshl_add_u64 v[124:125], v[124:125], 0, v[202:203]
	v_cvt_pk_bf16_f32 v114, v108, v109
	v_lshlrev_b32_e32 v108, 16, v187
	v_and_b32_e32 v109, 0xffff0000, v187
	v_pk_add_f32 v[108:109], v[110:111], v[108:109]
	s_waitcnt vmcnt(12)
	v_lshlrev_b32_e32 v110, 16, v180
	v_and_b32_e32 v111, 0xffff0000, v180
	v_pk_add_f32 v[104:105], v[104:105], v[110:111]
	v_lshlrev_b32_e32 v110, 16, v181
	v_and_b32_e32 v111, 0xffff0000, v181
	v_pk_add_f32 v[106:107], v[106:107], v[110:111]
	v_cvt_pk_bf16_f32 v104, v104, v105
	v_cvt_pk_bf16_f32 v105, v106, v107
	v_lshlrev_b32_e32 v106, 16, v182
	v_and_b32_e32 v107, 0xffff0000, v182
	v_pk_add_f32 v[96:97], v[96:97], v[106:107]
	v_cvt_pk_bf16_f32 v115, v108, v109
	v_cvt_pk_bf16_f32 v106, v96, v97
	v_lshlrev_b32_e32 v96, 16, v183
	v_and_b32_e32 v97, 0xffff0000, v183
	v_pk_add_f32 v[96:97], v[98:99], v[96:97]
	s_waitcnt vmcnt(11)
	v_lshlrev_b32_e32 v98, 16, v177
	v_cvt_pk_bf16_f32 v107, v96, v97
	v_lshlrev_b32_e32 v96, 16, v176
	v_and_b32_e32 v97, 0xffff0000, v176
	v_and_b32_e32 v99, 0xffff0000, v177
	v_pk_add_f32 v[96:97], v[100:101], v[96:97]
	v_pk_add_f32 v[98:99], v[102:103], v[98:99]
	v_cvt_pk_bf16_f32 v96, v96, v97
	v_cvt_pk_bf16_f32 v97, v98, v99
	v_lshlrev_b32_e32 v98, 16, v178
	v_and_b32_e32 v99, 0xffff0000, v178
	v_pk_add_f32 v[92:93], v[92:93], v[98:99]
	v_lshl_add_u64 v[108:109], s[88:89], 0, v[222:223]
	v_cvt_pk_bf16_f32 v98, v92, v93
	v_lshlrev_b32_e32 v92, 16, v179
	v_and_b32_e32 v93, 0xffff0000, v179
	v_pk_add_f32 v[92:93], v[94:95], v[92:93]
	s_waitcnt vmcnt(10)
	v_lshlrev_b32_e32 v94, 16, v168
	v_and_b32_e32 v95, 0xffff0000, v168
	v_pk_add_f32 v[88:89], v[88:89], v[94:95]
	v_lshlrev_b32_e32 v94, 16, v169
	v_and_b32_e32 v95, 0xffff0000, v169
	v_pk_add_f32 v[90:91], v[90:91], v[94:95]
	v_cvt_pk_bf16_f32 v88, v88, v89
	v_cvt_pk_bf16_f32 v89, v90, v91
	v_lshlrev_b32_e32 v90, 16, v170
	v_and_b32_e32 v91, 0xffff0000, v170
	v_pk_add_f32 v[80:81], v[80:81], v[90:91]
	v_cvt_pk_bf16_f32 v99, v92, v93
	v_cvt_pk_bf16_f32 v90, v80, v81
	v_lshlrev_b32_e32 v80, 16, v171
	v_and_b32_e32 v81, 0xffff0000, v171
	v_pk_add_f32 v[80:81], v[82:83], v[80:81]
	s_waitcnt vmcnt(9)
	v_lshlrev_b32_e32 v82, 16, v173
	v_cvt_pk_bf16_f32 v91, v80, v81
	v_lshlrev_b32_e32 v80, 16, v172
	v_and_b32_e32 v81, 0xffff0000, v172
	v_and_b32_e32 v83, 0xffff0000, v173
	v_pk_add_f32 v[80:81], v[84:85], v[80:81]
	v_pk_add_f32 v[82:83], v[86:87], v[82:83]
	v_cvt_pk_bf16_f32 v80, v80, v81
	v_cvt_pk_bf16_f32 v81, v82, v83
	v_lshlrev_b32_e32 v82, 16, v174
	v_and_b32_e32 v83, 0xffff0000, v174
	v_pk_add_f32 v[76:77], v[76:77], v[82:83]
	v_lshl_add_u64 v[92:93], s[88:89], 0, v[220:221]
	v_cvt_pk_bf16_f32 v82, v76, v77
	v_lshlrev_b32_e32 v76, 16, v175
	v_and_b32_e32 v77, 0xffff0000, v175
	v_pk_add_f32 v[76:77], v[78:79], v[76:77]
	s_waitcnt vmcnt(8)
	v_lshlrev_b32_e32 v78, 16, v164
	v_and_b32_e32 v79, 0xffff0000, v164
	v_pk_add_f32 v[72:73], v[72:73], v[78:79]
	v_lshlrev_b32_e32 v78, 16, v165
	v_and_b32_e32 v79, 0xffff0000, v165
	v_pk_add_f32 v[74:75], v[74:75], v[78:79]
	v_cvt_pk_bf16_f32 v72, v72, v73
	v_cvt_pk_bf16_f32 v73, v74, v75
	v_lshlrev_b32_e32 v74, 16, v166
	v_and_b32_e32 v75, 0xffff0000, v166
	v_pk_add_f32 v[68:69], v[68:69], v[74:75]
	v_cvt_pk_bf16_f32 v83, v76, v77
	v_cvt_pk_bf16_f32 v74, v68, v69
	v_lshlrev_b32_e32 v68, 16, v167
	v_and_b32_e32 v69, 0xffff0000, v167
	v_pk_add_f32 v[68:69], v[70:71], v[68:69]
	v_lshl_add_u64 v[76:77], s[88:89], 0, v[212:213]
	v_cvt_pk_bf16_f32 v75, v68, v69
	s_waitcnt vmcnt(7)
	v_lshlrev_b32_e32 v68, 16, v160
	v_and_b32_e32 v69, 0xffff0000, v160
	v_pk_add_f32 v[64:65], v[64:65], v[68:69]
	v_lshlrev_b32_e32 v68, 16, v161
	v_and_b32_e32 v69, 0xffff0000, v161
	v_pk_add_f32 v[66:67], v[66:67], v[68:69]
	v_cvt_pk_bf16_f32 v64, v64, v65
	v_cvt_pk_bf16_f32 v65, v66, v67
	v_lshlrev_b32_e32 v66, 16, v162
	v_and_b32_e32 v67, 0xffff0000, v162
	v_pk_add_f32 v[60:61], v[60:61], v[66:67]
	v_lshl_add_u64 v[108:109], v[108:109], 0, v[202:203]
	v_cvt_pk_bf16_f32 v66, v60, v61
	v_lshlrev_b32_e32 v60, 16, v163
	v_and_b32_e32 v61, 0xffff0000, v163
	v_pk_add_f32 v[60:61], v[62:63], v[60:61]
	s_waitcnt vmcnt(6)
; __device__ __forceinline__ unsigned cvt_pk_bf16(float lo, float hi) { const f32x2 v = {lo, hi}; const bf16v2_ r = __builtin_convertvector(v, bf16v2_); return __builtin_bit_cast(unsigned, r); }
; __device__ __forceinline__ float bflo(unsigned w) { return __uint_as_float(w << 16); }
; __device__ __forceinline__ float bfhi(unsigned w) { return __uint_as_float(w & 0xffff0000u); }
;     __device__ __forceinline__ void operator()(const f32x4 (&acc)[2][2][4][2], const Unit& u, int wr, int wc, int, int) const {
;     ...
; #pragma unroll
;         for (int ai = 0; ai < 2; ++ai)
; #pragma unroll
;             for (int m = 0; m < 4; ++m)
; #pragma unroll
;                 for (int bj = 0; bj < 2; ++bj) { const u32x4 c = cin[ai][m][bj]; const f32x4 v0 = acc[ai][bj][m][0], v1 = acc[ai][bj][m][1];
;                     u32x4 w; w.x = cvt_pk_bf16(bflo(c.x) + v0[0], bfhi(c.x) + v0[1]); w.y = cvt_pk_bf16(bflo(c.y) + v0[2], bfhi(c.y) + v0[3]);
;                     w.z = cvt_pk_bf16(bflo(c.z) + v1[0], bfhi(c.z) + v1[1]); w.w = cvt_pk_bf16(bflo(c.w) + v1[2], bfhi(c.w) + v1[3]);
;                     *(u32x4*)(C + (size_t)(row0 + ai * HALF + m * 16) * ldc + col0 + bj * HALF) = w; }
	v_lshlrev_b32_e32 v62, 16, v156
	v_and_b32_e32 v63, 0xffff0000, v156
	v_pk_add_f32 v[56:57], v[56:57], v[62:63]
	v_lshlrev_b32_e32 v62, 16, v157
	v_and_b32_e32 v63, 0xffff0000, v157
	v_pk_add_f32 v[58:59], v[58:59], v[62:63]
	v_cvt_pk_bf16_f32 v56, v56, v57
	v_cvt_pk_bf16_f32 v57, v58, v59
	v_lshlrev_b32_e32 v58, 16, v158
	v_and_b32_e32 v59, 0xffff0000, v158
	v_pk_add_f32 v[48:49], v[48:49], v[58:59]
	v_cvt_pk_bf16_f32 v67, v60, v61
	v_cvt_pk_bf16_f32 v58, v48, v49
	v_lshlrev_b32_e32 v48, 16, v159
	v_and_b32_e32 v49, 0xffff0000, v159
	v_pk_add_f32 v[48:49], v[50:51], v[48:49]
	s_waitcnt vmcnt(5)
	v_lshlrev_b32_e32 v50, 16, v153
	v_cvt_pk_bf16_f32 v59, v48, v49
	v_lshlrev_b32_e32 v48, 16, v152
	v_and_b32_e32 v49, 0xffff0000, v152
	v_and_b32_e32 v51, 0xffff0000, v153
	v_pk_add_f32 v[48:49], v[52:53], v[48:49]
	v_pk_add_f32 v[50:51], v[54:55], v[50:51]
	v_cvt_pk_bf16_f32 v48, v48, v49
	v_cvt_pk_bf16_f32 v49, v50, v51
	v_lshlrev_b32_e32 v50, 16, v154
	v_and_b32_e32 v51, 0xffff0000, v154
	v_pk_add_f32 v[44:45], v[44:45], v[50:51]
	v_lshl_add_u64 v[60:61], s[88:89], 0, v[210:211]
	v_cvt_pk_bf16_f32 v50, v44, v45
	v_lshlrev_b32_e32 v44, 16, v155
	v_and_b32_e32 v45, 0xffff0000, v155
	v_pk_add_f32 v[44:45], v[46:47], v[44:45]
	s_waitcnt vmcnt(4)
	v_lshlrev_b32_e32 v46, 16, v148
	v_and_b32_e32 v47, 0xffff0000, v148
	v_pk_add_f32 v[40:41], v[40:41], v[46:47]
	v_lshlrev_b32_e32 v46, 16, v149
	v_and_b32_e32 v47, 0xffff0000, v149
	v_pk_add_f32 v[42:43], v[42:43], v[46:47]
	v_cvt_pk_bf16_f32 v40, v40, v41
	v_cvt_pk_bf16_f32 v41, v42, v43
	v_lshlrev_b32_e32 v42, 16, v150
	v_and_b32_e32 v43, 0xffff0000, v150
	v_pk_add_f32 v[32:33], v[32:33], v[42:43]
	v_cvt_pk_bf16_f32 v51, v44, v45
	v_cvt_pk_bf16_f32 v42, v32, v33
	v_lshlrev_b32_e32 v32, 16, v151
	v_and_b32_e32 v33, 0xffff0000, v151
	v_pk_add_f32 v[32:33], v[34:35], v[32:33]
	s_waitcnt vmcnt(3)
	v_lshlrev_b32_e32 v34, 16, v145
	v_cvt_pk_bf16_f32 v43, v32, v33
	v_lshlrev_b32_e32 v32, 16, v144
	v_and_b32_e32 v33, 0xffff0000, v144
	v_and_b32_e32 v35, 0xffff0000, v145
	v_pk_add_f32 v[32:33], v[36:37], v[32:33]
	v_pk_add_f32 v[34:35], v[38:39], v[34:35]
	v_cvt_pk_bf16_f32 v32, v32, v33
	v_cvt_pk_bf16_f32 v33, v34, v35
	v_lshlrev_b32_e32 v34, 16, v146
	v_and_b32_e32 v35, 0xffff0000, v146
	v_pk_add_f32 v[28:29], v[28:29], v[34:35]
	v_lshl_add_u64 v[44:45], s[88:89], 0, v[208:209]
	v_cvt_pk_bf16_f32 v34, v28, v29
	v_lshlrev_b32_e32 v28, 16, v147
	v_and_b32_e32 v29, 0xffff0000, v147
	v_pk_add_f32 v[28:29], v[30:31], v[28:29]
	s_waitcnt vmcnt(2)
	v_lshlrev_b32_e32 v30, 16, v140
	v_and_b32_e32 v31, 0xffff0000, v140
	v_pk_add_f32 v[24:25], v[24:25], v[30:31]
	v_lshlrev_b32_e32 v30, 16, v141
	v_and_b32_e32 v31, 0xffff0000, v141
	v_pk_add_f32 v[26:27], v[26:27], v[30:31]
	v_cvt_pk_bf16_f32 v24, v24, v25
	v_cvt_pk_bf16_f32 v25, v26, v27
	v_lshlrev_b32_e32 v26, 16, v142
	v_and_b32_e32 v27, 0xffff0000, v142
	v_pk_add_f32 v[16:17], v[16:17], v[26:27]
	v_cvt_pk_bf16_f32 v35, v28, v29
	v_cvt_pk_bf16_f32 v26, v16, v17
	v_lshlrev_b32_e32 v16, 16, v143
	v_and_b32_e32 v17, 0xffff0000, v143
	v_pk_add_f32 v[16:17], v[18:19], v[16:17]
	s_waitcnt vmcnt(1)
	v_lshlrev_b32_e32 v18, 16, v137
	v_cvt_pk_bf16_f32 v27, v16, v17
	v_lshlrev_b32_e32 v16, 16, v136
	v_and_b32_e32 v17, 0xffff0000, v136
	v_and_b32_e32 v19, 0xffff0000, v137
	v_pk_add_f32 v[16:17], v[20:21], v[16:17]
	v_pk_add_f32 v[18:19], v[22:23], v[18:19]
	v_cvt_pk_bf16_f32 v16, v16, v17
	v_cvt_pk_bf16_f32 v17, v18, v19
	v_lshlrev_b32_e32 v18, 16, v138
	v_and_b32_e32 v19, 0xffff0000, v138
	v_pk_add_f32 v[12:13], v[12:13], v[18:19]
	v_lshl_add_u64 v[28:29], s[88:89], 0, v[206:207]
	v_cvt_pk_bf16_f32 v18, v12, v13
	v_lshlrev_b32_e32 v12, 16, v139
	v_and_b32_e32 v13, 0xffff0000, v139
	v_pk_add_f32 v[12:13], v[14:15], v[12:13]
	s_waitcnt vmcnt(0)
	v_lshlrev_b32_e32 v14, 16, v132
	v_and_b32_e32 v15, 0xffff0000, v132
	v_pk_add_f32 v[8:9], v[8:9], v[14:15]
	v_lshlrev_b32_e32 v14, 16, v133
	v_and_b32_e32 v15, 0xffff0000, v133
	v_pk_add_f32 v[10:11], v[10:11], v[14:15]
	v_cvt_pk_bf16_f32 v8, v8, v9
	v_cvt_pk_bf16_f32 v9, v10, v11
	v_lshlrev_b32_e32 v10, 16, v134
	v_and_b32_e32 v11, 0xffff0000, v134
	v_pk_add_f32 v[4:5], v[4:5], v[10:11]
	v_cvt_pk_bf16_f32 v19, v12, v13
	v_cvt_pk_bf16_f32 v10, v4, v5
	v_lshlrev_b32_e32 v4, 16, v135
	v_and_b32_e32 v5, 0xffff0000, v135
	v_lshl_add_u64 v[12:13], s[88:89], 0, v[204:205]
	v_pk_add_f32 v[4:5], v[6:7], v[4:5]
	v_lshl_add_u64 v[92:93], v[92:93], 0, v[202:203]
	v_lshl_add_u64 v[76:77], v[76:77], 0, v[202:203]
	v_lshl_add_u64 v[60:61], v[60:61], 0, v[202:203]
	v_lshl_add_u64 v[44:45], v[44:45], 0, v[202:203]
	v_lshl_add_u64 v[28:29], v[28:29], 0, v[202:203]
	v_lshl_add_u64 v[12:13], v[12:13], 0, v[202:203]
	v_cvt_pk_bf16_f32 v11, v4, v5
	global_store_dwordx4 v[124:125], v[128:131], off
	global_store_dwordx4 v[124:125], v[120:123], off offset:256
	global_store_dwordx4 v[108:109], v[112:115], off
	global_store_dwordx4 v[108:109], v[104:107], off offset:256
	global_store_dwordx4 v[92:93], v[96:99], off
	global_store_dwordx4 v[92:93], v[88:91], off offset:256
	global_store_dwordx4 v[76:77], v[80:83], off
	global_store_dwordx4 v[76:77], v[72:75], off offset:256
	global_store_dwordx4 v[60:61], v[64:67], off
	global_store_dwordx4 v[60:61], v[56:59], off offset:256
	global_store_dwordx4 v[44:45], v[48:51], off
	global_store_dwordx4 v[44:45], v[40:43], off offset:256
	global_store_dwordx4 v[28:29], v[32:35], off
	global_store_dwordx4 v[28:29], v[24:27], off offset:256
	global_store_dwordx4 v[12:13], v[16:19], off
	global_store_dwordx4 v[12:13], v[8:11], off offset:256
	s_cmpk_lt_u32 s2, 0x100
	s_cbranch_scc1 .Lalign_b_1396
	s_barrier

;     __device__ __forceinline__ void operator()(f32x4 (&acc)[2][2][4][2], const Unit& u, int wr, int wc, int ui, int) const {
;     ...
;         if (wr == 0 && fr < 2) { float* hg = headg + ((size_t)u.pm * 2 + fr) * FF + col; *(f32x4*)hg = acc[0][1][0][0]; *(f32x4*)(hg + 4) = acc[0][1][0][1];
;                                  float* hu = headu + ((size_t)u.pm * 2 + fr) * FF + col; *(f32x4*)hu = acc[0][0][0][0]; *(f32x4*)(hu + 4) = acc[0][0][0][1]; }
; template <class Epi, class Sched>
; __device__ __forceinline__ void gemm_phase(LAS unsigned char* lds, const Gemm g, const Sched& S, const Epi& E) {
;     ...
;         E(acc, cur, wr, wc, ui, fq);
;         S.done(cur);
;         if (!has_next) break;
.LBB0_1520:
	s_or_b64 exec, exec, s[4:5]
	s_andn2_b64 vcc, exec, s[44:45]
	s_cbranch_vccnz .Lalign_b_1526
	s_barrier
.Lalign_b_1526:
	s_and_b64 vcc, exec, s[40:41]
	s_mov_b32 s53, s54
	s_mov_b32 s52, s56
	s_mov_b64 s[6:7], s[60:61]
	s_mov_b64 s[4:5], s[58:59]
	s_mov_b32 s66, s65
	s_cbranch_vccnz .LBB0_1537

; #define PG8_STAGE(bufoff, gbase, voff) do { _Pragma("unroll") for (int _i = 0; _i < 2; ++_i) \
;         __builtin_amdgcn_global_load_lds((const unsigned*)((const char*)(gbase) + (voff)[_i]), (LAS unsigned*)(lds + (bufoff) + ldsw + _i * 8192), 16, 0, 0); } while (0)
; #define PG8_LDA(dst, b, h) do { _Pragma("unroll") for (int m = 0; m < 4; ++m) _Pragma("unroll") for (int k = 0; k < 2; ++k) dst[m][k] = *(const LAS bf16x8*)(lds + PG8_SA(b, h) + aoff + m * 2048 + k * 1024); } while (0)
; #define PG8_LDB(dst, b, h) do { _Pragma("unroll") for (int n = 0; n < 2; ++n) _Pragma("unroll") for (int k = 0; k < 2; ++k) dst[n][k] = *(const LAS bf16x8*)(lds + PG8_SB(b, h) + boff + n * 2048 + k * 1024); } while (0)
; #define PG8_MMA(ai, bj, At, Bt) do { __builtin_amdgcn_s_setprio(1); _Pragma("unroll") for (int m = 0; m < 4; ++m) _Pragma("unroll") for (int n = 0; n < 2; ++n) _Pragma("unroll") for (int k = 0; k < 2; ++k) \
;         acc[ai][bj][m][n] = __builtin_amdgcn_mfma_f32_16x16x32_bf16(Bt[n][k], At[m][k], acc[ai][bj][m][n], 0, 0, 0); __builtin_amdgcn_s_setprio(0); } while (0)
; #define PG8_WAIT_V(n) asm volatile("s_waitcnt vmcnt(" #n ")" ::: "memory")
; #define PG8_WAIT_L(n) asm volatile("s_waitcnt lgkmcnt(" #n ")" ::: "memory")
; #define PG8_BAR __builtin_amdgcn_s_barrier()
; #define PG8_SCHED __builtin_amdgcn_sched_barrier(0)
; template <class Epi, class Sched>
; __device__ __forceinline__ void gemm_phase(LAS unsigned char* lds, const Gemm g, const Sched& S, const Epi& E) {
;     ...
;             PG8_LDB(B0, 0, 0); PG8_SCHED; PG8_LDA(At, 0, 0); PG8_STAGE(PG8_SA(1, 1), a1 + hstepA, voffA);
;             PG8_WAIT_L(8); PG8_BAR; PG8_WAIT_L(0); PG8_MMA(0, 0, At, B0); PG8_BAR; PG8_SCHED;
;             PG8_LDB(B1, 0, 1); PG8_STAGE(PG8_SB(0, 0), b2, voffB);
;             PG8_BAR; PG8_WAIT_L(0); PG8_MMA(0, 1, At, B1); PG8_BAR;
;             PG8_LDA(At, 0, 1); PG8_STAGE(PG8_SA(0, 0), a2, voffA);
;             PG8_BAR; PG8_WAIT_L(0); PG8_MMA(1, 0, At, B0); PG8_BAR; PG8_SCHED;
;             PG8_STAGE(PG8_SB(0, 1), b2 + hstepB, voffB);
;             PG8_WAIT_V(6); PG8_BAR; PG8_MMA(1, 1, At, B1); PG8_BAR;
.LBB0_1526:
	s_setprio 0
	s_add_u32 s6, s4, 0xfff80080
	s_addc_u32 s7, s5, -1
	s_add_i32 s72, 0, 0x10000
	v_add_u32_e32 v2, s72, v1
	ds_read_b128 v[132:135], v2
	ds_read_b128 v[136:139], v2 offset:1024
	ds_read_b128 v[140:143], v2 offset:2048
	ds_read_b128 v[144:147], v2 offset:3072
	s_cmp_eq_u32 s71, 28
	s_cselect_b32 s15, s57, s7
	s_cselect_b32 s14, s67, s6
	s_cselect_b32 s7, s55, s70
	s_cselect_b32 s6, s68, s69
	ds_read_b128 v[148:151], v207
	ds_read_b128 v[152:155], v207 offset:1024
	ds_read_b128 v[156:159], v207 offset:2048
	ds_read_b128 v[160:163], v207 offset:3072
	ds_read_b128 v[164:167], v207 offset:4096
	ds_read_b128 v[168:171], v207 offset:5120
	ds_read_b128 v[186:189], v207 offset:6144
	ds_read_b128 v[190:193], v207 offset:7168
	s_add_i32 s74, 0, 0x14000
	v_add_u32_e32 v2, s74, v1
	ds_read_b128 v[194:197], v2
	ds_read_b128 v[198:201], v2 offset:1024
	ds_read_b128 v[202:205], v2 offset:2048
	ds_read_b128 v[208:211], v2 offset:3072
	s_add_i32 m0, s20, 0xc000
	s_nop 0
	global_load_lds_dwordx4 v182, s[4:5]
	s_add_i32 m0, s20, 0xe000
	s_nop 0
	global_load_lds_dwordx4 v184, s[4:5]
	s_waitcnt lgkmcnt(0)
	s_setprio 1
	s_barrier
	v_mfma_f32_16x16x32_bf16 v[68:71], v[132:135], v[148:151], v[68:71]
	v_mfma_f32_16x16x32_bf16 v[72:75], v[140:143], v[148:151], v[72:75]
	v_mfma_f32_16x16x32_bf16 v[120:123], v[132:135], v[156:159], v[120:123]
	v_mfma_f32_16x16x32_bf16 v[116:119], v[140:143], v[156:159], v[116:119]
	v_mfma_f32_16x16x32_bf16 v[112:115], v[132:135], v[164:167], v[112:115]
	v_mfma_f32_16x16x32_bf16 v[108:111], v[140:143], v[164:167], v[108:111]
	v_mfma_f32_16x16x32_bf16 v[104:107], v[132:135], v[186:189], v[104:107]
	v_mfma_f32_16x16x32_bf16 v[100:103], v[140:143], v[186:189], v[100:103]
	v_mfma_f32_16x16x32_bf16 v[68:71], v[136:139], v[152:155], v[68:71]
	v_mfma_f32_16x16x32_bf16 v[72:75], v[144:147], v[152:155], v[72:75]
	v_mfma_f32_16x16x32_bf16 v[120:123], v[136:139], v[160:163], v[120:123]
	v_mfma_f32_16x16x32_bf16 v[116:119], v[144:147], v[160:163], v[116:119]
	v_mfma_f32_16x16x32_bf16 v[112:115], v[136:139], v[168:171], v[112:115]
	v_mfma_f32_16x16x32_bf16 v[108:111], v[144:147], v[168:171], v[108:111]
	v_mfma_f32_16x16x32_bf16 v[104:107], v[136:139], v[190:193], v[104:107]
	v_mfma_f32_16x16x32_bf16 v[100:103], v[144:147], v[190:193], v[100:103]
	v_mfma_f32_16x16x32_bf16 v[76:79], v[194:197], v[148:151], v[76:79]
	v_mfma_f32_16x16x32_bf16 v[80:83], v[202:205], v[148:151], v[80:83]
	v_mfma_f32_16x16x32_bf16 v[96:99], v[194:197], v[156:159], v[96:99]
	v_mfma_f32_16x16x32_bf16 v[92:95], v[202:205], v[156:159], v[92:95]
	v_mfma_f32_16x16x32_bf16 v[88:91], v[194:197], v[164:167], v[88:91]
	v_mfma_f32_16x16x32_bf16 v[84:87], v[202:205], v[164:167], v[84:87]
	v_mfma_f32_16x16x32_bf16 v[128:131], v[194:197], v[186:189], v[128:131]
	v_mfma_f32_16x16x32_bf16 v[124:127], v[202:205], v[186:189], v[124:127]
	v_mfma_f32_16x16x32_bf16 v[76:79], v[198:201], v[152:155], v[76:79]
	v_mfma_f32_16x16x32_bf16 v[80:83], v[208:211], v[152:155], v[80:83]
	v_mfma_f32_16x16x32_bf16 v[96:99], v[198:201], v[160:163], v[96:99]
	v_mfma_f32_16x16x32_bf16 v[92:95], v[208:211], v[160:163], v[92:95]
	v_mfma_f32_16x16x32_bf16 v[88:91], v[198:201], v[168:171], v[88:91]
	v_mfma_f32_16x16x32_bf16 v[84:87], v[208:211], v[168:171], v[84:87]
	v_mfma_f32_16x16x32_bf16 v[128:131], v[198:201], v[190:193], v[128:131]
	v_mfma_f32_16x16x32_bf16 v[124:127], v[208:211], v[190:193], v[124:127]
	s_barrier
	s_setprio 0
	ds_read_b128 v[148:151], v207 offset:16384
	ds_read_b128 v[152:155], v207 offset:17408
	ds_read_b128 v[156:159], v207 offset:18432
	ds_read_b128 v[160:163], v207 offset:19456
	ds_read_b128 v[164:167], v207 offset:20480
	ds_read_b128 v[168:171], v207 offset:21504
	ds_read_b128 v[186:189], v207 offset:22528
	ds_read_b128 v[190:193], v207 offset:23552
	s_add_i32 s72, s72, s19
	v_lshl_add_u64 v[172:173], s[6:7], 0, v[178:179]
	s_mov_b32 m0, s72
	s_nop 0
	global_load_lds_dwordx4 v[172:173], off
	v_lshl_add_u64 v[212:213], s[6:7], 0, v[174:175]
	s_add_i32 m0, s72, 0x2000
	s_nop 0
	global_load_lds_dwordx4 v[212:213], off
	s_mov_b32 m0, s20
	v_lshl_add_u64 v[216:217], s[14:15], 0, v[180:181]
	global_load_lds_dwordx4 v[216:217], off
	v_lshl_add_u64 v[218:219], s[14:15], 0, v[176:177]
	s_mov_b32 m0, s21
	s_nop 0
	global_load_lds_dwordx4 v[218:219], off
	s_add_u32 s72, s6, 0x80000
	s_addc_u32 s73, s7, 0
	s_add_i32 s74, s74, s19
	s_mov_b32 m0, s74
	s_nop 0
	global_load_lds_dwordx4 v178, s[72:73]
	s_add_i32 m0, s74, 0x2000
	s_nop 0
	global_load_lds_dwordx4 v174, s[72:73]
	s_waitcnt lgkmcnt(0)
	s_waitcnt vmcnt(6)
	s_setprio 1
	s_barrier
; #define PG8_STAGE(bufoff, gbase, voff) do { _Pragma("unroll") for (int _i = 0; _i < 2; ++_i) \
;         __builtin_amdgcn_global_load_lds((const unsigned*)((const char*)(gbase) + (voff)[_i]), (LAS unsigned*)(lds + (bufoff) + ldsw + _i * 8192), 16, 0, 0); } while (0)
; #define PG8_LDA(dst, b, h) do { _Pragma("unroll") for (int m = 0; m < 4; ++m) _Pragma("unroll") for (int k = 0; k < 2; ++k) dst[m][k] = *(const LAS bf16x8*)(lds + PG8_SA(b, h) + aoff + m * 2048 + k * 1024); } while (0)
; #define PG8_LDB(dst, b, h) do { _Pragma("unroll") for (int n = 0; n < 2; ++n) _Pragma("unroll") for (int k = 0; k < 2; ++k) dst[n][k] = *(const LAS bf16x8*)(lds + PG8_SB(b, h) + boff + n * 2048 + k * 1024); } while (0)
; #define PG8_MMA(ai, bj, At, Bt) do { __builtin_amdgcn_s_setprio(1); _Pragma("unroll") for (int m = 0; m < 4; ++m) _Pragma("unroll") for (int n = 0; n < 2; ++n) _Pragma("unroll") for (int k = 0; k < 2; ++k) \
;         acc[ai][bj][m][n] = __builtin_amdgcn_mfma_f32_16x16x32_bf16(Bt[n][k], At[m][k], acc[ai][bj][m][n], 0, 0, 0); __builtin_amdgcn_s_setprio(0); } while (0)
; #define PG8_WAIT_V(n) asm volatile("s_waitcnt vmcnt(" #n ")" ::: "memory")
; #define PG8_WAIT_L(n) asm volatile("s_waitcnt lgkmcnt(" #n ")" ::: "memory")
; #define PG8_BAR __builtin_amdgcn_s_barrier()
; #define PG8_SCHED __builtin_amdgcn_sched_barrier(0)
; template <class Epi, class Sched>
; __device__ __forceinline__ void gemm_phase(LAS unsigned char* lds, const Gemm g, const Sched& S, const Epi& E) {
;     ...
;             PG8_WAIT_V(6); PG8_BAR; PG8_MMA(1, 1, At, B1); PG8_BAR;
;             PG8_LDB(B0, 1, 0); PG8_SCHED; PG8_LDA(At, 1, 0); PG8_STAGE(PG8_SA(0, 1), a2 + hstepA, voffA);
;             PG8_WAIT_L(8); PG8_BAR; PG8_WAIT_L(0); PG8_MMA(0, 0, At, B0); PG8_BAR; PG8_SCHED;
;             PG8_LDB(B1, 1, 1); PG8_STAGE(PG8_SB(1, 0), b3, voffB);
;             PG8_BAR; PG8_WAIT_L(0); PG8_MMA(0, 1, At, B1); PG8_BAR;
;             PG8_LDA(At, 1, 1); PG8_STAGE(PG8_SA(1, 0), a3, voffA);
;             PG8_BAR; PG8_WAIT_L(0); PG8_MMA(1, 0, At, B0); PG8_BAR; PG8_SCHED;
	v_mfma_f32_16x16x32_bf16 v[56:59], v[132:135], v[148:151], v[56:59]
	v_mfma_f32_16x16x32_bf16 v[52:55], v[140:143], v[148:151], v[52:55]
	v_mfma_f32_16x16x32_bf16 v[48:51], v[132:135], v[156:159], v[48:51]
	v_mfma_f32_16x16x32_bf16 v[44:47], v[140:143], v[156:159], v[44:47]
	v_mfma_f32_16x16x32_bf16 v[40:43], v[132:135], v[164:167], v[40:43]
	v_mfma_f32_16x16x32_bf16 v[36:39], v[140:143], v[164:167], v[36:39]
	v_mfma_f32_16x16x32_bf16 v[32:35], v[132:135], v[186:189], v[32:35]
	v_mfma_f32_16x16x32_bf16 v[28:31], v[140:143], v[186:189], v[28:31]
	v_mfma_f32_16x16x32_bf16 v[56:59], v[136:139], v[152:155], v[56:59]
	v_mfma_f32_16x16x32_bf16 v[52:55], v[144:147], v[152:155], v[52:55]
	v_mfma_f32_16x16x32_bf16 v[48:51], v[136:139], v[160:163], v[48:51]
	v_mfma_f32_16x16x32_bf16 v[44:47], v[144:147], v[160:163], v[44:47]
	v_mfma_f32_16x16x32_bf16 v[40:43], v[136:139], v[168:171], v[40:43]
	v_mfma_f32_16x16x32_bf16 v[36:39], v[144:147], v[168:171], v[36:39]
	v_mfma_f32_16x16x32_bf16 v[32:35], v[136:139], v[190:193], v[32:35]
	v_mfma_f32_16x16x32_bf16 v[28:31], v[144:147], v[190:193], v[28:31]
	v_mfma_f32_16x16x32_bf16 v[24:27], v[194:197], v[148:151], v[24:27]
	v_mfma_f32_16x16x32_bf16 v[20:23], v[202:205], v[148:151], v[20:23]
	v_mfma_f32_16x16x32_bf16 v[16:19], v[194:197], v[156:159], v[16:19]
	v_mfma_f32_16x16x32_bf16 v[12:15], v[202:205], v[156:159], v[12:15]
	v_mfma_f32_16x16x32_bf16 v[8:11], v[194:197], v[164:167], v[8:11]
	v_mfma_f32_16x16x32_bf16 v[4:7], v[202:205], v[164:167], v[4:7]
	v_mfma_f32_16x16x32_bf16 v[60:63], v[194:197], v[186:189], v[60:63]
	v_mfma_f32_16x16x32_bf16 v[64:67], v[202:205], v[186:189], v[64:67]
	v_mfma_f32_16x16x32_bf16 v[24:27], v[198:201], v[152:155], v[24:27]
	v_mfma_f32_16x16x32_bf16 v[20:23], v[208:211], v[152:155], v[20:23]
	v_mfma_f32_16x16x32_bf16 v[16:19], v[198:201], v[160:163], v[16:19]
	v_mfma_f32_16x16x32_bf16 v[12:15], v[208:211], v[160:163], v[12:15]
	v_mfma_f32_16x16x32_bf16 v[8:11], v[198:201], v[168:171], v[8:11]
	v_mfma_f32_16x16x32_bf16 v[4:7], v[208:211], v[168:171], v[4:7]
	v_mfma_f32_16x16x32_bf16 v[60:63], v[198:201], v[190:193], v[60:63]
	v_mfma_f32_16x16x32_bf16 v[64:67], v[208:211], v[190:193], v[64:67]
	s_barrier
	s_setprio 0
	s_add_i32 s72, 0, 0x18000
	v_add_u32_e32 v2, s72, v1
	ds_read_b128 v[132:135], v2
	ds_read_b128 v[136:139], v2 offset:1024
	ds_read_b128 v[140:143], v2 offset:2048
	ds_read_b128 v[144:147], v2 offset:3072
	s_add_u32 s14, s14, 0x80000
	s_addc_u32 s15, s15, 0
	ds_read_b128 v[148:151], v207 offset:32768
	ds_read_b128 v[152:155], v207 offset:33792
	ds_read_b128 v[156:159], v207 offset:34816
	ds_read_b128 v[160:163], v207 offset:35840
	ds_read_b128 v[164:167], v207 offset:36864
	ds_read_b128 v[168:171], v207 offset:37888
	ds_read_b128 v[186:189], v207 offset:38912
	ds_read_b128 v[190:193], v207 offset:39936
	s_mov_b32 m0, s24
	s_nop 0
	global_load_lds_dwordx4 v180, s[14:15]
	s_mov_b32 m0, s25
	s_nop 0
	global_load_lds_dwordx4 v176, s[14:15]
	s_add_i32 s14, 0, 0x1c000
	v_add_u32_e32 v2, s14, v1
	ds_read_b128 v[194:197], v2
	ds_read_b128 v[198:201], v2 offset:1024
	ds_read_b128 v[202:205], v2 offset:2048
	ds_read_b128 v[208:211], v2 offset:3072
	s_waitcnt lgkmcnt(0)
	s_setprio 1
	s_barrier
	v_mfma_f32_16x16x32_bf16 v[68:71], v[132:135], v[148:151], v[68:71]
	v_mfma_f32_16x16x32_bf16 v[72:75], v[140:143], v[148:151], v[72:75]
	v_mfma_f32_16x16x32_bf16 v[120:123], v[132:135], v[156:159], v[120:123]
	v_mfma_f32_16x16x32_bf16 v[116:119], v[140:143], v[156:159], v[116:119]
	v_mfma_f32_16x16x32_bf16 v[112:115], v[132:135], v[164:167], v[112:115]
	v_mfma_f32_16x16x32_bf16 v[108:111], v[140:143], v[164:167], v[108:111]
	v_mfma_f32_16x16x32_bf16 v[104:107], v[132:135], v[186:189], v[104:107]
	v_mfma_f32_16x16x32_bf16 v[100:103], v[140:143], v[186:189], v[100:103]
	v_mfma_f32_16x16x32_bf16 v[68:71], v[136:139], v[152:155], v[68:71]
	v_mfma_f32_16x16x32_bf16 v[72:75], v[144:147], v[152:155], v[72:75]
	v_mfma_f32_16x16x32_bf16 v[120:123], v[136:139], v[160:163], v[120:123]
	v_mfma_f32_16x16x32_bf16 v[116:119], v[144:147], v[160:163], v[116:119]
	v_mfma_f32_16x16x32_bf16 v[112:115], v[136:139], v[168:171], v[112:115]
	v_mfma_f32_16x16x32_bf16 v[108:111], v[144:147], v[168:171], v[108:111]
	v_mfma_f32_16x16x32_bf16 v[104:107], v[136:139], v[190:193], v[104:107]
	v_mfma_f32_16x16x32_bf16 v[100:103], v[144:147], v[190:193], v[100:103]
	v_mfma_f32_16x16x32_bf16 v[76:79], v[194:197], v[148:151], v[76:79]
	v_mfma_f32_16x16x32_bf16 v[80:83], v[202:205], v[148:151], v[80:83]
	v_mfma_f32_16x16x32_bf16 v[96:99], v[194:197], v[156:159], v[96:99]
	v_mfma_f32_16x16x32_bf16 v[92:95], v[202:205], v[156:159], v[92:95]
	v_mfma_f32_16x16x32_bf16 v[88:91], v[194:197], v[164:167], v[88:91]
	v_mfma_f32_16x16x32_bf16 v[84:87], v[202:205], v[164:167], v[84:87]
	v_mfma_f32_16x16x32_bf16 v[128:131], v[194:197], v[186:189], v[128:131]
	v_mfma_f32_16x16x32_bf16 v[124:127], v[202:205], v[186:189], v[124:127]
	v_mfma_f32_16x16x32_bf16 v[76:79], v[198:201], v[152:155], v[76:79]
	v_mfma_f32_16x16x32_bf16 v[80:83], v[208:211], v[152:155], v[80:83]
	v_mfma_f32_16x16x32_bf16 v[96:99], v[198:201], v[160:163], v[96:99]
	v_mfma_f32_16x16x32_bf16 v[92:95], v[208:211], v[160:163], v[92:95]
	v_mfma_f32_16x16x32_bf16 v[88:91], v[198:201], v[168:171], v[88:91]
	v_mfma_f32_16x16x32_bf16 v[84:87], v[208:211], v[168:171], v[84:87]
	v_mfma_f32_16x16x32_bf16 v[128:131], v[198:201], v[190:193], v[128:131]
	v_mfma_f32_16x16x32_bf16 v[124:127], v[208:211], v[190:193], v[124:127]
	s_barrier
; #define LAS __attribute__((address_space(3)))
; __device__ __forceinline__ int opaque_tid() { int t = threadIdx.x; asm volatile("" : "+v"(t)); return t; }
; #define PG8_STAGE(bufoff, gbase, voff) do { _Pragma("unroll") for (int _i = 0; _i < 2; ++_i) \
;         __builtin_amdgcn_global_load_lds((const unsigned*)((const char*)(gbase) + (voff)[_i]), (LAS unsigned*)(lds + (bufoff) + ldsw + _i * 8192), 16, 0, 0); } while (0)
; #define PG8_MMA(ai, bj, At, Bt) do { __builtin_amdgcn_s_setprio(1); _Pragma("unroll") for (int m = 0; m < 4; ++m) _Pragma("unroll") for (int n = 0; n < 2; ++n) _Pragma("unroll") for (int k = 0; k < 2; ++k) \
;         acc[ai][bj][m][n] = __builtin_amdgcn_mfma_f32_16x16x32_bf16(Bt[n][k], At[m][k], acc[ai][bj][m][n], 0, 0, 0); __builtin_amdgcn_s_setprio(0); } while (0)
; #define PG8_WAIT_V(n) asm volatile("s_waitcnt vmcnt(" #n ")" ::: "memory")
; #define PG8_WAIT_L(n) asm volatile("s_waitcnt lgkmcnt(" #n ")" ::: "memory")
; #define PG8_BAR __builtin_amdgcn_s_barrier()
; #define PG8_SCHED __builtin_amdgcn_sched_barrier(0)
;     __device__ __forceinline__ void operator()(f32x4 (&acc)[2][2][4][2], const Unit& u, int wr, int wc, int ui, int) const {
;         const int ol_ = opaque_tid() & 63, fr = ol_ & 15, fq = ol_ >> 4;
;         { float r_[2][4];
;           rs_read(r_, ui, wr, fr);
; #pragma unroll
;           for (int ai = 0; ai < 2; ++ai)
; #pragma unroll
;               for (int bj = 0; bj < 2; ++bj)
; #pragma unroll
;                   for (int m = 0; m < 4; ++m) { acc[ai][bj][m][0] *= r_[ai][m]; acc[ai][bj][m][1] *= r_[ai][m]; } }
;         const int col = u.pn * 128 + wc * 32 + 8 * fq;
;         if (fr >= 14) {
; #pragma unroll
;             for (int ai = 0; ai < 2; ++ai) { LAS f32x4* s = (LAS f32x4*)(hl + ((((ai * 2 + wr) * 4 + wc) * 8 + fq * 2 + (fr - 14)) * 32));
;                 s[0] = acc[ai][1][3][0]; s[1] = acc[ai][1][3][1]; }
; template <class Epi, class Sched>
; __device__ __forceinline__ void gemm_phase(LAS unsigned char* lds, const Gemm g, const Sched& S, const Epi& E) {
;     ...
;             PG8_BAR; PG8_WAIT_L(0); PG8_MMA(1, 0, At, B0); PG8_BAR; PG8_SCHED;
;             PG8_STAGE(PG8_SB(1, 1), b3 + hstepB, voffB);
;             PG8_WAIT_V(6); PG8_BAR; PG8_MMA(1, 1, At, B1); PG8_BAR;
	s_setprio 0
	ds_read_b128 v[148:151], v207 offset:49152
	ds_read_b128 v[152:155], v207 offset:50176
	ds_read_b128 v[156:159], v207 offset:51200
	ds_read_b128 v[160:163], v207 offset:52224
	ds_read_b128 v[164:167], v207 offset:53248
	ds_read_b128 v[168:171], v207 offset:54272
	ds_read_b128 v[186:189], v207 offset:55296
	ds_read_b128 v[190:193], v207 offset:56320
	s_add_i32 s15, s72, s19
	v_lshl_add_u64 v[172:173], v[172:173], 0, s[8:9]
	s_mov_b32 m0, s15
	s_nop 0
	global_load_lds_dwordx4 v[172:173], off
	v_lshl_add_u64 v[172:173], v[212:213], 0, s[8:9]
	s_add_i32 m0, s15, 0x2000
	s_nop 0
	global_load_lds_dwordx4 v[172:173], off
	s_mov_b32 m0, s30
	v_lshl_add_u64 v[172:173], v[216:217], 0, s[8:9]
	global_load_lds_dwordx4 v[172:173], off
	v_lshl_add_u64 v[172:173], v[218:219], 0, s[8:9]
	s_mov_b32 m0, s31
	s_nop 0
	global_load_lds_dwordx4 v[172:173], off
	s_add_u32 s6, s6, 0x80080
	s_addc_u32 s7, s7, 0
	s_add_i32 s14, s14, s19
	s_mov_b32 m0, s14
	s_nop 0
	global_load_lds_dwordx4 v178, s[6:7]
	s_add_i32 m0, s14, 0x2000
	s_nop 0
	global_load_lds_dwordx4 v174, s[6:7]
	s_add_i32 s71, s71, 2
	s_add_u32 s4, s4, 0x100
	s_addc_u32 s5, s5, 0
	s_add_u32 s69, s69, 0x100
	s_addc_u32 s70, s70, 0
	s_cmp_gt_u32 s71, 29
	s_waitcnt lgkmcnt(0)
	s_waitcnt vmcnt(6)
	s_setprio 1
	s_barrier
	v_mfma_f32_16x16x32_bf16 v[56:59], v[132:135], v[148:151], v[56:59]
	v_mfma_f32_16x16x32_bf16 v[52:55], v[140:143], v[148:151], v[52:55]
	v_mfma_f32_16x16x32_bf16 v[48:51], v[132:135], v[156:159], v[48:51]
	v_mfma_f32_16x16x32_bf16 v[44:47], v[140:143], v[156:159], v[44:47]
	v_mfma_f32_16x16x32_bf16 v[40:43], v[132:135], v[164:167], v[40:43]
	v_mfma_f32_16x16x32_bf16 v[36:39], v[140:143], v[164:167], v[36:39]
	v_mfma_f32_16x16x32_bf16 v[32:35], v[132:135], v[186:189], v[32:35]
	v_mfma_f32_16x16x32_bf16 v[28:31], v[140:143], v[186:189], v[28:31]
	v_mfma_f32_16x16x32_bf16 v[56:59], v[136:139], v[152:155], v[56:59]
	v_mfma_f32_16x16x32_bf16 v[52:55], v[144:147], v[152:155], v[52:55]
	v_mfma_f32_16x16x32_bf16 v[48:51], v[136:139], v[160:163], v[48:51]
	v_mfma_f32_16x16x32_bf16 v[44:47], v[144:147], v[160:163], v[44:47]
	v_mfma_f32_16x16x32_bf16 v[40:43], v[136:139], v[168:171], v[40:43]
	v_mfma_f32_16x16x32_bf16 v[36:39], v[144:147], v[168:171], v[36:39]
	v_mfma_f32_16x16x32_bf16 v[32:35], v[136:139], v[190:193], v[32:35]
	v_mfma_f32_16x16x32_bf16 v[28:31], v[144:147], v[190:193], v[28:31]
	v_mfma_f32_16x16x32_bf16 v[24:27], v[194:197], v[148:151], v[24:27]
	v_mfma_f32_16x16x32_bf16 v[20:23], v[202:205], v[148:151], v[20:23]
	v_mfma_f32_16x16x32_bf16 v[16:19], v[194:197], v[156:159], v[16:19]
	v_mfma_f32_16x16x32_bf16 v[12:15], v[202:205], v[156:159], v[12:15]
	v_mfma_f32_16x16x32_bf16 v[8:11], v[194:197], v[164:167], v[8:11]
	v_mfma_f32_16x16x32_bf16 v[4:7], v[202:205], v[164:167], v[4:7]
	v_mfma_f32_16x16x32_bf16 v[60:63], v[194:197], v[186:189], v[60:63]
	v_mfma_f32_16x16x32_bf16 v[64:67], v[202:205], v[186:189], v[64:67]
	v_mfma_f32_16x16x32_bf16 v[24:27], v[198:201], v[152:155], v[24:27]
	v_mfma_f32_16x16x32_bf16 v[20:23], v[208:211], v[152:155], v[20:23]
	v_mfma_f32_16x16x32_bf16 v[16:19], v[198:201], v[160:163], v[16:19]
	v_mfma_f32_16x16x32_bf16 v[12:15], v[208:211], v[160:163], v[12:15]
	v_mfma_f32_16x16x32_bf16 v[8:11], v[198:201], v[168:171], v[8:11]
	v_mfma_f32_16x16x32_bf16 v[4:7], v[208:211], v[168:171], v[4:7]
	v_mfma_f32_16x16x32_bf16 v[60:63], v[198:201], v[190:193], v[60:63]
	v_mfma_f32_16x16x32_bf16 v[64:67], v[208:211], v[190:193], v[64:67]
	s_barrier
	s_cbranch_scc0 .LBB0_1526
	s_setprio 0
	s_andn2_b64 vcc, exec, s[46:47]
	s_cbranch_vccnz .Lalign_a_1526
	s_barrier
.Lalign_a_1526:
	v_bfe_u32 v186, v0, 4, 2
	s_lshl_b32 s4, s53, 7
	s_or_b32 s4, s4, s29
	v_lshl_or_b32 v186, v186, 3, s4
	v_lshlrev_b32_e32 v186, 2, v186
	global_load_dwordx4 v[162:165], v186, s[36:37] offset:16
	global_load_dwordx4 v[170:173], v186, s[36:37]
	global_load_dwordx4 v[154:157], v186, s[48:49] offset:16
	global_load_dwordx4 v[166:169], v186, s[48:49]
	global_load_dwordx4 v[146:149], v186, s[50:51] offset:16
	global_load_dwordx4 v[158:161], v186, s[50:51]
	global_load_dwordx4 v[142:145], v186, s[42:43] offset:16
	global_load_dwordx4 v[150:153], v186, s[42:43]
	s_lshl_b32 s4, s66, 10
	v_mov_b32_e32 v134, v0
	s_and_b32 s4, s4, 0x400
	s_add_i32 s4, s35, s4
	v_and_b32_e32 v210, 15, v134
	v_lshl_add_u32 v2, v210, 2, s4
	ds_read2_b32 v[204:205], v2 offset1:16
	ds_read2_b32 v[202:203], v2 offset0:32 offset1:48
	ds_read2_b32 v[198:199], v2 offset0:128 offset1:144
	ds_read2_b32 v[196:197], v2 offset0:160 offset1:176
	v_cmp_lt_u32_e32 vcc, 13, v210
	s_waitcnt lgkmcnt(0)
	v_mov_b32_e32 v206, v205
	v_mov_b32_e32 v208, v203
	v_mov_b32_e32 v2, v199
	v_mov_b32_e32 v200, v197
	v_pk_mul_f32 v[132:133], v[130:131], v[208:209] op_sel_hi:[1,0]
	v_pk_mul_f32 v[130:131], v[128:129], v[208:209] op_sel_hi:[1,0]
	v_pk_mul_f32 v[128:129], v[126:127], v[208:209] op_sel_hi:[1,0]
	v_pk_mul_f32 v[126:127], v[124:125], v[208:209] op_sel_hi:[1,0]
	v_pk_mul_f32 v[62:63], v[62:63], v[200:201] op_sel_hi:[1,0]
	v_pk_mul_f32 v[60:61], v[60:61], v[200:201] op_sel_hi:[1,0]
	v_pk_mul_f32 v[66:67], v[66:67], v[200:201] op_sel_hi:[1,0]
	v_pk_mul_f32 v[64:65], v[64:65], v[200:201] op_sel_hi:[1,0]
	v_bfe_u32 v125, v134, 4, 2
	s_and_saveexec_b64 s[4:5], vcc
	s_cbranch_execz .LBB0_1529
	v_lshlrev_b32_e32 v124, 1, v125
	v_add3_u32 v124, v210, v124, -14
	v_add_u32_e32 v134, s39, v124
	v_add_u32_e32 v124, s38, v124
	v_lshl_add_u32 v124, v124, 5, s62
	v_lshl_add_u32 v134, v134, 5, s62
	ds_write_b128 v124, v[130:133]
	ds_write_b128 v124, v[126:129] offset:16
	ds_write_b128 v134, v[60:63]
	ds_write_b128 v134, v[64:67] offset:16

; #define PG8_STAGE(bufoff, gbase, voff) do { _Pragma("unroll") for (int _i = 0; _i < 2; ++_i) \
;         __builtin_amdgcn_global_load_lds((const unsigned*)((const char*)(gbase) + (voff)[_i]), (LAS unsigned*)(lds + (bufoff) + ldsw + _i * 8192), 16, 0, 0); } while (0)
; #define PG8_LDA(dst, b, h) do { _Pragma("unroll") for (int m = 0; m < 4; ++m) _Pragma("unroll") for (int k = 0; k < 2; ++k) dst[m][k] = *(const LAS bf16x8*)(lds + PG8_SA(b, h) + aoff + m * 2048 + k * 1024); } while (0)
; #define PG8_LDB(dst, b, h) do { _Pragma("unroll") for (int n = 0; n < 2; ++n) _Pragma("unroll") for (int k = 0; k < 2; ++k) dst[n][k] = *(const LAS bf16x8*)(lds + PG8_SB(b, h) + boff + n * 2048 + k * 1024); } while (0)
; #define PG8_MMA(ai, bj, At, Bt) do { __builtin_amdgcn_s_setprio(1); _Pragma("unroll") for (int m = 0; m < 4; ++m) _Pragma("unroll") for (int n = 0; n < 2; ++n) _Pragma("unroll") for (int k = 0; k < 2; ++k) \
;         acc[ai][bj][m][n] = __builtin_amdgcn_mfma_f32_16x16x32_bf16(Bt[n][k], At[m][k], acc[ai][bj][m][n], 0, 0, 0); __builtin_amdgcn_s_setprio(0); } while (0)
; #define PG8_WAIT_V(n) asm volatile("s_waitcnt vmcnt(" #n ")" ::: "memory")
; #define PG8_WAIT_L(n) asm volatile("s_waitcnt lgkmcnt(" #n ")" ::: "memory")
; #define PG8_BAR __builtin_amdgcn_s_barrier()
; #define PG8_SCHED __builtin_amdgcn_sched_barrier(0)
; template <class Epi, class Sched>
; __device__ __forceinline__ void gemm_phase(LAS unsigned char* lds, const Gemm g, const Sched& S, const Epi& E) {
;     ...
;             PG8_LDB(B0, 0, 0); PG8_SCHED; PG8_LDA(At, 0, 0); PG8_STAGE(PG8_SA(1, 1), a1 + hstepA, voffA);
;             PG8_WAIT_L(8); PG8_BAR; PG8_WAIT_L(0); PG8_MMA(0, 0, At, B0); PG8_BAR; PG8_SCHED;
;             PG8_LDB(B1, 0, 1); PG8_STAGE(PG8_SB(0, 0), b2, voffB);
;             PG8_BAR; PG8_WAIT_L(0); PG8_MMA(0, 1, At, B1); PG8_BAR;
;             PG8_LDA(At, 0, 1); PG8_STAGE(PG8_SA(0, 0), a2, voffA);
;             PG8_BAR; PG8_WAIT_L(0); PG8_MMA(1, 0, At, B0); PG8_BAR; PG8_SCHED;
;             PG8_STAGE(PG8_SB(0, 1), b2 + hstepB, voffB);
;             PG8_WAIT_V(6); PG8_BAR; PG8_MMA(1, 1, At, B1); PG8_BAR;
.LBB0_1666:
	s_setprio 0
	s_add_u32 s14, s6, 0x100
	s_addc_u32 s15, s7, 0
	s_add_i32 s45, 0, 0x10000
	v_add_u32_e32 v144, s45, v1
	ds_read_b128 v[132:135], v144
	ds_read_b128 v[136:139], v144 offset:1024
	ds_read_b128 v[140:143], v144 offset:2048
	ds_read_b128 v[144:147], v144 offset:3072
	s_cmpk_eq_i32 s44, 0x54
	s_cselect_b32 s21, s1, s15
	s_cselect_b32 s20, s0, s14
	s_cselect_b32 s19, s5, s43
	s_cselect_b32 s18, s4, s42
	ds_read_b128 v[148:151], v224
	ds_read_b128 v[152:155], v224 offset:1024
	ds_read_b128 v[156:159], v224 offset:2048
	ds_read_b128 v[160:163], v224 offset:3072
	ds_read_b128 v[164:167], v224 offset:4096
	ds_read_b128 v[168:171], v224 offset:5120
	ds_read_b128 v[172:175], v224 offset:6144
	ds_read_b128 v[176:179], v224 offset:7168
	s_add_i32 s51, 0, 0x14000
	v_add_u32_e32 v202, s51, v1
	ds_read_b128 v[180:183], v202
	ds_read_b128 v[184:187], v202 offset:1024
	ds_read_b128 v[188:191], v202 offset:2048
	ds_read_b128 v[202:205], v202 offset:3072
	s_add_i32 m0, s29, 0xc000
	s_nop 0
	global_load_lds_dwordx4 v198, s[6:7]
	s_add_i32 m0, s29, 0xe000
	s_nop 0
	global_load_lds_dwordx4 v200, s[6:7]
	s_waitcnt lgkmcnt(0)
	s_setprio 1
	s_barrier
	v_mfma_f32_16x16x32_bf16 v[128:131], v[132:135], v[148:151], v[128:131]
	v_mfma_f32_16x16x32_bf16 v[124:127], v[140:143], v[148:151], v[124:127]
	v_mfma_f32_16x16x32_bf16 v[112:115], v[132:135], v[156:159], v[112:115]
	v_mfma_f32_16x16x32_bf16 v[108:111], v[140:143], v[156:159], v[108:111]
	v_mfma_f32_16x16x32_bf16 v[100:103], v[132:135], v[164:167], v[100:103]
	v_mfma_f32_16x16x32_bf16 v[92:95], v[140:143], v[164:167], v[92:95]
	v_mfma_f32_16x16x32_bf16 v[84:87], v[132:135], v[172:175], v[84:87]
	v_mfma_f32_16x16x32_bf16 v[76:79], v[140:143], v[172:175], v[76:79]
	v_mfma_f32_16x16x32_bf16 v[128:131], v[136:139], v[152:155], v[128:131]
	v_mfma_f32_16x16x32_bf16 v[124:127], v[144:147], v[152:155], v[124:127]
	v_mfma_f32_16x16x32_bf16 v[112:115], v[136:139], v[160:163], v[112:115]
	v_mfma_f32_16x16x32_bf16 v[108:111], v[144:147], v[160:163], v[108:111]
	v_mfma_f32_16x16x32_bf16 v[100:103], v[136:139], v[168:171], v[100:103]
	v_mfma_f32_16x16x32_bf16 v[92:95], v[144:147], v[168:171], v[92:95]
	v_mfma_f32_16x16x32_bf16 v[84:87], v[136:139], v[176:179], v[84:87]
	v_mfma_f32_16x16x32_bf16 v[76:79], v[144:147], v[176:179], v[76:79]
	v_mfma_f32_16x16x32_bf16 v[120:123], v[180:183], v[148:151], v[120:123]
	v_mfma_f32_16x16x32_bf16 v[116:119], v[188:191], v[148:151], v[116:119]
	v_mfma_f32_16x16x32_bf16 v[104:107], v[180:183], v[156:159], v[104:107]
	v_mfma_f32_16x16x32_bf16 v[96:99], v[188:191], v[156:159], v[96:99]
	v_mfma_f32_16x16x32_bf16 v[88:91], v[180:183], v[164:167], v[88:91]
	v_mfma_f32_16x16x32_bf16 v[80:83], v[188:191], v[164:167], v[80:83]
	v_mfma_f32_16x16x32_bf16 v[72:75], v[180:183], v[172:175], v[72:75]
	v_mfma_f32_16x16x32_bf16 v[68:71], v[188:191], v[172:175], v[68:71]
	v_mfma_f32_16x16x32_bf16 v[120:123], v[184:187], v[152:155], v[120:123]
	v_mfma_f32_16x16x32_bf16 v[116:119], v[202:205], v[152:155], v[116:119]
	v_mfma_f32_16x16x32_bf16 v[104:107], v[184:187], v[160:163], v[104:107]
	v_mfma_f32_16x16x32_bf16 v[96:99], v[202:205], v[160:163], v[96:99]
	v_mfma_f32_16x16x32_bf16 v[88:91], v[184:187], v[168:171], v[88:91]
	v_mfma_f32_16x16x32_bf16 v[80:83], v[202:205], v[168:171], v[80:83]
	v_mfma_f32_16x16x32_bf16 v[72:75], v[184:187], v[176:179], v[72:75]
	v_mfma_f32_16x16x32_bf16 v[68:71], v[202:205], v[176:179], v[68:71]
	s_barrier
	s_setprio 0
	ds_read_b128 v[148:151], v224 offset:16384
	ds_read_b128 v[152:155], v224 offset:17408
	ds_read_b128 v[156:159], v224 offset:18432
	ds_read_b128 v[160:163], v224 offset:19456
	ds_read_b128 v[164:167], v224 offset:20480
	ds_read_b128 v[168:171], v224 offset:21504
	ds_read_b128 v[172:175], v224 offset:22528
	ds_read_b128 v[176:179], v224 offset:23552
	s_add_i32 s6, s45, s28
	v_lshl_add_u64 v[206:207], s[18:19], 0, v[2:3]
	s_mov_b32 m0, s6
	s_nop 0
	global_load_lds_dwordx4 v[206:207], off
	v_lshl_add_u64 v[208:209], s[18:19], 0, v[192:193]
	s_add_i32 m0, s6, 0x2000
	s_nop 0
	global_load_lds_dwordx4 v[208:209], off
	s_mov_b32 m0, s29
	v_lshl_add_u64 v[210:211], s[20:21], 0, v[196:197]
	global_load_lds_dwordx4 v[210:211], off
	v_lshl_add_u64 v[212:213], s[20:21], 0, v[194:195]
	s_mov_b32 m0, s30
	s_nop 0
	global_load_lds_dwordx4 v[212:213], off
	s_add_u32 s6, s18, 0x160000
	s_addc_u32 s7, s19, 0
	s_add_i32 s45, s51, s28
	s_mov_b32 m0, s45
	s_nop 0
	global_load_lds_dwordx4 v2, s[6:7]
	s_add_i32 m0, s45, 0x2000
	s_nop 0
	global_load_lds_dwordx4 v192, s[6:7]
	s_waitcnt lgkmcnt(0)
	s_waitcnt vmcnt(6)
	s_setprio 1
	s_barrier
; #define PG8_STAGE(bufoff, gbase, voff) do { _Pragma("unroll") for (int _i = 0; _i < 2; ++_i) \
;         __builtin_amdgcn_global_load_lds((const unsigned*)((const char*)(gbase) + (voff)[_i]), (LAS unsigned*)(lds + (bufoff) + ldsw + _i * 8192), 16, 0, 0); } while (0)
; #define PG8_LDA(dst, b, h) do { _Pragma("unroll") for (int m = 0; m < 4; ++m) _Pragma("unroll") for (int k = 0; k < 2; ++k) dst[m][k] = *(const LAS bf16x8*)(lds + PG8_SA(b, h) + aoff + m * 2048 + k * 1024); } while (0)
; #define PG8_LDB(dst, b, h) do { _Pragma("unroll") for (int n = 0; n < 2; ++n) _Pragma("unroll") for (int k = 0; k < 2; ++k) dst[n][k] = *(const LAS bf16x8*)(lds + PG8_SB(b, h) + boff + n * 2048 + k * 1024); } while (0)
; #define PG8_MMA(ai, bj, At, Bt) do { __builtin_amdgcn_s_setprio(1); _Pragma("unroll") for (int m = 0; m < 4; ++m) _Pragma("unroll") for (int n = 0; n < 2; ++n) _Pragma("unroll") for (int k = 0; k < 2; ++k) \
;         acc[ai][bj][m][n] = __builtin_amdgcn_mfma_f32_16x16x32_bf16(Bt[n][k], At[m][k], acc[ai][bj][m][n], 0, 0, 0); __builtin_amdgcn_s_setprio(0); } while (0)
; #define PG8_WAIT_V(n) asm volatile("s_waitcnt vmcnt(" #n ")" ::: "memory")
; #define PG8_WAIT_L(n) asm volatile("s_waitcnt lgkmcnt(" #n ")" ::: "memory")
; #define PG8_BAR __builtin_amdgcn_s_barrier()
; #define PG8_SCHED __builtin_amdgcn_sched_barrier(0)
; template <class Epi, class Sched>
; __device__ __forceinline__ void gemm_phase(LAS unsigned char* lds, const Gemm g, const Sched& S, const Epi& E) {
;     ...
;             PG8_WAIT_V(6); PG8_BAR; PG8_MMA(1, 1, At, B1); PG8_BAR;
;             PG8_LDB(B0, 1, 0); PG8_SCHED; PG8_LDA(At, 1, 0); PG8_STAGE(PG8_SA(0, 1), a2 + hstepA, voffA);
;             PG8_WAIT_L(8); PG8_BAR; PG8_WAIT_L(0); PG8_MMA(0, 0, At, B0); PG8_BAR; PG8_SCHED;
;             PG8_LDB(B1, 1, 1); PG8_STAGE(PG8_SB(1, 0), b3, voffB);
;             PG8_BAR; PG8_WAIT_L(0); PG8_MMA(0, 1, At, B1); PG8_BAR;
;             PG8_LDA(At, 1, 1); PG8_STAGE(PG8_SA(1, 0), a3, voffA);
;             PG8_BAR; PG8_WAIT_L(0); PG8_MMA(1, 0, At, B0); PG8_BAR; PG8_SCHED;
	v_mfma_f32_16x16x32_bf16 v[64:67], v[132:135], v[148:151], v[64:67]
	v_mfma_f32_16x16x32_bf16 v[60:63], v[140:143], v[148:151], v[60:63]
	v_mfma_f32_16x16x32_bf16 v[52:55], v[132:135], v[156:159], v[52:55]
	v_mfma_f32_16x16x32_bf16 v[44:47], v[140:143], v[156:159], v[44:47]
	v_mfma_f32_16x16x32_bf16 v[36:39], v[132:135], v[164:167], v[36:39]
	v_mfma_f32_16x16x32_bf16 v[28:31], v[140:143], v[164:167], v[28:31]
	v_mfma_f32_16x16x32_bf16 v[20:23], v[132:135], v[172:175], v[20:23]
	v_mfma_f32_16x16x32_bf16 v[12:15], v[140:143], v[172:175], v[12:15]
	v_mfma_f32_16x16x32_bf16 v[64:67], v[136:139], v[152:155], v[64:67]
	v_mfma_f32_16x16x32_bf16 v[60:63], v[144:147], v[152:155], v[60:63]
	v_mfma_f32_16x16x32_bf16 v[52:55], v[136:139], v[160:163], v[52:55]
	v_mfma_f32_16x16x32_bf16 v[44:47], v[144:147], v[160:163], v[44:47]
	v_mfma_f32_16x16x32_bf16 v[36:39], v[136:139], v[168:171], v[36:39]
	v_mfma_f32_16x16x32_bf16 v[28:31], v[144:147], v[168:171], v[28:31]
	v_mfma_f32_16x16x32_bf16 v[20:23], v[136:139], v[176:179], v[20:23]
	v_mfma_f32_16x16x32_bf16 v[12:15], v[144:147], v[176:179], v[12:15]
	v_mfma_f32_16x16x32_bf16 v[56:59], v[180:183], v[148:151], v[56:59]
	v_mfma_f32_16x16x32_bf16 v[48:51], v[188:191], v[148:151], v[48:51]
	v_mfma_f32_16x16x32_bf16 v[40:43], v[180:183], v[156:159], v[40:43]
	v_mfma_f32_16x16x32_bf16 v[32:35], v[188:191], v[156:159], v[32:35]
	v_mfma_f32_16x16x32_bf16 v[24:27], v[180:183], v[164:167], v[24:27]
	v_mfma_f32_16x16x32_bf16 v[16:19], v[188:191], v[164:167], v[16:19]
	v_mfma_f32_16x16x32_bf16 v[8:11], v[180:183], v[172:175], v[8:11]
	v_mfma_f32_16x16x32_bf16 v[4:7], v[188:191], v[172:175], v[4:7]
	v_mfma_f32_16x16x32_bf16 v[56:59], v[184:187], v[152:155], v[56:59]
	v_mfma_f32_16x16x32_bf16 v[48:51], v[202:205], v[152:155], v[48:51]
	v_mfma_f32_16x16x32_bf16 v[40:43], v[184:187], v[160:163], v[40:43]
	v_mfma_f32_16x16x32_bf16 v[32:35], v[202:205], v[160:163], v[32:35]
	v_mfma_f32_16x16x32_bf16 v[24:27], v[184:187], v[168:171], v[24:27]
	v_mfma_f32_16x16x32_bf16 v[16:19], v[202:205], v[168:171], v[16:19]
	v_mfma_f32_16x16x32_bf16 v[8:11], v[184:187], v[176:179], v[8:11]
	v_mfma_f32_16x16x32_bf16 v[4:7], v[202:205], v[176:179], v[4:7]
	s_barrier
	s_setprio 0
	s_add_i32 s45, 0, 0x18000
	v_add_u32_e32 v144, s45, v1
	ds_read_b128 v[132:135], v144
	ds_read_b128 v[136:139], v144 offset:1024
	ds_read_b128 v[140:143], v144 offset:2048
	ds_read_b128 v[144:147], v144 offset:3072
	s_add_u32 s6, s20, 0x160000
	s_addc_u32 s7, s21, 0
	ds_read_b128 v[148:151], v224 offset:32768
	ds_read_b128 v[152:155], v224 offset:33792
	ds_read_b128 v[156:159], v224 offset:34816
	ds_read_b128 v[160:163], v224 offset:35840
	ds_read_b128 v[164:167], v224 offset:36864
	ds_read_b128 v[168:171], v224 offset:37888
	ds_read_b128 v[172:175], v224 offset:38912
	ds_read_b128 v[176:179], v224 offset:39936
	s_mov_b32 m0, s31
	s_nop 0
	global_load_lds_dwordx4 v196, s[6:7]
	s_mov_b32 m0, s35
	s_nop 0
	global_load_lds_dwordx4 v194, s[6:7]
	s_add_i32 s20, 0, 0x1c000
	v_add_u32_e32 v202, s20, v1
	ds_read_b128 v[180:183], v202
	ds_read_b128 v[184:187], v202 offset:1024
	ds_read_b128 v[188:191], v202 offset:2048
	ds_read_b128 v[202:205], v202 offset:3072
	s_waitcnt lgkmcnt(0)
	s_setprio 1
	s_barrier
	v_mfma_f32_16x16x32_bf16 v[128:131], v[132:135], v[148:151], v[128:131]
	v_mfma_f32_16x16x32_bf16 v[124:127], v[140:143], v[148:151], v[124:127]
	v_mfma_f32_16x16x32_bf16 v[112:115], v[132:135], v[156:159], v[112:115]
	v_mfma_f32_16x16x32_bf16 v[108:111], v[140:143], v[156:159], v[108:111]
	v_mfma_f32_16x16x32_bf16 v[100:103], v[132:135], v[164:167], v[100:103]
	v_mfma_f32_16x16x32_bf16 v[92:95], v[140:143], v[164:167], v[92:95]
	v_mfma_f32_16x16x32_bf16 v[84:87], v[132:135], v[172:175], v[84:87]
	v_mfma_f32_16x16x32_bf16 v[76:79], v[140:143], v[172:175], v[76:79]
	v_mfma_f32_16x16x32_bf16 v[128:131], v[136:139], v[152:155], v[128:131]
	v_mfma_f32_16x16x32_bf16 v[124:127], v[144:147], v[152:155], v[124:127]
	v_mfma_f32_16x16x32_bf16 v[112:115], v[136:139], v[160:163], v[112:115]
	v_mfma_f32_16x16x32_bf16 v[108:111], v[144:147], v[160:163], v[108:111]
	v_mfma_f32_16x16x32_bf16 v[100:103], v[136:139], v[168:171], v[100:103]
	v_mfma_f32_16x16x32_bf16 v[92:95], v[144:147], v[168:171], v[92:95]
	v_mfma_f32_16x16x32_bf16 v[84:87], v[136:139], v[176:179], v[84:87]
	v_mfma_f32_16x16x32_bf16 v[76:79], v[144:147], v[176:179], v[76:79]
	v_mfma_f32_16x16x32_bf16 v[120:123], v[180:183], v[148:151], v[120:123]
	v_mfma_f32_16x16x32_bf16 v[116:119], v[188:191], v[148:151], v[116:119]
	v_mfma_f32_16x16x32_bf16 v[104:107], v[180:183], v[156:159], v[104:107]
	v_mfma_f32_16x16x32_bf16 v[96:99], v[188:191], v[156:159], v[96:99]
	v_mfma_f32_16x16x32_bf16 v[88:91], v[180:183], v[164:167], v[88:91]
	v_mfma_f32_16x16x32_bf16 v[80:83], v[188:191], v[164:167], v[80:83]
	v_mfma_f32_16x16x32_bf16 v[72:75], v[180:183], v[172:175], v[72:75]
	v_mfma_f32_16x16x32_bf16 v[68:71], v[188:191], v[172:175], v[68:71]
	v_mfma_f32_16x16x32_bf16 v[120:123], v[184:187], v[152:155], v[120:123]
	v_mfma_f32_16x16x32_bf16 v[116:119], v[202:205], v[152:155], v[116:119]
	v_mfma_f32_16x16x32_bf16 v[104:107], v[184:187], v[160:163], v[104:107]
	v_mfma_f32_16x16x32_bf16 v[96:99], v[202:205], v[160:163], v[96:99]
	v_mfma_f32_16x16x32_bf16 v[88:91], v[184:187], v[168:171], v[88:91]
	v_mfma_f32_16x16x32_bf16 v[80:83], v[202:205], v[168:171], v[80:83]
	v_mfma_f32_16x16x32_bf16 v[72:75], v[184:187], v[176:179], v[72:75]
	v_mfma_f32_16x16x32_bf16 v[68:71], v[202:205], v[176:179], v[68:71]
	s_barrier
; __device__ __forceinline__ int opaque_tid() { int t = threadIdx.x; asm volatile("" : "+v"(t)); return t; }
; #define PG8_STAGE(bufoff, gbase, voff) do { _Pragma("unroll") for (int _i = 0; _i < 2; ++_i) \
;         __builtin_amdgcn_global_load_lds((const unsigned*)((const char*)(gbase) + (voff)[_i]), (LAS unsigned*)(lds + (bufoff) + ldsw + _i * 8192), 16, 0, 0); } while (0)
; #define PG8_MMA(ai, bj, At, Bt) do { __builtin_amdgcn_s_setprio(1); _Pragma("unroll") for (int m = 0; m < 4; ++m) _Pragma("unroll") for (int n = 0; n < 2; ++n) _Pragma("unroll") for (int k = 0; k < 2; ++k) \
;         acc[ai][bj][m][n] = __builtin_amdgcn_mfma_f32_16x16x32_bf16(Bt[n][k], At[m][k], acc[ai][bj][m][n], 0, 0, 0); __builtin_amdgcn_s_setprio(0); } while (0)
; #define PG8_WAIT_V(n) asm volatile("s_waitcnt vmcnt(" #n ")" ::: "memory")
; #define PG8_WAIT_L(n) asm volatile("s_waitcnt lgkmcnt(" #n ")" ::: "memory")
; #define PG8_BAR __builtin_amdgcn_s_barrier()
; #define PG8_SCHED __builtin_amdgcn_sched_barrier(0)
;     __device__ __forceinline__ void operator()(const f32x4 (&acc)[2][2][4][2], const Unit& u, int wr, int wc, int, int) const {
;         const int ol_ = opaque_tid() & 63, fr = ol_ & 15, fq = ol_ >> 4;
;         const int row0 = u.pm * BM + wr * 64 + fr, col0 = u.pn * BM + wc * 32 + 8 * fq;
;         u32x4 cin[2][4][2];
; #pragma unroll
;         for (int ai = 0; ai < 2; ++ai)
; #pragma unroll
;             for (int m = 0; m < 4; ++m)
; #pragma unroll
;                 for (int bj = 0; bj < 2; ++bj) cin[ai][m][bj] = *(const u32x4*)(C + (size_t)(row0 + ai * HALF + m * 16) * ldc + col0 + bj * HALF);
; template <class Epi, class Sched>
; __device__ __forceinline__ void gemm_phase(LAS unsigned char* lds, const Gemm g, const Sched& S, const Epi& E) {
;     ...
;             PG8_BAR; PG8_WAIT_L(0); PG8_MMA(1, 0, At, B0); PG8_BAR; PG8_SCHED;
;             PG8_STAGE(PG8_SB(1, 1), b3 + hstepB, voffB);
;             PG8_WAIT_V(6); PG8_BAR; PG8_MMA(1, 1, At, B1); PG8_BAR;
	s_setprio 0
	ds_read_b128 v[148:151], v224 offset:49152
	ds_read_b128 v[152:155], v224 offset:50176
	ds_read_b128 v[156:159], v224 offset:51200
	ds_read_b128 v[160:163], v224 offset:52224
	ds_read_b128 v[164:167], v224 offset:53248
	ds_read_b128 v[168:171], v224 offset:54272
	ds_read_b128 v[172:175], v224 offset:55296
	ds_read_b128 v[176:179], v224 offset:56320
	s_add_i32 s6, s45, s28
	v_lshl_add_u64 v[206:207], v[206:207], 0, s[8:9]
	s_mov_b32 m0, s6
	s_nop 0
	global_load_lds_dwordx4 v[206:207], off
	v_lshl_add_u64 v[206:207], v[208:209], 0, s[8:9]
	s_add_i32 m0, s6, 0x2000
	s_nop 0
	global_load_lds_dwordx4 v[206:207], off
	s_mov_b32 m0, s38
	v_lshl_add_u64 v[206:207], v[210:211], 0, s[8:9]
	global_load_lds_dwordx4 v[206:207], off
	v_lshl_add_u64 v[206:207], v[212:213], 0, s[8:9]
	s_mov_b32 m0, s39
	s_nop 0
	global_load_lds_dwordx4 v[206:207], off
	s_add_u32 s6, s18, 0x160080
	s_addc_u32 s7, s19, 0
	s_add_i32 s18, s20, s28
	s_mov_b32 m0, s18
	s_nop 0
	global_load_lds_dwordx4 v2, s[6:7]
	s_add_i32 m0, s18, 0x2000
	s_nop 0
	global_load_lds_dwordx4 v192, s[6:7]
	s_add_i32 s44, s44, 2
	s_add_u32 s42, s42, 0x100
	s_addc_u32 s43, s43, 0
	s_cmpk_gt_u32 s44, 0x55
	s_mov_b64 s[6:7], s[14:15]
	s_waitcnt lgkmcnt(0)
	s_waitcnt vmcnt(6)
	s_setprio 1
	s_barrier
	v_mfma_f32_16x16x32_bf16 v[64:67], v[132:135], v[148:151], v[64:67]
	v_mfma_f32_16x16x32_bf16 v[60:63], v[140:143], v[148:151], v[60:63]
	v_mfma_f32_16x16x32_bf16 v[52:55], v[132:135], v[156:159], v[52:55]
	v_mfma_f32_16x16x32_bf16 v[44:47], v[140:143], v[156:159], v[44:47]
	v_mfma_f32_16x16x32_bf16 v[36:39], v[132:135], v[164:167], v[36:39]
	v_mfma_f32_16x16x32_bf16 v[28:31], v[140:143], v[164:167], v[28:31]
	v_mfma_f32_16x16x32_bf16 v[20:23], v[132:135], v[172:175], v[20:23]
	v_mfma_f32_16x16x32_bf16 v[12:15], v[140:143], v[172:175], v[12:15]
	v_mfma_f32_16x16x32_bf16 v[64:67], v[136:139], v[152:155], v[64:67]
	v_mfma_f32_16x16x32_bf16 v[60:63], v[144:147], v[152:155], v[60:63]
	v_mfma_f32_16x16x32_bf16 v[52:55], v[136:139], v[160:163], v[52:55]
	v_mfma_f32_16x16x32_bf16 v[44:47], v[144:147], v[160:163], v[44:47]
	v_mfma_f32_16x16x32_bf16 v[36:39], v[136:139], v[168:171], v[36:39]
	v_mfma_f32_16x16x32_bf16 v[28:31], v[144:147], v[168:171], v[28:31]
	v_mfma_f32_16x16x32_bf16 v[20:23], v[136:139], v[176:179], v[20:23]
	v_mfma_f32_16x16x32_bf16 v[12:15], v[144:147], v[176:179], v[12:15]
	v_mfma_f32_16x16x32_bf16 v[56:59], v[180:183], v[148:151], v[56:59]
	v_mfma_f32_16x16x32_bf16 v[48:51], v[188:191], v[148:151], v[48:51]
	v_mfma_f32_16x16x32_bf16 v[40:43], v[180:183], v[156:159], v[40:43]
	v_mfma_f32_16x16x32_bf16 v[32:35], v[188:191], v[156:159], v[32:35]
	v_mfma_f32_16x16x32_bf16 v[24:27], v[180:183], v[164:167], v[24:27]
	v_mfma_f32_16x16x32_bf16 v[16:19], v[188:191], v[164:167], v[16:19]
	v_mfma_f32_16x16x32_bf16 v[8:11], v[180:183], v[172:175], v[8:11]
	v_mfma_f32_16x16x32_bf16 v[4:7], v[188:191], v[172:175], v[4:7]
	v_mfma_f32_16x16x32_bf16 v[56:59], v[184:187], v[152:155], v[56:59]
	v_mfma_f32_16x16x32_bf16 v[48:51], v[202:205], v[152:155], v[48:51]
	v_mfma_f32_16x16x32_bf16 v[40:43], v[184:187], v[160:163], v[40:43]
	v_mfma_f32_16x16x32_bf16 v[32:35], v[202:205], v[160:163], v[32:35]
	v_mfma_f32_16x16x32_bf16 v[24:27], v[184:187], v[168:171], v[24:27]
	v_mfma_f32_16x16x32_bf16 v[16:19], v[202:205], v[168:171], v[16:19]
	v_mfma_f32_16x16x32_bf16 v[8:11], v[184:187], v[176:179], v[8:11]
	v_mfma_f32_16x16x32_bf16 v[4:7], v[202:205], v[176:179], v[4:7]
	s_barrier
	s_cbranch_scc0 .LBB0_1666
	s_setprio 0
	s_cmpk_gt_u32 s2, 0xff
	s_cbranch_scc1 .Lalign_a_1666
	s_barrier
.Lalign_a_1666:
	v_mov_b32_e32 v133, v0
	s_lshl_b32 s6, s50, 8
	s_add_i32 s6, s6, s36
	v_and_or_b32 v132, v133, 15, s6
	s_lshl_b32 s6, s49, 8
	v_lshrrev_b32_e32 v133, 1, v133
	v_and_or_b32 v133, v133, 24, s6
	v_or_b32_e32 v134, s37, v133
	v_ashrrev_i32_e32 v135, 31, v134
	v_lshlrev_b64 v[202:203], 1, v[134:135]
	v_ashrrev_i32_e32 v133, 31, v132
	v_lshl_add_u64 v[134:135], s[88:89], 0, v[202:203]
	v_lshlrev_b64 v[226:227], 12, v[132:133]
	v_lshl_add_u64 v[136:137], v[134:135], 0, v[226:227]
	global_load_dwordx4 v[216:219], v[136:137], off
	global_load_dwordx4 v[188:191], v[136:137], off offset:256
	v_or_b32_e32 v136, 16, v132
	v_ashrrev_i32_e32 v137, 31, v136
	v_lshlrev_b64 v[222:223], 12, v[136:137]
	v_lshl_add_u64 v[136:137], v[134:135], 0, v[222:223]
	global_load_dwordx4 v[184:187], v[136:137], off
	global_load_dwordx4 v[180:183], v[136:137], off offset:256
	v_or_b32_e32 v136, 32, v132
	v_ashrrev_i32_e32 v137, 31, v136
	v_lshlrev_b64 v[220:221], 12, v[136:137]
	v_lshl_add_u64 v[136:137], v[134:135], 0, v[220:221]
	global_load_dwordx4 v[176:179], v[136:137], off
	global_load_dwordx4 v[168:171], v[136:137], off offset:256
	v_or_b32_e32 v132, 48, v132
	v_ashrrev_i32_e32 v133, 31, v132
	v_lshlrev_b64 v[212:213], 12, v[132:133]
	v_lshl_add_u64 v[132:133], v[134:135], 0, v[212:213]
	global_load_dwordx4 v[172:175], v[132:133], off
	global_load_dwordx4 v[164:167], v[132:133], off offset:256
	s_mov_b64 s[6:7], 0x80000
	v_lshl_add_u64 v[210:211], v[226:227], 0, s[6:7]
	v_lshl_add_u64 v[132:133], v[134:135], 0, v[210:211]
	global_load_dwordx4 v[160:163], v[132:133], off
	global_load_dwordx4 v[156:159], v[132:133], off offset:256
	s_mov_b64 s[6:7], 0x90000
	v_lshl_add_u64 v[208:209], v[226:227], 0, s[6:7]
	v_lshl_add_u64 v[132:133], v[134:135], 0, v[208:209]
	global_load_dwordx4 v[152:155], v[132:133], off
	global_load_dwordx4 v[148:151], v[132:133], off offset:256
	s_mov_b64 s[6:7], 0xa0000
	v_lshl_add_u64 v[206:207], v[226:227], 0, s[6:7]
	v_lshl_add_u64 v[132:133], v[134:135], 0, v[206:207]
	global_load_dwordx4 v[144:147], v[132:133], off
	global_load_dwordx4 v[140:143], v[132:133], off offset:256
	s_mov_b64 s[6:7], 0xb0000
	v_lshl_add_u64 v[204:205], v[226:227], 0, s[6:7]
	v_lshl_add_u64 v[132:133], v[134:135], 0, v[204:205]
	global_load_dwordx4 v[136:139], v[132:133], off
	s_nop 0
	global_load_dwordx4 v[132:135], v[132:133], off offset:256
	s_and_b64 vcc, exec, s[40:41]
	s_mov_b32 s49, s47
	s_mov_b32 s50, s48
	s_mov_b64 s[14:15], s[4:5]
	s_mov_b64 s[6:7], s[0:1]
	s_waitcnt vmcnt(15)
; __device__ __forceinline__ unsigned cvt_pk_bf16(float lo, float hi) { const f32x2 v = {lo, hi}; const bf16v2_ r = __builtin_convertvector(v, bf16v2_); return __builtin_bit_cast(unsigned, r); }
; __device__ __forceinline__ float bflo(unsigned w) { return __uint_as_float(w << 16); }
; __device__ __forceinline__ float bfhi(unsigned w) { return __uint_as_float(w & 0xffff0000u); }
;     __device__ __forceinline__ void operator()(const f32x4 (&acc)[2][2][4][2], const Unit& u, int wr, int wc, int, int) const {
;     ...
; #pragma unroll
;         for (int ai = 0; ai < 2; ++ai)
; #pragma unroll
;             for (int m = 0; m < 4; ++m)
; #pragma unroll
;                 for (int bj = 0; bj < 2; ++bj) { const u32x4 c = cin[ai][m][bj]; const f32x4 v0 = acc[ai][bj][m][0], v1 = acc[ai][bj][m][1];
;                     u32x4 w; w.x = cvt_pk_bf16(bflo(c.x) + v0[0], bfhi(c.x) + v0[1]); w.y = cvt_pk_bf16(bflo(c.y) + v0[2], bfhi(c.y) + v0[3]);
;                     w.z = cvt_pk_bf16(bflo(c.z) + v1[0], bfhi(c.z) + v1[1]); w.w = cvt_pk_bf16(bflo(c.w) + v1[2], bfhi(c.w) + v1[3]);
;                     *(u32x4*)(C + (size_t)(row0 + ai * HALF + m * 16) * ldc + col0 + bj * HALF) = w; }
	v_lshlrev_b32_e32 v228, 16, v216
	v_and_b32_e32 v229, 0xffff0000, v216
	v_lshlrev_b32_e32 v216, 16, v217
	v_and_b32_e32 v217, 0xffff0000, v217
	v_pk_add_f32 v[128:129], v[128:129], v[228:229]
	v_pk_add_f32 v[130:131], v[130:131], v[216:217]
	v_cvt_pk_bf16_f32 v128, v128, v129
	v_cvt_pk_bf16_f32 v129, v130, v131
	v_lshlrev_b32_e32 v130, 16, v218
	v_and_b32_e32 v131, 0xffff0000, v218
	v_pk_add_f32 v[124:125], v[124:125], v[130:131]
	s_nop 0
	v_cvt_pk_bf16_f32 v130, v124, v125
	v_lshlrev_b32_e32 v124, 16, v219
	v_and_b32_e32 v125, 0xffff0000, v219
	v_pk_add_f32 v[124:125], v[126:127], v[124:125]
	s_waitcnt vmcnt(14)
	v_lshlrev_b32_e32 v126, 16, v188
	v_and_b32_e32 v127, 0xffff0000, v188
	v_pk_add_f32 v[120:121], v[120:121], v[126:127]
	v_lshlrev_b32_e32 v126, 16, v189
	v_and_b32_e32 v127, 0xffff0000, v189
	v_pk_add_f32 v[122:123], v[122:123], v[126:127]
	v_cvt_pk_bf16_f32 v120, v120, v121
	v_cvt_pk_bf16_f32 v121, v122, v123
	v_lshlrev_b32_e32 v122, 16, v190
	v_and_b32_e32 v123, 0xffff0000, v190
	v_pk_add_f32 v[116:117], v[116:117], v[122:123]
	v_cvt_pk_bf16_f32 v131, v124, v125
	v_cvt_pk_bf16_f32 v122, v116, v117
	v_lshlrev_b32_e32 v116, 16, v191
	v_and_b32_e32 v117, 0xffff0000, v191
	v_pk_add_f32 v[116:117], v[118:119], v[116:117]
	v_lshl_add_u64 v[124:125], s[88:89], 0, v[226:227]
	v_cvt_pk_bf16_f32 v123, v116, v117
	s_waitcnt vmcnt(13)
	v_lshlrev_b32_e32 v116, 16, v184
	v_and_b32_e32 v117, 0xffff0000, v184
	v_pk_add_f32 v[112:113], v[112:113], v[116:117]
	v_lshlrev_b32_e32 v116, 16, v185
	v_and_b32_e32 v117, 0xffff0000, v185
	v_pk_add_f32 v[114:115], v[114:115], v[116:117]
	v_cvt_pk_bf16_f32 v112, v112, v113
	v_cvt_pk_bf16_f32 v113, v114, v115
	v_lshlrev_b32_e32 v114, 16, v186
	v_and_b32_e32 v115, 0xffff0000, v186
	v_pk_add_f32 v[108:109], v[108:109], v[114:115]
	v_lshl_add_u64 v[124:125], v[124:125], 0, v[202:203]
	v_cvt_pk_bf16_f32 v114, v108, v109
	v_lshlrev_b32_e32 v108, 16, v187
	v_and_b32_e32 v109, 0xffff0000, v187
	v_pk_add_f32 v[108:109], v[110:111], v[108:109]
	s_waitcnt vmcnt(12)
	v_lshlrev_b32_e32 v110, 16, v180
	v_and_b32_e32 v111, 0xffff0000, v180
	v_pk_add_f32 v[104:105], v[104:105], v[110:111]
	v_lshlrev_b32_e32 v110, 16, v181
	v_and_b32_e32 v111, 0xffff0000, v181
	v_pk_add_f32 v[106:107], v[106:107], v[110:111]
	v_cvt_pk_bf16_f32 v104, v104, v105
	v_cvt_pk_bf16_f32 v105, v106, v107
	v_lshlrev_b32_e32 v106, 16, v182
	v_and_b32_e32 v107, 0xffff0000, v182
	v_pk_add_f32 v[96:97], v[96:97], v[106:107]
	v_cvt_pk_bf16_f32 v115, v108, v109
	v_cvt_pk_bf16_f32 v106, v96, v97
	v_lshlrev_b32_e32 v96, 16, v183
	v_and_b32_e32 v97, 0xffff0000, v183
	v_pk_add_f32 v[96:97], v[98:99], v[96:97]
	s_waitcnt vmcnt(11)
	v_lshlrev_b32_e32 v98, 16, v177
	v_cvt_pk_bf16_f32 v107, v96, v97
	v_lshlrev_b32_e32 v96, 16, v176
	v_and_b32_e32 v97, 0xffff0000, v176
	v_and_b32_e32 v99, 0xffff0000, v177
	v_pk_add_f32 v[96:97], v[100:101], v[96:97]
	v_pk_add_f32 v[98:99], v[102:103], v[98:99]
	v_cvt_pk_bf16_f32 v96, v96, v97
	v_cvt_pk_bf16_f32 v97, v98, v99
	v_lshlrev_b32_e32 v98, 16, v178
	v_and_b32_e32 v99, 0xffff0000, v178
	v_pk_add_f32 v[92:93], v[92:93], v[98:99]
	v_lshl_add_u64 v[108:109], s[88:89], 0, v[222:223]
	v_cvt_pk_bf16_f32 v98, v92, v93
	v_lshlrev_b32_e32 v92, 16, v179
	v_and_b32_e32 v93, 0xffff0000, v179
	v_pk_add_f32 v[92:93], v[94:95], v[92:93]
	s_waitcnt vmcnt(10)
	v_lshlrev_b32_e32 v94, 16, v168
	v_and_b32_e32 v95, 0xffff0000, v168
	v_pk_add_f32 v[88:89], v[88:89], v[94:95]
	v_lshlrev_b32_e32 v94, 16, v169
	v_and_b32_e32 v95, 0xffff0000, v169
	v_pk_add_f32 v[90:91], v[90:91], v[94:95]
	v_cvt_pk_bf16_f32 v88, v88, v89
	v_cvt_pk_bf16_f32 v89, v90, v91
	v_lshlrev_b32_e32 v90, 16, v170
	v_and_b32_e32 v91, 0xffff0000, v170
	v_pk_add_f32 v[80:81], v[80:81], v[90:91]
	v_cvt_pk_bf16_f32 v99, v92, v93
	v_cvt_pk_bf16_f32 v90, v80, v81
	v_lshlrev_b32_e32 v80, 16, v171
	v_and_b32_e32 v81, 0xffff0000, v171
	v_pk_add_f32 v[80:81], v[82:83], v[80:81]
	s_waitcnt vmcnt(9)
	v_lshlrev_b32_e32 v82, 16, v173
	v_cvt_pk_bf16_f32 v91, v80, v81
	v_lshlrev_b32_e32 v80, 16, v172
	v_and_b32_e32 v81, 0xffff0000, v172
	v_and_b32_e32 v83, 0xffff0000, v173
	v_pk_add_f32 v[80:81], v[84:85], v[80:81]
	v_pk_add_f32 v[82:83], v[86:87], v[82:83]
	v_cvt_pk_bf16_f32 v80, v80, v81
	v_cvt_pk_bf16_f32 v81, v82, v83
	v_lshlrev_b32_e32 v82, 16, v174
	v_and_b32_e32 v83, 0xffff0000, v174
	v_pk_add_f32 v[76:77], v[76:77], v[82:83]
	v_lshl_add_u64 v[92:93], s[88:89], 0, v[220:221]
	v_cvt_pk_bf16_f32 v82, v76, v77
	v_lshlrev_b32_e32 v76, 16, v175
	v_and_b32_e32 v77, 0xffff0000, v175
	v_pk_add_f32 v[76:77], v[78:79], v[76:77]
	s_waitcnt vmcnt(8)
	v_lshlrev_b32_e32 v78, 16, v164
	v_and_b32_e32 v79, 0xffff0000, v164
	v_pk_add_f32 v[72:73], v[72:73], v[78:79]
	v_lshlrev_b32_e32 v78, 16, v165
	v_and_b32_e32 v79, 0xffff0000, v165
	v_pk_add_f32 v[74:75], v[74:75], v[78:79]
	v_cvt_pk_bf16_f32 v72, v72, v73
	v_cvt_pk_bf16_f32 v73, v74, v75
	v_lshlrev_b32_e32 v74, 16, v166
	v_and_b32_e32 v75, 0xffff0000, v166
	v_pk_add_f32 v[68:69], v[68:69], v[74:75]
	v_cvt_pk_bf16_f32 v83, v76, v77
	v_cvt_pk_bf16_f32 v74, v68, v69
	v_lshlrev_b32_e32 v68, 16, v167
	v_and_b32_e32 v69, 0xffff0000, v167
	v_pk_add_f32 v[68:69], v[70:71], v[68:69]
	v_lshl_add_u64 v[76:77], s[88:89], 0, v[212:213]
	v_cvt_pk_bf16_f32 v75, v68, v69
	s_waitcnt vmcnt(7)
	v_lshlrev_b32_e32 v68, 16, v160
	v_and_b32_e32 v69, 0xffff0000, v160
	v_pk_add_f32 v[64:65], v[64:65], v[68:69]
	v_lshlrev_b32_e32 v68, 16, v161
	v_and_b32_e32 v69, 0xffff0000, v161
	v_pk_add_f32 v[66:67], v[66:67], v[68:69]
	v_cvt_pk_bf16_f32 v64, v64, v65
	v_cvt_pk_bf16_f32 v65, v66, v67
	v_lshlrev_b32_e32 v66, 16, v162
	v_and_b32_e32 v67, 0xffff0000, v162
	v_pk_add_f32 v[60:61], v[60:61], v[66:67]
	v_lshl_add_u64 v[108:109], v[108:109], 0, v[202:203]
	v_cvt_pk_bf16_f32 v66, v60, v61
	v_lshlrev_b32_e32 v60, 16, v163
	v_and_b32_e32 v61, 0xffff0000, v163
	v_pk_add_f32 v[60:61], v[62:63], v[60:61]
	s_waitcnt vmcnt(6)
; __device__ __forceinline__ unsigned cvt_pk_bf16(float lo, float hi) { const f32x2 v = {lo, hi}; const bf16v2_ r = __builtin_convertvector(v, bf16v2_); return __builtin_bit_cast(unsigned, r); }
; __device__ __forceinline__ float bflo(unsigned w) { return __uint_as_float(w << 16); }
; __device__ __forceinline__ float bfhi(unsigned w) { return __uint_as_float(w & 0xffff0000u); }
;     __device__ __forceinline__ void operator()(const f32x4 (&acc)[2][2][4][2], const Unit& u, int wr, int wc, int, int) const {
;     ...
; #pragma unroll
;         for (int ai = 0; ai < 2; ++ai)
; #pragma unroll
;             for (int m = 0; m < 4; ++m)
; #pragma unroll
;                 for (int bj = 0; bj < 2; ++bj) { const u32x4 c = cin[ai][m][bj]; const f32x4 v0 = acc[ai][bj][m][0], v1 = acc[ai][bj][m][1];
;                     u32x4 w; w.x = cvt_pk_bf16(bflo(c.x) + v0[0], bfhi(c.x) + v0[1]); w.y = cvt_pk_bf16(bflo(c.y) + v0[2], bfhi(c.y) + v0[3]);
;                     w.z = cvt_pk_bf16(bflo(c.z) + v1[0], bfhi(c.z) + v1[1]); w.w = cvt_pk_bf16(bflo(c.w) + v1[2], bfhi(c.w) + v1[3]);
;                     *(u32x4*)(C + (size_t)(row0 + ai * HALF + m * 16) * ldc + col0 + bj * HALF) = w; }
	v_lshlrev_b32_e32 v62, 16, v156
	v_and_b32_e32 v63, 0xffff0000, v156
	v_pk_add_f32 v[56:57], v[56:57], v[62:63]
	v_lshlrev_b32_e32 v62, 16, v157
	v_and_b32_e32 v63, 0xffff0000, v157
	v_pk_add_f32 v[58:59], v[58:59], v[62:63]
	v_cvt_pk_bf16_f32 v56, v56, v57
	v_cvt_pk_bf16_f32 v57, v58, v59
	v_lshlrev_b32_e32 v58, 16, v158
	v_and_b32_e32 v59, 0xffff0000, v158
	v_pk_add_f32 v[48:49], v[48:49], v[58:59]
	v_cvt_pk_bf16_f32 v67, v60, v61
	v_cvt_pk_bf16_f32 v58, v48, v49
	v_lshlrev_b32_e32 v48, 16, v159
	v_and_b32_e32 v49, 0xffff0000, v159
	v_pk_add_f32 v[48:49], v[50:51], v[48:49]
	s_waitcnt vmcnt(5)
	v_lshlrev_b32_e32 v50, 16, v153
	v_cvt_pk_bf16_f32 v59, v48, v49
	v_lshlrev_b32_e32 v48, 16, v152
	v_and_b32_e32 v49, 0xffff0000, v152
	v_and_b32_e32 v51, 0xffff0000, v153
	v_pk_add_f32 v[48:49], v[52:53], v[48:49]
	v_pk_add_f32 v[50:51], v[54:55], v[50:51]
	v_cvt_pk_bf16_f32 v48, v48, v49
	v_cvt_pk_bf16_f32 v49, v50, v51
	v_lshlrev_b32_e32 v50, 16, v154
	v_and_b32_e32 v51, 0xffff0000, v154
	v_pk_add_f32 v[44:45], v[44:45], v[50:51]
	v_lshl_add_u64 v[60:61], s[88:89], 0, v[210:211]
	v_cvt_pk_bf16_f32 v50, v44, v45
	v_lshlrev_b32_e32 v44, 16, v155
	v_and_b32_e32 v45, 0xffff0000, v155
	v_pk_add_f32 v[44:45], v[46:47], v[44:45]
	s_waitcnt vmcnt(4)
	v_lshlrev_b32_e32 v46, 16, v148
	v_and_b32_e32 v47, 0xffff0000, v148
	v_pk_add_f32 v[40:41], v[40:41], v[46:47]
	v_lshlrev_b32_e32 v46, 16, v149
	v_and_b32_e32 v47, 0xffff0000, v149
	v_pk_add_f32 v[42:43], v[42:43], v[46:47]
	v_cvt_pk_bf16_f32 v40, v40, v41
	v_cvt_pk_bf16_f32 v41, v42, v43
	v_lshlrev_b32_e32 v42, 16, v150
	v_and_b32_e32 v43, 0xffff0000, v150
	v_pk_add_f32 v[32:33], v[32:33], v[42:43]
	v_cvt_pk_bf16_f32 v51, v44, v45
	v_cvt_pk_bf16_f32 v42, v32, v33
	v_lshlrev_b32_e32 v32, 16, v151
	v_and_b32_e32 v33, 0xffff0000, v151
	v_pk_add_f32 v[32:33], v[34:35], v[32:33]
	s_waitcnt vmcnt(3)
	v_lshlrev_b32_e32 v34, 16, v145
	v_cvt_pk_bf16_f32 v43, v32, v33
	v_lshlrev_b32_e32 v32, 16, v144
	v_and_b32_e32 v33, 0xffff0000, v144
	v_and_b32_e32 v35, 0xffff0000, v145
	v_pk_add_f32 v[32:33], v[36:37], v[32:33]
	v_pk_add_f32 v[34:35], v[38:39], v[34:35]
	v_cvt_pk_bf16_f32 v32, v32, v33
	v_cvt_pk_bf16_f32 v33, v34, v35
	v_lshlrev_b32_e32 v34, 16, v146
	v_and_b32_e32 v35, 0xffff0000, v146
	v_pk_add_f32 v[28:29], v[28:29], v[34:35]
	v_lshl_add_u64 v[44:45], s[88:89], 0, v[208:209]
	v_cvt_pk_bf16_f32 v34, v28, v29
	v_lshlrev_b32_e32 v28, 16, v147
	v_and_b32_e32 v29, 0xffff0000, v147
	v_pk_add_f32 v[28:29], v[30:31], v[28:29]
	s_waitcnt vmcnt(2)
	v_lshlrev_b32_e32 v30, 16, v140
	v_and_b32_e32 v31, 0xffff0000, v140
	v_pk_add_f32 v[24:25], v[24:25], v[30:31]
	v_lshlrev_b32_e32 v30, 16, v141
	v_and_b32_e32 v31, 0xffff0000, v141
	v_pk_add_f32 v[26:27], v[26:27], v[30:31]
	v_cvt_pk_bf16_f32 v24, v24, v25
	v_cvt_pk_bf16_f32 v25, v26, v27
	v_lshlrev_b32_e32 v26, 16, v142
	v_and_b32_e32 v27, 0xffff0000, v142
	v_pk_add_f32 v[16:17], v[16:17], v[26:27]
	v_cvt_pk_bf16_f32 v35, v28, v29
	v_cvt_pk_bf16_f32 v26, v16, v17
	v_lshlrev_b32_e32 v16, 16, v143
	v_and_b32_e32 v17, 0xffff0000, v143
	v_pk_add_f32 v[16:17], v[18:19], v[16:17]
	s_waitcnt vmcnt(1)
	v_lshlrev_b32_e32 v18, 16, v137
	v_cvt_pk_bf16_f32 v27, v16, v17
	v_lshlrev_b32_e32 v16, 16, v136
	v_and_b32_e32 v17, 0xffff0000, v136
	v_and_b32_e32 v19, 0xffff0000, v137
	v_pk_add_f32 v[16:17], v[20:21], v[16:17]
	v_pk_add_f32 v[18:19], v[22:23], v[18:19]
	v_cvt_pk_bf16_f32 v16, v16, v17
	v_cvt_pk_bf16_f32 v17, v18, v19
	v_lshlrev_b32_e32 v18, 16, v138
	v_and_b32_e32 v19, 0xffff0000, v138
	v_pk_add_f32 v[12:13], v[12:13], v[18:19]
	v_lshl_add_u64 v[28:29], s[88:89], 0, v[206:207]
	v_cvt_pk_bf16_f32 v18, v12, v13
	v_lshlrev_b32_e32 v12, 16, v139
	v_and_b32_e32 v13, 0xffff0000, v139
	v_pk_add_f32 v[12:13], v[14:15], v[12:13]
	s_waitcnt vmcnt(0)
	v_lshlrev_b32_e32 v14, 16, v132
	v_and_b32_e32 v15, 0xffff0000, v132
	v_pk_add_f32 v[8:9], v[8:9], v[14:15]
	v_lshlrev_b32_e32 v14, 16, v133
	v_and_b32_e32 v15, 0xffff0000, v133
	v_pk_add_f32 v[10:11], v[10:11], v[14:15]
	v_cvt_pk_bf16_f32 v8, v8, v9
	v_cvt_pk_bf16_f32 v9, v10, v11
	v_lshlrev_b32_e32 v10, 16, v134
	v_and_b32_e32 v11, 0xffff0000, v134
	v_pk_add_f32 v[4:5], v[4:5], v[10:11]
	v_cvt_pk_bf16_f32 v19, v12, v13
	v_cvt_pk_bf16_f32 v10, v4, v5
	v_lshlrev_b32_e32 v4, 16, v135
	v_and_b32_e32 v5, 0xffff0000, v135
	v_lshl_add_u64 v[12:13], s[88:89], 0, v[204:205]
	v_pk_add_f32 v[4:5], v[6:7], v[4:5]
	v_lshl_add_u64 v[92:93], v[92:93], 0, v[202:203]
	v_lshl_add_u64 v[76:77], v[76:77], 0, v[202:203]
	v_lshl_add_u64 v[60:61], v[60:61], 0, v[202:203]
	v_lshl_add_u64 v[44:45], v[44:45], 0, v[202:203]
	v_lshl_add_u64 v[28:29], v[28:29], 0, v[202:203]
	v_lshl_add_u64 v[12:13], v[12:13], 0, v[202:203]
	v_cvt_pk_bf16_f32 v11, v4, v5
	global_store_dwordx4 v[124:125], v[128:131], off
	global_store_dwordx4 v[124:125], v[120:123], off offset:256
	global_store_dwordx4 v[108:109], v[112:115], off
	global_store_dwordx4 v[108:109], v[104:107], off offset:256
	global_store_dwordx4 v[92:93], v[96:99], off
	global_store_dwordx4 v[92:93], v[88:91], off offset:256
	global_store_dwordx4 v[76:77], v[80:83], off
	global_store_dwordx4 v[76:77], v[72:75], off offset:256
	global_store_dwordx4 v[60:61], v[64:67], off
	global_store_dwordx4 v[60:61], v[56:59], off offset:256
	global_store_dwordx4 v[44:45], v[48:51], off
	global_store_dwordx4 v[44:45], v[40:43], off offset:256
	global_store_dwordx4 v[28:29], v[32:35], off
	global_store_dwordx4 v[28:29], v[24:27], off offset:256
	global_store_dwordx4 v[12:13], v[16:19], off
	global_store_dwordx4 v[12:13], v[8:11], off offset:256
	s_cmpk_lt_u32 s2, 0x100
	s_cbranch_scc1 .Lalign_b_1666
	s_barrier
